# v14 + strategy 7.4: all per-segment s_setprio flips deleted, one static s_setprio 1 for waves 4-7 at kernel entry
# baseline (speedup 1.0000x reference)
; #define LAS __attribute__((address_space(3)))
; __device__ __forceinline__ int opaque_tid(int wv) { int l; asm volatile("v_mbcnt_lo_u32_b32 %0, -1, 0\n\tv_mbcnt_hi_u32_b32 %0, -1, %0" : "=v"(l)); return (wv << 6) | l; }
; __global__ void __launch_bounds__(NTHR, 2) fwd_kernel(Args a_unused) {
;     ...
;     const int G = NWG, bid = blockIdx.x;
;     const int wv = __builtin_amdgcn_readfirstlane(threadIdx.x >> 6);
;     ArgsCP ap = (ArgsCP)__builtin_amdgcn_kernarg_segment_ptr();
;     ...
;     volatile LAS unsigned* xst = (volatile LAS unsigned*)(lds + LDS_BYTES - 16);
;     { const int t_ = opaque_tid(wv); if (t_ < 4) xst[t_] = 0u; }
;     if (load_args(ap).ws == nullptr) grid.sync();
;     (void)xcd_barrier_post((unsigned*)load_args(ap).ws, xst, opaque_tid(wv) == 0);
_Z10fwd_kernel4Args:
	s_mov_b64 s[46:47], s[0:1]
	v_writelane_b32 v255, 0, 62
	v_and_b32_e32 v1, 0x3ff, v0
	s_mov_b32 s60, s2
	s_add_u32 s2, s46, 0x90
	v_readfirstlane_b32 s0, v1
	s_addc_u32 s3, s47, 0
	v_mbcnt_lo_u32_b32 v2, -1, 0
	v_mbcnt_hi_u32_b32 v2, -1, v2
	s_nop 0
	v_writelane_b32 v252, s0, 0
	s_lshr_b32 s4, s0, 8
	s_cmp_lg_u32 s4, 0
	s_cbranch_scc0 .Lmy_prio_done
	s_setprio 1
.Lmy_prio_done:
	s_andn2_b32 s0, s0, 63
	v_or_b32_e32 v2, s0, v2
	v_writelane_b32 v252, s0, 1
	v_cmp_gt_i32_e32 vcc, 4, v2
	s_and_saveexec_b64 s[0:1], vcc
	v_lshl_add_u32 v2, v2, 2, 0
	v_add_u32_e32 v2, 0x23ff0, v2
	v_mov_b32_e32 v3, 0
	ds_write_b32 v2, v3
	s_or_b64 exec, exec, s[0:1]
	s_mov_b64 s[0:1], s[46:47]
	s_load_dwordx2 s[0:1], s[0:1], 0x88
	s_waitcnt lgkmcnt(0)
	s_cmp_lg_u64 s[0:1], 0
	s_cbranch_scc1 .LBB0_14
	v_lshrrev_b32_e32 v2, 20, v0
	v_lshrrev_b32_e32 v0, 10, v0
	v_or_b32_e32 v0, v0, v2
	s_movk_i32 s0, 0x3ff
	v_and_or_b32 v0, v0, s0, v1
	v_cmp_eq_u32_e32 vcc, 0, v0
	s_barrier
	s_and_saveexec_b64 s[0:1], vcc
	s_cbranch_execz .LBB0_13
	buffer_wbl2 sc1
	s_load_dwordx2 s[2:3], s[2:3], 0x58
	v_mov_b32_e32 v2, 0
	s_mov_b64 s[4:5], exec
	v_mbcnt_lo_u32_b32 v1, s4, 0
	v_mbcnt_hi_u32_b32 v1, s5, v1
	s_waitcnt lgkmcnt(0)
	global_load_dword v0, v2, s[2:3] offset:40
	v_cmp_eq_u32_e32 vcc, 0, v1
	s_and_saveexec_b64 s[6:7], vcc
	s_cbranch_execz .LBB0_6
	s_bcnt1_i32_b64 s4, s[4:5]
	v_mov_b32_e32 v3, s4
	global_atomic_add v3, v2, v3, s[2:3] offset:32 sc0

; #define PG8_STAGE(bufoff, gbase, voff) do { _Pragma("unroll") for (int _i = 0; _i < 2; ++_i) \
;         __builtin_amdgcn_global_load_lds((const unsigned*)((const char*)(gbase) + (voff)[_i]), (LAS unsigned*)(lds + (bufoff) + ldsw + _i * 8192), 16, 0, 0); } while (0)
; #define PG8_LDA(dst, b, h) do { _Pragma("unroll") for (int m = 0; m < 4; ++m) _Pragma("unroll") for (int k = 0; k < 2; ++k) dst[m][k] = *(const LAS bf16x8*)(lds + PG8_SA(b, h) + aoff + m * 2048 + k * 1024); } while (0)
; #define PG8_LDB(dst, b, h) do { _Pragma("unroll") for (int n = 0; n < 2; ++n) _Pragma("unroll") for (int k = 0; k < 2; ++k) dst[n][k] = *(const LAS bf16x8*)(lds + PG8_SB(b, h) + boff + n * 2048 + k * 1024); } while (0)
; #define PG8_WAIT_V(n) asm volatile("s_waitcnt vmcnt(" #n ")" ::: "memory")
; #define PG8_WAIT_L(n) asm volatile("s_waitcnt lgkmcnt(" #n ")" ::: "memory")
; #define PG8_BAR __builtin_amdgcn_s_barrier()
; template <class Epi, class Sched>
; __device__ __forceinline__ void gemm_phase(int wv, LAS unsigned char* lds, const Gemm g, const Sched& S, const Epi& E) {
;     ...
;             const char* a1 = cA + (size_t)(t + 1) * kstep;
;             const char* a2 = last ? nA : cA + (size_t)(t + 2) * kstep; const char* b2 = last ? nB : cB + (size_t)(t + 2) * kstep;
;             const char* a3 = a2 + kstep; const char* b3 = b2 + kstep;
;             PG8_LDB(B0, 0, 0); PG8_LDB(B1, 0, 1); PG8_SCHED; PG8_LDA(At, 0, 0); PG8_STAGE(PG8_SA(1, 1), a1 + hstep, voffA);
;             PG8_WAIT_V(8); PG8_WAIT_L(0); PG8_BAR; PG8_MMA(0, 0, At, B0); PG8_MMA(0, 1, At, B1); PG8_BAR; PG8_SCHED;
;             PG8_LDA(At, 0, 1); PG8_STAGE(PG8_SB(0, 0), b2, voffB); PG8_STAGE(PG8_SB(0, 1), b2 + hstepB, voffB); PG8_STAGE(PG8_SA(0, 0), a2, voffA);
;             PG8_WAIT_V(8); PG8_WAIT_L(0); PG8_BAR; PG8_MMA(1, 0, At, B0); PG8_MMA(1, 1, At, B1); PG8_BAR; PG8_SCHED;
;             PG8_LDB(B0, 1, 0); PG8_LDB(B1, 1, 1); PG8_SCHED; PG8_LDA(At, 1, 0); PG8_STAGE(PG8_SA(0, 1), a2 + hstep, voffA);
;             PG8_WAIT_V(8); PG8_WAIT_L(0); PG8_BAR; PG8_MMA(0, 0, At, B0); PG8_MMA(0, 1, At, B1); PG8_BAR; PG8_SCHED;
;             PG8_LDA(At, 1, 1); PG8_STAGE(PG8_SB(1, 0), b3, voffB); PG8_STAGE(PG8_SB(1, 1), b3 + hstepB, voffB); PG8_STAGE(PG8_SA(1, 0), a3, voffA);
;             PG8_WAIT_V(8); PG8_WAIT_L(0); PG8_BAR; PG8_MMA(1, 0, At, B0); PG8_MMA(1, 1, At, B1); PG8_BAR; PG8_SCHED;
.LBB0_178:
	s_add_u32 s20, s18, 0xfffc0080
	s_addc_u32 s21, s19, -1
	s_add_i32 s47, 0, 0x10000
	s_cmp_eq_u32 s46, 12
	s_cselect_b32 s23, s11, s21
	s_cselect_b32 s22, s41, s20
	s_cselect_b32 s21, s13, s45
	s_cselect_b32 s20, s42, s43
	s_add_i32 s50, 0, 0x14000
	v_add_u32_e32 v154, s47, v143
	v_add_u32_e32 v170, s50, v143
	ds_read_b128 v[138:141], v154
	ds_read_b128 v[146:149], v154 offset:1024
	ds_read_b128 v[150:153], v154 offset:2048
	ds_read_b128 v[154:157], v154 offset:3072
	ds_read_b128 v[158:161], v170
	ds_read_b128 v[162:165], v170 offset:1024
	ds_read_b128 v[166:169], v170 offset:2048
	ds_read_b128 v[170:173], v170 offset:3072
	v_lshl_add_u64 v[186:187], s[18:19], 0, v[134:135]
	s_add_i32 m0, s29, 0xc000
	ds_read_b128 v[174:177], v145
	ds_read_b128 v[178:181], v145 offset:1024
	ds_read_b128 v[182:185], v145 offset:2048
	ds_read_b128 v[198:201], v145 offset:3072
	ds_read_b128 v[202:205], v145 offset:4096
	ds_read_b128 v[206:209], v145 offset:5120
	ds_read_b128 v[210:213], v145 offset:6144
	ds_read_b128 v[214:217], v145 offset:7168
	global_load_lds_dwordx4 v[186:187], off
	v_lshl_add_u64 v[186:187], s[18:19], 0, v[136:137]
	s_add_i32 m0, s29, 0xe000
	s_nop 0
	global_load_lds_dwordx4 v[186:187], off
	s_waitcnt vmcnt(8)
	s_waitcnt lgkmcnt(0)
	s_barrier
	s_waitcnt lgkmcnt(0)
	v_mfma_f32_16x16x32_bf16 v[124:127], v[138:141], v[174:177], v[124:127]
	v_mfma_f32_16x16x32_bf16 v[120:123], v[150:153], v[174:177], v[120:123]
	v_mfma_f32_16x16x32_bf16 v[108:111], v[138:141], v[182:185], v[108:111]
	v_mfma_f32_16x16x32_bf16 v[100:103], v[150:153], v[182:185], v[100:103]
	v_mfma_f32_16x16x32_bf16 v[92:95], v[138:141], v[202:205], v[92:95]
	v_mfma_f32_16x16x32_bf16 v[84:87], v[150:153], v[202:205], v[84:87]
	v_mfma_f32_16x16x32_bf16 v[76:79], v[138:141], v[210:213], v[76:79]
	v_mfma_f32_16x16x32_bf16 v[68:71], v[150:153], v[210:213], v[68:71]
	v_mfma_f32_16x16x32_bf16 v[124:127], v[146:149], v[178:181], v[124:127]
	v_mfma_f32_16x16x32_bf16 v[120:123], v[154:157], v[178:181], v[120:123]
	v_mfma_f32_16x16x32_bf16 v[108:111], v[146:149], v[198:201], v[108:111]
	v_mfma_f32_16x16x32_bf16 v[100:103], v[154:157], v[198:201], v[100:103]
	v_mfma_f32_16x16x32_bf16 v[92:95], v[146:149], v[206:209], v[92:95]
	v_mfma_f32_16x16x32_bf16 v[84:87], v[154:157], v[206:209], v[84:87]
	v_mfma_f32_16x16x32_bf16 v[76:79], v[146:149], v[214:217], v[76:79]
	v_mfma_f32_16x16x32_bf16 v[68:71], v[154:157], v[214:217], v[68:71]
	v_mfma_f32_16x16x32_bf16 v[116:119], v[158:161], v[174:177], v[116:119]
	v_mfma_f32_16x16x32_bf16 v[112:115], v[166:169], v[174:177], v[112:115]
	v_mfma_f32_16x16x32_bf16 v[104:107], v[158:161], v[182:185], v[104:107]
	v_mfma_f32_16x16x32_bf16 v[96:99], v[166:169], v[182:185], v[96:99]
	v_mfma_f32_16x16x32_bf16 v[88:91], v[158:161], v[202:205], v[88:91]
	v_mfma_f32_16x16x32_bf16 v[80:83], v[166:169], v[202:205], v[80:83]
	v_mfma_f32_16x16x32_bf16 v[72:75], v[158:161], v[210:213], v[72:75]
	v_mfma_f32_16x16x32_bf16 v[64:67], v[166:169], v[210:213], v[64:67]
	v_mfma_f32_16x16x32_bf16 v[116:119], v[162:165], v[178:181], v[116:119]
	v_mfma_f32_16x16x32_bf16 v[112:115], v[170:173], v[178:181], v[112:115]
	v_mfma_f32_16x16x32_bf16 v[104:107], v[162:165], v[198:201], v[104:107]
	v_mfma_f32_16x16x32_bf16 v[96:99], v[170:173], v[198:201], v[96:99]
	v_mfma_f32_16x16x32_bf16 v[88:91], v[162:165], v[206:209], v[88:91]
	v_mfma_f32_16x16x32_bf16 v[80:83], v[170:173], v[206:209], v[80:83]
	v_mfma_f32_16x16x32_bf16 v[72:75], v[162:165], v[214:217], v[72:75]
	v_mfma_f32_16x16x32_bf16 v[64:67], v[170:173], v[214:217], v[64:67]
	s_barrier
	s_add_i32 s47, s47, s28
	v_lshl_add_u64 v[186:187], s[20:21], 0, v[188:189]
	s_mov_b32 m0, s47
	ds_read_b128 v[174:177], v145 offset:16384
	ds_read_b128 v[178:181], v145 offset:17408
	ds_read_b128 v[182:185], v145 offset:18432
	ds_read_b128 v[198:201], v145 offset:19456
	ds_read_b128 v[202:205], v145 offset:20480
	ds_read_b128 v[206:209], v145 offset:21504
	ds_read_b128 v[210:213], v145 offset:22528
	ds_read_b128 v[214:217], v145 offset:23552
	global_load_lds_dwordx4 v[186:187], off
	s_add_i32 m0, s47, 0x2000
	s_add_u32 s48, s20, 0x40000
	v_lshl_add_u64 v[218:219], s[20:21], 0, v[128:129]
	s_addc_u32 s49, s21, 0
	s_add_i32 s47, s50, s28
	global_load_lds_dwordx4 v[218:219], off
	v_lshl_add_u64 v[220:221], s[48:49], 0, v[188:189]
	s_mov_b32 m0, s47
	v_lshl_add_u64 v[222:223], s[22:23], 0, v[130:131]
	global_load_lds_dwordx4 v[220:221], off
	v_lshl_add_u64 v[220:221], s[48:49], 0, v[128:129]
	s_add_i32 m0, s47, 0x2000
	s_nop 0
	global_load_lds_dwordx4 v[220:221], off
	v_lshl_add_u64 v[220:221], s[22:23], 0, v[132:133]
	s_mov_b32 m0, s29
	s_nop 0
	global_load_lds_dwordx4 v[220:221], off
	s_mov_b32 m0, s30
	s_nop 0
	global_load_lds_dwordx4 v[222:223], off
	s_waitcnt vmcnt(8)
	s_waitcnt lgkmcnt(0)
	s_barrier
; #define PG8_STAGE(bufoff, gbase, voff) do { _Pragma("unroll") for (int _i = 0; _i < 2; ++_i) \
;         __builtin_amdgcn_global_load_lds((const unsigned*)((const char*)(gbase) + (voff)[_i]), (LAS unsigned*)(lds + (bufoff) + ldsw + _i * 8192), 16, 0, 0); } while (0)
; #define PG8_LDA(dst, b, h) do { _Pragma("unroll") for (int m = 0; m < 4; ++m) _Pragma("unroll") for (int k = 0; k < 2; ++k) dst[m][k] = *(const LAS bf16x8*)(lds + PG8_SA(b, h) + aoff + m * 2048 + k * 1024); } while (0)
; #define PG8_LDB(dst, b, h) do { _Pragma("unroll") for (int n = 0; n < 2; ++n) _Pragma("unroll") for (int k = 0; k < 2; ++k) dst[n][k] = *(const LAS bf16x8*)(lds + PG8_SB(b, h) + boff + n * 2048 + k * 1024); } while (0)
; #define PG8_WAIT_V(n) asm volatile("s_waitcnt vmcnt(" #n ")" ::: "memory")
; #define PG8_WAIT_L(n) asm volatile("s_waitcnt lgkmcnt(" #n ")" ::: "memory")
; #define PG8_BAR __builtin_amdgcn_s_barrier()
; template <class Epi, class Sched>
; __device__ __forceinline__ void gemm_phase(int wv, LAS unsigned char* lds, const Gemm g, const Sched& S, const Epi& E) {
;     ...
;             const char* a1 = cA + (size_t)(t + 1) * kstep;
;             const char* a2 = last ? nA : cA + (size_t)(t + 2) * kstep; const char* b2 = last ? nB : cB + (size_t)(t + 2) * kstep;
;             const char* a3 = a2 + kstep; const char* b3 = b2 + kstep;
;             PG8_LDB(B0, 0, 0); PG8_LDB(B1, 0, 1); PG8_SCHED; PG8_LDA(At, 0, 0); PG8_STAGE(PG8_SA(1, 1), a1 + hstep, voffA);
;             PG8_WAIT_V(8); PG8_WAIT_L(0); PG8_BAR; PG8_MMA(0, 0, At, B0); PG8_MMA(0, 1, At, B1); PG8_BAR; PG8_SCHED;
;             PG8_LDA(At, 0, 1); PG8_STAGE(PG8_SB(0, 0), b2, voffB); PG8_STAGE(PG8_SB(0, 1), b2 + hstepB, voffB); PG8_STAGE(PG8_SA(0, 0), a2, voffA);
;             PG8_WAIT_V(8); PG8_WAIT_L(0); PG8_BAR; PG8_MMA(1, 0, At, B0); PG8_MMA(1, 1, At, B1); PG8_BAR; PG8_SCHED;
;             PG8_LDB(B0, 1, 0); PG8_LDB(B1, 1, 1); PG8_SCHED; PG8_LDA(At, 1, 0); PG8_STAGE(PG8_SA(0, 1), a2 + hstep, voffA);
;             PG8_WAIT_V(8); PG8_WAIT_L(0); PG8_BAR; PG8_MMA(0, 0, At, B0); PG8_MMA(0, 1, At, B1); PG8_BAR; PG8_SCHED;
;             PG8_LDA(At, 1, 1); PG8_STAGE(PG8_SB(1, 0), b3, voffB); PG8_STAGE(PG8_SB(1, 1), b3 + hstepB, voffB); PG8_STAGE(PG8_SA(1, 0), a3, voffA);
;             PG8_WAIT_V(8); PG8_WAIT_L(0); PG8_BAR; PG8_MMA(1, 0, At, B0); PG8_MMA(1, 1, At, B1); PG8_BAR; PG8_SCHED;
	s_waitcnt lgkmcnt(0)
	v_mfma_f32_16x16x32_bf16 v[60:63], v[138:141], v[174:177], v[60:63]
	v_mfma_f32_16x16x32_bf16 v[52:55], v[150:153], v[174:177], v[52:55]
	v_mfma_f32_16x16x32_bf16 v[44:47], v[138:141], v[182:185], v[44:47]
	v_mfma_f32_16x16x32_bf16 v[36:39], v[150:153], v[182:185], v[36:39]
	v_mfma_f32_16x16x32_bf16 v[28:31], v[138:141], v[202:205], v[28:31]
	v_mfma_f32_16x16x32_bf16 v[20:23], v[150:153], v[202:205], v[20:23]
	v_mfma_f32_16x16x32_bf16 v[12:15], v[138:141], v[210:213], v[12:15]
	v_mfma_f32_16x16x32_bf16 v[4:7], v[150:153], v[210:213], v[4:7]
	v_mfma_f32_16x16x32_bf16 v[60:63], v[146:149], v[178:181], v[60:63]
	v_mfma_f32_16x16x32_bf16 v[52:55], v[154:157], v[178:181], v[52:55]
	v_mfma_f32_16x16x32_bf16 v[44:47], v[146:149], v[198:201], v[44:47]
	v_mfma_f32_16x16x32_bf16 v[36:39], v[154:157], v[198:201], v[36:39]
	v_mfma_f32_16x16x32_bf16 v[28:31], v[146:149], v[206:209], v[28:31]
	v_mfma_f32_16x16x32_bf16 v[20:23], v[154:157], v[206:209], v[20:23]
	v_mfma_f32_16x16x32_bf16 v[12:15], v[146:149], v[214:217], v[12:15]
	v_mfma_f32_16x16x32_bf16 v[4:7], v[154:157], v[214:217], v[4:7]
	v_mfma_f32_16x16x32_bf16 v[56:59], v[158:161], v[174:177], v[56:59]
	v_mfma_f32_16x16x32_bf16 v[48:51], v[166:169], v[174:177], v[48:51]
	v_mfma_f32_16x16x32_bf16 v[40:43], v[158:161], v[182:185], v[40:43]
	v_mfma_f32_16x16x32_bf16 v[32:35], v[166:169], v[182:185], v[32:35]
	v_mfma_f32_16x16x32_bf16 v[24:27], v[158:161], v[202:205], v[24:27]
	v_mfma_f32_16x16x32_bf16 v[16:19], v[166:169], v[202:205], v[16:19]
	v_mfma_f32_16x16x32_bf16 v[8:11], v[158:161], v[210:213], v[8:11]
	v_mfma_f32_16x16x32_bf16 v[0:3], v[166:169], v[210:213], v[0:3]
	v_mfma_f32_16x16x32_bf16 v[56:59], v[162:165], v[178:181], v[56:59]
	v_mfma_f32_16x16x32_bf16 v[48:51], v[170:173], v[178:181], v[48:51]
	v_mfma_f32_16x16x32_bf16 v[40:43], v[162:165], v[198:201], v[40:43]
	v_mfma_f32_16x16x32_bf16 v[32:35], v[170:173], v[198:201], v[32:35]
	v_mfma_f32_16x16x32_bf16 v[24:27], v[162:165], v[206:209], v[24:27]
	v_mfma_f32_16x16x32_bf16 v[16:19], v[170:173], v[206:209], v[16:19]
	v_mfma_f32_16x16x32_bf16 v[8:11], v[162:165], v[214:217], v[8:11]
	v_mfma_f32_16x16x32_bf16 v[0:3], v[170:173], v[214:217], v[0:3]
	s_barrier
	s_add_i32 s47, 0, 0x18000
	s_add_i32 s48, 0, 0x1c000
	v_add_u32_e32 v154, s47, v143
	v_add_u32_e32 v170, s48, v143
	ds_read_b128 v[138:141], v154
	ds_read_b128 v[146:149], v154 offset:1024
	ds_read_b128 v[150:153], v154 offset:2048
	ds_read_b128 v[154:157], v154 offset:3072
	ds_read_b128 v[158:161], v170
	ds_read_b128 v[162:165], v170 offset:1024
	ds_read_b128 v[166:169], v170 offset:2048
	ds_read_b128 v[170:173], v170 offset:3072
	s_add_u32 s22, s22, 0x40000
	s_addc_u32 s23, s23, 0
	s_mov_b32 m0, s31
	v_lshl_add_u64 v[228:229], s[22:23], 0, v[132:133]
	ds_read_b128 v[174:177], v145 offset:32768
	ds_read_b128 v[178:181], v145 offset:33792
	ds_read_b128 v[182:185], v145 offset:34816
	ds_read_b128 v[198:201], v145 offset:35840
	ds_read_b128 v[202:205], v145 offset:36864
	ds_read_b128 v[206:209], v145 offset:37888
	ds_read_b128 v[210:213], v145 offset:38912
	ds_read_b128 v[214:217], v145 offset:39936
	global_load_lds_dwordx4 v[228:229], off
	v_lshl_add_u64 v[228:229], s[22:23], 0, v[130:131]
	s_mov_b32 m0, s36
	s_nop 0
	global_load_lds_dwordx4 v[228:229], off
	s_waitcnt vmcnt(8)
	s_waitcnt lgkmcnt(0)
	s_barrier
	s_waitcnt lgkmcnt(0)
	v_mfma_f32_16x16x32_bf16 v[124:127], v[138:141], v[174:177], v[124:127]
	v_mfma_f32_16x16x32_bf16 v[120:123], v[150:153], v[174:177], v[120:123]
	v_mfma_f32_16x16x32_bf16 v[108:111], v[138:141], v[182:185], v[108:111]
	v_mfma_f32_16x16x32_bf16 v[100:103], v[150:153], v[182:185], v[100:103]
	v_mfma_f32_16x16x32_bf16 v[92:95], v[138:141], v[202:205], v[92:95]
	v_mfma_f32_16x16x32_bf16 v[84:87], v[150:153], v[202:205], v[84:87]
	v_mfma_f32_16x16x32_bf16 v[76:79], v[138:141], v[210:213], v[76:79]
	v_mfma_f32_16x16x32_bf16 v[68:71], v[150:153], v[210:213], v[68:71]
	v_mfma_f32_16x16x32_bf16 v[124:127], v[146:149], v[178:181], v[124:127]
	v_mfma_f32_16x16x32_bf16 v[120:123], v[154:157], v[178:181], v[120:123]
	v_mfma_f32_16x16x32_bf16 v[108:111], v[146:149], v[198:201], v[108:111]
	v_mfma_f32_16x16x32_bf16 v[100:103], v[154:157], v[198:201], v[100:103]
	v_mfma_f32_16x16x32_bf16 v[92:95], v[146:149], v[206:209], v[92:95]
	v_mfma_f32_16x16x32_bf16 v[84:87], v[154:157], v[206:209], v[84:87]
	v_mfma_f32_16x16x32_bf16 v[76:79], v[146:149], v[214:217], v[76:79]
	v_mfma_f32_16x16x32_bf16 v[68:71], v[154:157], v[214:217], v[68:71]
	v_mfma_f32_16x16x32_bf16 v[116:119], v[158:161], v[174:177], v[116:119]
	v_mfma_f32_16x16x32_bf16 v[112:115], v[166:169], v[174:177], v[112:115]
	v_mfma_f32_16x16x32_bf16 v[104:107], v[158:161], v[182:185], v[104:107]
	v_mfma_f32_16x16x32_bf16 v[96:99], v[166:169], v[182:185], v[96:99]
	v_mfma_f32_16x16x32_bf16 v[88:91], v[158:161], v[202:205], v[88:91]
	v_mfma_f32_16x16x32_bf16 v[80:83], v[166:169], v[202:205], v[80:83]
	v_mfma_f32_16x16x32_bf16 v[72:75], v[158:161], v[210:213], v[72:75]
	v_mfma_f32_16x16x32_bf16 v[64:67], v[166:169], v[210:213], v[64:67]
	v_mfma_f32_16x16x32_bf16 v[116:119], v[162:165], v[178:181], v[116:119]
	v_mfma_f32_16x16x32_bf16 v[112:115], v[170:173], v[178:181], v[112:115]
	v_mfma_f32_16x16x32_bf16 v[104:107], v[162:165], v[198:201], v[104:107]
	v_mfma_f32_16x16x32_bf16 v[96:99], v[170:173], v[198:201], v[96:99]
	v_mfma_f32_16x16x32_bf16 v[88:91], v[162:165], v[206:209], v[88:91]
	v_mfma_f32_16x16x32_bf16 v[80:83], v[170:173], v[206:209], v[80:83]
	v_mfma_f32_16x16x32_bf16 v[72:75], v[162:165], v[214:217], v[72:75]
	v_mfma_f32_16x16x32_bf16 v[64:67], v[170:173], v[214:217], v[64:67]
	s_barrier
; #define PG8_STAGE(bufoff, gbase, voff) do { _Pragma("unroll") for (int _i = 0; _i < 2; ++_i) \
;         __builtin_amdgcn_global_load_lds((const unsigned*)((const char*)(gbase) + (voff)[_i]), (LAS unsigned*)(lds + (bufoff) + ldsw + _i * 8192), 16, 0, 0); } while (0)
; #define PG8_LDA(dst, b, h) do { _Pragma("unroll") for (int m = 0; m < 4; ++m) _Pragma("unroll") for (int k = 0; k < 2; ++k) dst[m][k] = *(const LAS bf16x8*)(lds + PG8_SA(b, h) + aoff + m * 2048 + k * 1024); } while (0)
; #define PG8_LDB(dst, b, h) do { _Pragma("unroll") for (int n = 0; n < 2; ++n) _Pragma("unroll") for (int k = 0; k < 2; ++k) dst[n][k] = *(const LAS bf16x8*)(lds + PG8_SB(b, h) + boff + n * 2048 + k * 1024); } while (0)
; #define PG8_MMA(ai, bj, At, Bt) do { __builtin_amdgcn_s_setprio(1); _Pragma("unroll") for (int m = 0; m < 4; ++m) _Pragma("unroll") for (int n = 0; n < 2; ++n) _Pragma("unroll") for (int k = 0; k < 2; ++k) \
;         acc[ai][bj][m][n] = __builtin_amdgcn_mfma_f32_16x16x32_bf16(Bt[n][k], At[m][k], acc[ai][bj][m][n], 0, 0, 0); __builtin_amdgcn_s_setprio(0); } while (0)
; #define PG8_WAIT_V(n) asm volatile("s_waitcnt vmcnt(" #n ")" ::: "memory")
; #define PG8_WAIT_L(n) asm volatile("s_waitcnt lgkmcnt(" #n ")" ::: "memory")
; #define PG8_BAR __builtin_amdgcn_s_barrier()
; #define PG8_SCHED __builtin_amdgcn_sched_barrier(0)
; template <class Epi, class Sched>
; __device__ __forceinline__ void gemm_phase(int wv, LAS unsigned char* lds, const Gemm g, const Sched& S, const Epi& E) {
;     ...
;             PG8_LDB(B0, 1, 0); PG8_LDB(B1, 1, 1); PG8_SCHED; PG8_LDA(At, 1, 0); PG8_STAGE(PG8_SA(0, 1), a2 + hstep, voffA);
;             PG8_WAIT_V(8); PG8_WAIT_L(0); PG8_BAR; PG8_MMA(0, 0, At, B0); PG8_MMA(0, 1, At, B1); PG8_BAR; PG8_SCHED;
;             PG8_LDA(At, 1, 1); PG8_STAGE(PG8_SB(1, 0), b3, voffB); PG8_STAGE(PG8_SB(1, 1), b3 + hstepB, voffB); PG8_STAGE(PG8_SA(1, 0), a3, voffA);
;             PG8_WAIT_V(8); PG8_WAIT_L(0); PG8_BAR; PG8_MMA(1, 0, At, B0); PG8_MMA(1, 1, At, B1); PG8_BAR; PG8_SCHED;
;         }
	s_add_i32 s22, s47, s28
	v_lshl_add_u64 v[186:187], v[186:187], 0, s[74:75]
	s_mov_b32 m0, s22
	ds_read_b128 v[174:177], v145 offset:49152
	ds_read_b128 v[178:181], v145 offset:50176
	ds_read_b128 v[182:185], v145 offset:51200
	ds_read_b128 v[198:201], v145 offset:52224
	ds_read_b128 v[202:205], v145 offset:53248
	ds_read_b128 v[206:209], v145 offset:54272
	ds_read_b128 v[210:213], v145 offset:55296
	ds_read_b128 v[214:217], v145 offset:56320
	global_load_lds_dwordx4 v[186:187], off
	s_add_i32 m0, s22, 0x2000
	s_add_u32 s20, s20, 0x40080
	v_lshl_add_u64 v[186:187], v[218:219], 0, s[74:75]
	s_addc_u32 s21, s21, 0
	s_add_i32 s22, s48, s28
	global_load_lds_dwordx4 v[186:187], off
	v_lshl_add_u64 v[186:187], s[20:21], 0, v[188:189]
	s_mov_b32 m0, s22
	s_nop 0
	global_load_lds_dwordx4 v[186:187], off
	v_lshl_add_u64 v[186:187], s[20:21], 0, v[128:129]
	s_add_i32 m0, s22, 0x2000
	s_nop 0
	global_load_lds_dwordx4 v[186:187], off
	v_lshl_add_u64 v[186:187], v[220:221], 0, s[74:75]
	s_mov_b32 m0, s37
	s_nop 0
	global_load_lds_dwordx4 v[186:187], off
	v_lshl_add_u64 v[186:187], v[222:223], 0, s[74:75]
	s_mov_b32 m0, s38
	s_nop 0
	global_load_lds_dwordx4 v[186:187], off
	s_waitcnt vmcnt(8)
	s_waitcnt lgkmcnt(0)
	s_barrier
	s_waitcnt lgkmcnt(0)
	v_mfma_f32_16x16x32_bf16 v[60:63], v[138:141], v[174:177], v[60:63]
	v_mfma_f32_16x16x32_bf16 v[52:55], v[150:153], v[174:177], v[52:55]
	v_mfma_f32_16x16x32_bf16 v[44:47], v[138:141], v[182:185], v[44:47]
	v_mfma_f32_16x16x32_bf16 v[36:39], v[150:153], v[182:185], v[36:39]
	v_mfma_f32_16x16x32_bf16 v[28:31], v[138:141], v[202:205], v[28:31]
	v_mfma_f32_16x16x32_bf16 v[20:23], v[150:153], v[202:205], v[20:23]
	v_mfma_f32_16x16x32_bf16 v[12:15], v[138:141], v[210:213], v[12:15]
	v_mfma_f32_16x16x32_bf16 v[4:7], v[150:153], v[210:213], v[4:7]
	v_mfma_f32_16x16x32_bf16 v[60:63], v[146:149], v[178:181], v[60:63]
	v_mfma_f32_16x16x32_bf16 v[52:55], v[154:157], v[178:181], v[52:55]
	v_mfma_f32_16x16x32_bf16 v[44:47], v[146:149], v[198:201], v[44:47]
	v_mfma_f32_16x16x32_bf16 v[36:39], v[154:157], v[198:201], v[36:39]
	v_mfma_f32_16x16x32_bf16 v[28:31], v[146:149], v[206:209], v[28:31]
	v_mfma_f32_16x16x32_bf16 v[20:23], v[154:157], v[206:209], v[20:23]
	v_mfma_f32_16x16x32_bf16 v[12:15], v[146:149], v[214:217], v[12:15]
	v_mfma_f32_16x16x32_bf16 v[4:7], v[154:157], v[214:217], v[4:7]
	v_mfma_f32_16x16x32_bf16 v[56:59], v[158:161], v[174:177], v[56:59]
	v_mfma_f32_16x16x32_bf16 v[48:51], v[166:169], v[174:177], v[48:51]
	v_mfma_f32_16x16x32_bf16 v[40:43], v[158:161], v[182:185], v[40:43]
	v_mfma_f32_16x16x32_bf16 v[32:35], v[166:169], v[182:185], v[32:35]
	v_mfma_f32_16x16x32_bf16 v[24:27], v[158:161], v[202:205], v[24:27]
	v_mfma_f32_16x16x32_bf16 v[16:19], v[166:169], v[202:205], v[16:19]
	v_mfma_f32_16x16x32_bf16 v[8:11], v[158:161], v[210:213], v[8:11]
	v_mfma_f32_16x16x32_bf16 v[0:3], v[166:169], v[210:213], v[0:3]
	v_mfma_f32_16x16x32_bf16 v[56:59], v[162:165], v[178:181], v[56:59]
	v_mfma_f32_16x16x32_bf16 v[48:51], v[170:173], v[178:181], v[48:51]
	v_mfma_f32_16x16x32_bf16 v[40:43], v[162:165], v[198:201], v[40:43]
	v_mfma_f32_16x16x32_bf16 v[32:35], v[170:173], v[198:201], v[32:35]
	v_mfma_f32_16x16x32_bf16 v[24:27], v[162:165], v[206:209], v[24:27]
	v_mfma_f32_16x16x32_bf16 v[16:19], v[170:173], v[206:209], v[16:19]
	v_mfma_f32_16x16x32_bf16 v[8:11], v[162:165], v[214:217], v[8:11]
	v_mfma_f32_16x16x32_bf16 v[0:3], v[170:173], v[214:217], v[0:3]
	s_barrier
	s_add_i32 s46, s46, 2
	s_add_u32 s18, s18, 0x100
	s_addc_u32 s19, s19, 0
	s_add_u32 s43, s43, 0x100
	s_addc_u32 s45, s45, 0
	s_cmp_gt_u32 s46, 13
	s_cbranch_scc0 .LBB0_178
	s_and_b64 vcc, exec, s[8:9]
	s_cbranch_vccz .LBB0_181
	s_barrier

; #define PG8_STAGE(bufoff, gbase, voff) do { _Pragma("unroll") for (int _i = 0; _i < 2; ++_i) \
;         __builtin_amdgcn_global_load_lds((const unsigned*)((const char*)(gbase) + (voff)[_i]), (LAS unsigned*)(lds + (bufoff) + ldsw + _i * 8192), 16, 0, 0); } while (0)
; #define PG8_LDA(dst, b, h) do { _Pragma("unroll") for (int m = 0; m < 4; ++m) _Pragma("unroll") for (int k = 0; k < 2; ++k) dst[m][k] = *(const LAS bf16x8*)(lds + PG8_SA(b, h) + aoff + m * 2048 + k * 1024); } while (0)
; #define PG8_LDB(dst, b, h) do { _Pragma("unroll") for (int n = 0; n < 2; ++n) _Pragma("unroll") for (int k = 0; k < 2; ++k) dst[n][k] = *(const LAS bf16x8*)(lds + PG8_SB(b, h) + boff + n * 2048 + k * 1024); } while (0)
; #define PG8_WAIT_V(n) asm volatile("s_waitcnt vmcnt(" #n ")" ::: "memory")
; #define PG8_WAIT_L(n) asm volatile("s_waitcnt lgkmcnt(" #n ")" ::: "memory")
; #define PG8_BAR __builtin_amdgcn_s_barrier()
; template <class Epi, class Sched>
; __device__ __forceinline__ void gemm_phase(int wv, LAS unsigned char* lds, const Gemm g, const Sched& S, const Epi& E) {
;     ...
;             const char* a1 = cA + (size_t)(t + 1) * kstep;
;             const char* a2 = last ? nA : cA + (size_t)(t + 2) * kstep; const char* b2 = last ? nB : cB + (size_t)(t + 2) * kstep;
;             const char* a3 = a2 + kstep; const char* b3 = b2 + kstep;
;             PG8_LDB(B0, 0, 0); PG8_LDB(B1, 0, 1); PG8_SCHED; PG8_LDA(At, 0, 0); PG8_STAGE(PG8_SA(1, 1), a1 + hstep, voffA);
;             PG8_WAIT_V(8); PG8_WAIT_L(0); PG8_BAR; PG8_MMA(0, 0, At, B0); PG8_MMA(0, 1, At, B1); PG8_BAR; PG8_SCHED;
;             PG8_LDA(At, 0, 1); PG8_STAGE(PG8_SB(0, 0), b2, voffB); PG8_STAGE(PG8_SB(0, 1), b2 + hstepB, voffB); PG8_STAGE(PG8_SA(0, 0), a2, voffA);
;             PG8_WAIT_V(8); PG8_WAIT_L(0); PG8_BAR; PG8_MMA(1, 0, At, B0); PG8_MMA(1, 1, At, B1); PG8_BAR; PG8_SCHED;
;             PG8_LDB(B0, 1, 0); PG8_LDB(B1, 1, 1); PG8_SCHED; PG8_LDA(At, 1, 0); PG8_STAGE(PG8_SA(0, 1), a2 + hstep, voffA);
;             PG8_WAIT_V(8); PG8_WAIT_L(0); PG8_BAR; PG8_MMA(0, 0, At, B0); PG8_MMA(0, 1, At, B1); PG8_BAR; PG8_SCHED;
;             PG8_LDA(At, 1, 1); PG8_STAGE(PG8_SB(1, 0), b3, voffB); PG8_STAGE(PG8_SB(1, 1), b3 + hstepB, voffB); PG8_STAGE(PG8_SA(1, 0), a3, voffA);
;             PG8_WAIT_V(8); PG8_WAIT_L(0); PG8_BAR; PG8_MMA(1, 0, At, B0); PG8_MMA(1, 1, At, B1); PG8_BAR; PG8_SCHED;
.LBB0_255:
	s_add_u32 s20, s18, 0x100
	s_addc_u32 s21, s19, 0
	s_add_i32 s49, 0, 0x10000
	s_cmp_eq_u32 s48, 40
	s_cselect_b32 s25, s5, s21
	s_cselect_b32 s24, s4, s20
	s_cselect_b32 s23, s17, s47
	s_cselect_b32 s22, s16, s46
	s_add_i32 s50, 0, 0x14000
	v_add_u32_e32 v124, s49, v240
	v_add_u32_e32 v156, s50, v240
	ds_read_b128 v[112:115], v124
	ds_read_b128 v[116:119], v124 offset:1024
	ds_read_b128 v[120:123], v124 offset:2048
	ds_read_b128 v[124:127], v124 offset:3072
	ds_read_b128 v[128:131], v156
	ds_read_b128 v[140:143], v156 offset:1024
	ds_read_b128 v[152:155], v156 offset:2048
	ds_read_b128 v[156:159], v156 offset:3072
	v_lshl_add_u64 v[212:213], s[18:19], 0, v[204:205]
	s_add_i32 m0, s31, 0xc000
	ds_read_b128 v[160:163], v244
	ds_read_b128 v[164:167], v244 offset:1024
	ds_read_b128 v[168:171], v244 offset:2048
	ds_read_b128 v[172:175], v244 offset:3072
	ds_read_b128 v[176:179], v244 offset:4096
	ds_read_b128 v[180:183], v244 offset:5120
	ds_read_b128 v[184:187], v244 offset:6144
	ds_read_b128 v[208:211], v244 offset:7168
	global_load_lds_dwordx4 v[212:213], off
	v_lshl_add_u64 v[212:213], s[18:19], 0, v[206:207]
	s_add_i32 m0, s31, 0xe000
	s_nop 0
	global_load_lds_dwordx4 v[212:213], off
	s_waitcnt vmcnt(8)
	s_waitcnt lgkmcnt(0)
	s_barrier
	s_waitcnt lgkmcnt(0)
	v_mfma_f32_16x16x32_bf16 v[148:151], v[112:115], v[160:163], v[148:151]
	v_mfma_f32_16x16x32_bf16 v[144:147], v[120:123], v[160:163], v[144:147]
	v_mfma_f32_16x16x32_bf16 v[108:111], v[112:115], v[168:171], v[108:111]
	v_mfma_f32_16x16x32_bf16 v[104:107], v[120:123], v[168:171], v[104:107]
	v_mfma_f32_16x16x32_bf16 v[92:95], v[112:115], v[176:179], v[92:95]
	v_mfma_f32_16x16x32_bf16 v[88:91], v[120:123], v[176:179], v[88:91]
	v_mfma_f32_16x16x32_bf16 v[76:79], v[112:115], v[184:187], v[76:79]
	v_mfma_f32_16x16x32_bf16 v[72:75], v[120:123], v[184:187], v[72:75]
	v_mfma_f32_16x16x32_bf16 v[148:151], v[116:119], v[164:167], v[148:151]
	v_mfma_f32_16x16x32_bf16 v[144:147], v[124:127], v[164:167], v[144:147]
	v_mfma_f32_16x16x32_bf16 v[108:111], v[116:119], v[172:175], v[108:111]
	v_mfma_f32_16x16x32_bf16 v[104:107], v[124:127], v[172:175], v[104:107]
	v_mfma_f32_16x16x32_bf16 v[92:95], v[116:119], v[180:183], v[92:95]
	v_mfma_f32_16x16x32_bf16 v[88:91], v[124:127], v[180:183], v[88:91]
	v_mfma_f32_16x16x32_bf16 v[76:79], v[116:119], v[208:211], v[76:79]
	v_mfma_f32_16x16x32_bf16 v[72:75], v[124:127], v[208:211], v[72:75]
	v_mfma_f32_16x16x32_bf16 v[136:139], v[128:131], v[160:163], v[136:139]
	v_mfma_f32_16x16x32_bf16 v[132:135], v[152:155], v[160:163], v[132:135]
	v_mfma_f32_16x16x32_bf16 v[100:103], v[128:131], v[168:171], v[100:103]
	v_mfma_f32_16x16x32_bf16 v[96:99], v[152:155], v[168:171], v[96:99]
	v_mfma_f32_16x16x32_bf16 v[84:87], v[128:131], v[176:179], v[84:87]
	v_mfma_f32_16x16x32_bf16 v[80:83], v[152:155], v[176:179], v[80:83]
	v_mfma_f32_16x16x32_bf16 v[68:71], v[128:131], v[184:187], v[68:71]
	v_mfma_f32_16x16x32_bf16 v[64:67], v[152:155], v[184:187], v[64:67]
	v_mfma_f32_16x16x32_bf16 v[136:139], v[140:143], v[164:167], v[136:139]
	v_mfma_f32_16x16x32_bf16 v[132:135], v[156:159], v[164:167], v[132:135]
	v_mfma_f32_16x16x32_bf16 v[100:103], v[140:143], v[172:175], v[100:103]
	v_mfma_f32_16x16x32_bf16 v[96:99], v[156:159], v[172:175], v[96:99]
	v_mfma_f32_16x16x32_bf16 v[84:87], v[140:143], v[180:183], v[84:87]
	v_mfma_f32_16x16x32_bf16 v[80:83], v[156:159], v[180:183], v[80:83]
	v_mfma_f32_16x16x32_bf16 v[68:71], v[140:143], v[208:211], v[68:71]
	v_mfma_f32_16x16x32_bf16 v[64:67], v[156:159], v[208:211], v[64:67]
	s_barrier
	s_add_i32 s18, s49, s30
	v_lshl_add_u64 v[212:213], s[22:23], 0, v[188:189]
	s_mov_b32 m0, s18
	ds_read_b128 v[160:163], v244 offset:16384
	ds_read_b128 v[164:167], v244 offset:17408
	ds_read_b128 v[168:171], v244 offset:18432
	ds_read_b128 v[172:175], v244 offset:19456
	ds_read_b128 v[176:179], v244 offset:20480
	ds_read_b128 v[180:183], v244 offset:21504
	ds_read_b128 v[184:187], v244 offset:22528
	ds_read_b128 v[208:211], v244 offset:23552
	global_load_lds_dwordx4 v[212:213], off
	s_add_i32 m0, s18, 0x2000
	s_add_u32 s18, s22, 0xb000
	v_lshl_add_u64 v[214:215], s[22:23], 0, v[198:199]
	s_addc_u32 s19, s23, 0
	s_add_i32 s49, s50, s30
	global_load_lds_dwordx4 v[214:215], off
	v_lshl_add_u64 v[216:217], s[18:19], 0, v[188:189]
	s_mov_b32 m0, s49
	v_lshl_add_u64 v[218:219], s[24:25], 0, v[200:201]
	global_load_lds_dwordx4 v[216:217], off
	v_lshl_add_u64 v[216:217], s[18:19], 0, v[198:199]
	s_add_i32 m0, s49, 0x2000
	s_nop 0
	global_load_lds_dwordx4 v[216:217], off
	v_lshl_add_u64 v[216:217], s[24:25], 0, v[202:203]
	s_mov_b32 m0, s31
	s_nop 0
	global_load_lds_dwordx4 v[216:217], off
	s_mov_b32 m0, s36
	s_nop 0
	global_load_lds_dwordx4 v[218:219], off
	s_waitcnt vmcnt(8)
	s_waitcnt lgkmcnt(0)
	s_barrier
; #define PG8_STAGE(bufoff, gbase, voff) do { _Pragma("unroll") for (int _i = 0; _i < 2; ++_i) \
;         __builtin_amdgcn_global_load_lds((const unsigned*)((const char*)(gbase) + (voff)[_i]), (LAS unsigned*)(lds + (bufoff) + ldsw + _i * 8192), 16, 0, 0); } while (0)
; #define PG8_LDA(dst, b, h) do { _Pragma("unroll") for (int m = 0; m < 4; ++m) _Pragma("unroll") for (int k = 0; k < 2; ++k) dst[m][k] = *(const LAS bf16x8*)(lds + PG8_SA(b, h) + aoff + m * 2048 + k * 1024); } while (0)
; #define PG8_LDB(dst, b, h) do { _Pragma("unroll") for (int n = 0; n < 2; ++n) _Pragma("unroll") for (int k = 0; k < 2; ++k) dst[n][k] = *(const LAS bf16x8*)(lds + PG8_SB(b, h) + boff + n * 2048 + k * 1024); } while (0)
; #define PG8_WAIT_V(n) asm volatile("s_waitcnt vmcnt(" #n ")" ::: "memory")
; #define PG8_WAIT_L(n) asm volatile("s_waitcnt lgkmcnt(" #n ")" ::: "memory")
; #define PG8_BAR __builtin_amdgcn_s_barrier()
; template <class Epi, class Sched>
; __device__ __forceinline__ void gemm_phase(int wv, LAS unsigned char* lds, const Gemm g, const Sched& S, const Epi& E) {
;     ...
;             const char* a1 = cA + (size_t)(t + 1) * kstep;
;             const char* a2 = last ? nA : cA + (size_t)(t + 2) * kstep; const char* b2 = last ? nB : cB + (size_t)(t + 2) * kstep;
;             const char* a3 = a2 + kstep; const char* b3 = b2 + kstep;
;             PG8_LDB(B0, 0, 0); PG8_LDB(B1, 0, 1); PG8_SCHED; PG8_LDA(At, 0, 0); PG8_STAGE(PG8_SA(1, 1), a1 + hstep, voffA);
;             PG8_WAIT_V(8); PG8_WAIT_L(0); PG8_BAR; PG8_MMA(0, 0, At, B0); PG8_MMA(0, 1, At, B1); PG8_BAR; PG8_SCHED;
;             PG8_LDA(At, 0, 1); PG8_STAGE(PG8_SB(0, 0), b2, voffB); PG8_STAGE(PG8_SB(0, 1), b2 + hstepB, voffB); PG8_STAGE(PG8_SA(0, 0), a2, voffA);
;             PG8_WAIT_V(8); PG8_WAIT_L(0); PG8_BAR; PG8_MMA(1, 0, At, B0); PG8_MMA(1, 1, At, B1); PG8_BAR; PG8_SCHED;
;             PG8_LDB(B0, 1, 0); PG8_LDB(B1, 1, 1); PG8_SCHED; PG8_LDA(At, 1, 0); PG8_STAGE(PG8_SA(0, 1), a2 + hstep, voffA);
;             PG8_WAIT_V(8); PG8_WAIT_L(0); PG8_BAR; PG8_MMA(0, 0, At, B0); PG8_MMA(0, 1, At, B1); PG8_BAR; PG8_SCHED;
;             PG8_LDA(At, 1, 1); PG8_STAGE(PG8_SB(1, 0), b3, voffB); PG8_STAGE(PG8_SB(1, 1), b3 + hstepB, voffB); PG8_STAGE(PG8_SA(1, 0), a3, voffA);
;             PG8_WAIT_V(8); PG8_WAIT_L(0); PG8_BAR; PG8_MMA(1, 0, At, B0); PG8_MMA(1, 1, At, B1); PG8_BAR; PG8_SCHED;
	s_waitcnt lgkmcnt(0)
	v_mfma_f32_16x16x32_bf16 v[60:63], v[112:115], v[160:163], v[60:63]
	v_mfma_f32_16x16x32_bf16 v[56:59], v[120:123], v[160:163], v[56:59]
	v_mfma_f32_16x16x32_bf16 v[44:47], v[112:115], v[168:171], v[44:47]
	v_mfma_f32_16x16x32_bf16 v[40:43], v[120:123], v[168:171], v[40:43]
	v_mfma_f32_16x16x32_bf16 v[28:31], v[112:115], v[176:179], v[28:31]
	v_mfma_f32_16x16x32_bf16 v[24:27], v[120:123], v[176:179], v[24:27]
	v_mfma_f32_16x16x32_bf16 v[12:15], v[112:115], v[184:187], v[12:15]
	v_mfma_f32_16x16x32_bf16 v[8:11], v[120:123], v[184:187], v[8:11]
	v_mfma_f32_16x16x32_bf16 v[60:63], v[116:119], v[164:167], v[60:63]
	v_mfma_f32_16x16x32_bf16 v[56:59], v[124:127], v[164:167], v[56:59]
	v_mfma_f32_16x16x32_bf16 v[44:47], v[116:119], v[172:175], v[44:47]
	v_mfma_f32_16x16x32_bf16 v[40:43], v[124:127], v[172:175], v[40:43]
	v_mfma_f32_16x16x32_bf16 v[28:31], v[116:119], v[180:183], v[28:31]
	v_mfma_f32_16x16x32_bf16 v[24:27], v[124:127], v[180:183], v[24:27]
	v_mfma_f32_16x16x32_bf16 v[12:15], v[116:119], v[208:211], v[12:15]
	v_mfma_f32_16x16x32_bf16 v[8:11], v[124:127], v[208:211], v[8:11]
	v_mfma_f32_16x16x32_bf16 v[52:55], v[128:131], v[160:163], v[52:55]
	v_mfma_f32_16x16x32_bf16 v[48:51], v[152:155], v[160:163], v[48:51]
	v_mfma_f32_16x16x32_bf16 v[36:39], v[128:131], v[168:171], v[36:39]
	v_mfma_f32_16x16x32_bf16 v[32:35], v[152:155], v[168:171], v[32:35]
	v_mfma_f32_16x16x32_bf16 v[20:23], v[128:131], v[176:179], v[20:23]
	v_mfma_f32_16x16x32_bf16 v[16:19], v[152:155], v[176:179], v[16:19]
	v_mfma_f32_16x16x32_bf16 v[4:7], v[128:131], v[184:187], v[4:7]
	v_mfma_f32_16x16x32_bf16 v[0:3], v[152:155], v[184:187], v[0:3]
	v_mfma_f32_16x16x32_bf16 v[52:55], v[140:143], v[164:167], v[52:55]
	v_mfma_f32_16x16x32_bf16 v[48:51], v[156:159], v[164:167], v[48:51]
	v_mfma_f32_16x16x32_bf16 v[36:39], v[140:143], v[172:175], v[36:39]
	v_mfma_f32_16x16x32_bf16 v[32:35], v[156:159], v[172:175], v[32:35]
	v_mfma_f32_16x16x32_bf16 v[20:23], v[140:143], v[180:183], v[20:23]
	v_mfma_f32_16x16x32_bf16 v[16:19], v[156:159], v[180:183], v[16:19]
	v_mfma_f32_16x16x32_bf16 v[4:7], v[140:143], v[208:211], v[4:7]
	v_mfma_f32_16x16x32_bf16 v[0:3], v[156:159], v[208:211], v[0:3]
	s_barrier
	s_add_i32 s49, 0, 0x18000
	s_add_i32 s50, 0, 0x1c000
	v_add_u32_e32 v124, s49, v240
	v_add_u32_e32 v156, s50, v240
	ds_read_b128 v[112:115], v124
	ds_read_b128 v[116:119], v124 offset:1024
	ds_read_b128 v[120:123], v124 offset:2048
	ds_read_b128 v[124:127], v124 offset:3072
	ds_read_b128 v[128:131], v156
	ds_read_b128 v[140:143], v156 offset:1024
	ds_read_b128 v[152:155], v156 offset:2048
	ds_read_b128 v[156:159], v156 offset:3072
	s_add_u32 s18, s24, 0xb0000
	s_addc_u32 s19, s25, 0
	s_mov_b32 m0, s37
	v_lshl_add_u64 v[220:221], s[18:19], 0, v[202:203]
	ds_read_b128 v[160:163], v244 offset:32768
	ds_read_b128 v[164:167], v244 offset:33792
	ds_read_b128 v[168:171], v244 offset:34816
	ds_read_b128 v[172:175], v244 offset:35840
	ds_read_b128 v[176:179], v244 offset:36864
	ds_read_b128 v[180:183], v244 offset:37888
	ds_read_b128 v[184:187], v244 offset:38912
	ds_read_b128 v[208:211], v244 offset:39936
	global_load_lds_dwordx4 v[220:221], off
	v_lshl_add_u64 v[220:221], s[18:19], 0, v[200:201]
	s_mov_b32 m0, s38
	s_nop 0
	global_load_lds_dwordx4 v[220:221], off
	s_waitcnt vmcnt(8)
	s_waitcnt lgkmcnt(0)
	s_barrier
	s_waitcnt lgkmcnt(0)
	v_mfma_f32_16x16x32_bf16 v[148:151], v[112:115], v[160:163], v[148:151]
	v_mfma_f32_16x16x32_bf16 v[144:147], v[120:123], v[160:163], v[144:147]
	v_mfma_f32_16x16x32_bf16 v[108:111], v[112:115], v[168:171], v[108:111]
	v_mfma_f32_16x16x32_bf16 v[104:107], v[120:123], v[168:171], v[104:107]
	v_mfma_f32_16x16x32_bf16 v[92:95], v[112:115], v[176:179], v[92:95]
	v_mfma_f32_16x16x32_bf16 v[88:91], v[120:123], v[176:179], v[88:91]
	v_mfma_f32_16x16x32_bf16 v[76:79], v[112:115], v[184:187], v[76:79]
	v_mfma_f32_16x16x32_bf16 v[72:75], v[120:123], v[184:187], v[72:75]
	v_mfma_f32_16x16x32_bf16 v[148:151], v[116:119], v[164:167], v[148:151]
	v_mfma_f32_16x16x32_bf16 v[144:147], v[124:127], v[164:167], v[144:147]
	v_mfma_f32_16x16x32_bf16 v[108:111], v[116:119], v[172:175], v[108:111]
	v_mfma_f32_16x16x32_bf16 v[104:107], v[124:127], v[172:175], v[104:107]
	v_mfma_f32_16x16x32_bf16 v[92:95], v[116:119], v[180:183], v[92:95]
	v_mfma_f32_16x16x32_bf16 v[88:91], v[124:127], v[180:183], v[88:91]
	v_mfma_f32_16x16x32_bf16 v[76:79], v[116:119], v[208:211], v[76:79]
	v_mfma_f32_16x16x32_bf16 v[72:75], v[124:127], v[208:211], v[72:75]
	v_mfma_f32_16x16x32_bf16 v[136:139], v[128:131], v[160:163], v[136:139]
	v_mfma_f32_16x16x32_bf16 v[132:135], v[152:155], v[160:163], v[132:135]
	v_mfma_f32_16x16x32_bf16 v[100:103], v[128:131], v[168:171], v[100:103]
	v_mfma_f32_16x16x32_bf16 v[96:99], v[152:155], v[168:171], v[96:99]
	v_mfma_f32_16x16x32_bf16 v[84:87], v[128:131], v[176:179], v[84:87]
	v_mfma_f32_16x16x32_bf16 v[80:83], v[152:155], v[176:179], v[80:83]
	v_mfma_f32_16x16x32_bf16 v[68:71], v[128:131], v[184:187], v[68:71]
	v_mfma_f32_16x16x32_bf16 v[64:67], v[152:155], v[184:187], v[64:67]
	v_mfma_f32_16x16x32_bf16 v[136:139], v[140:143], v[164:167], v[136:139]
	v_mfma_f32_16x16x32_bf16 v[132:135], v[156:159], v[164:167], v[132:135]
	v_mfma_f32_16x16x32_bf16 v[100:103], v[140:143], v[172:175], v[100:103]
	v_mfma_f32_16x16x32_bf16 v[96:99], v[156:159], v[172:175], v[96:99]
	v_mfma_f32_16x16x32_bf16 v[84:87], v[140:143], v[180:183], v[84:87]
	v_mfma_f32_16x16x32_bf16 v[80:83], v[156:159], v[180:183], v[80:83]
	v_mfma_f32_16x16x32_bf16 v[68:71], v[140:143], v[208:211], v[68:71]
	v_mfma_f32_16x16x32_bf16 v[64:67], v[156:159], v[208:211], v[64:67]
	s_barrier
; #define PG8_STAGE(bufoff, gbase, voff) do { _Pragma("unroll") for (int _i = 0; _i < 2; ++_i) \
;         __builtin_amdgcn_global_load_lds((const unsigned*)((const char*)(gbase) + (voff)[_i]), (LAS unsigned*)(lds + (bufoff) + ldsw + _i * 8192), 16, 0, 0); } while (0)
; #define PG8_LDA(dst, b, h) do { _Pragma("unroll") for (int m = 0; m < 4; ++m) _Pragma("unroll") for (int k = 0; k < 2; ++k) dst[m][k] = *(const LAS bf16x8*)(lds + PG8_SA(b, h) + aoff + m * 2048 + k * 1024); } while (0)
; #define PG8_LDB(dst, b, h) do { _Pragma("unroll") for (int n = 0; n < 2; ++n) _Pragma("unroll") for (int k = 0; k < 2; ++k) dst[n][k] = *(const LAS bf16x8*)(lds + PG8_SB(b, h) + boff + n * 2048 + k * 1024); } while (0)
; #define PG8_MMA(ai, bj, At, Bt) do { __builtin_amdgcn_s_setprio(1); _Pragma("unroll") for (int m = 0; m < 4; ++m) _Pragma("unroll") for (int n = 0; n < 2; ++n) _Pragma("unroll") for (int k = 0; k < 2; ++k) \
;         acc[ai][bj][m][n] = __builtin_amdgcn_mfma_f32_16x16x32_bf16(Bt[n][k], At[m][k], acc[ai][bj][m][n], 0, 0, 0); __builtin_amdgcn_s_setprio(0); } while (0)
; #define PG8_WAIT_V(n) asm volatile("s_waitcnt vmcnt(" #n ")" ::: "memory")
; #define PG8_WAIT_L(n) asm volatile("s_waitcnt lgkmcnt(" #n ")" ::: "memory")
; #define PG8_BAR __builtin_amdgcn_s_barrier()
; #define PG8_SCHED __builtin_amdgcn_sched_barrier(0)
; template <class Epi, class Sched>
; __device__ __forceinline__ void gemm_phase(int wv, LAS unsigned char* lds, const Gemm g, const Sched& S, const Epi& E) {
;     ...
;             PG8_LDB(B0, 1, 0); PG8_LDB(B1, 1, 1); PG8_SCHED; PG8_LDA(At, 1, 0); PG8_STAGE(PG8_SA(0, 1), a2 + hstep, voffA);
;             PG8_WAIT_V(8); PG8_WAIT_L(0); PG8_BAR; PG8_MMA(0, 0, At, B0); PG8_MMA(0, 1, At, B1); PG8_BAR; PG8_SCHED;
;             PG8_LDA(At, 1, 1); PG8_STAGE(PG8_SB(1, 0), b3, voffB); PG8_STAGE(PG8_SB(1, 1), b3 + hstepB, voffB); PG8_STAGE(PG8_SA(1, 0), a3, voffA);
;             PG8_WAIT_V(8); PG8_WAIT_L(0); PG8_BAR; PG8_MMA(1, 0, At, B0); PG8_MMA(1, 1, At, B1); PG8_BAR; PG8_SCHED;
;         }
	s_add_i32 s18, s49, s30
	v_lshl_add_u64 v[212:213], v[212:213], 0, s[74:75]
	s_mov_b32 m0, s18
	ds_read_b128 v[160:163], v244 offset:49152
	ds_read_b128 v[164:167], v244 offset:50176
	ds_read_b128 v[168:171], v244 offset:51200
	ds_read_b128 v[172:175], v244 offset:52224
	ds_read_b128 v[176:179], v244 offset:53248
	ds_read_b128 v[180:183], v244 offset:54272
	ds_read_b128 v[184:187], v244 offset:55296
	ds_read_b128 v[208:211], v244 offset:56320
	global_load_lds_dwordx4 v[212:213], off
	s_add_i32 m0, s18, 0x2000
	s_add_u32 s18, s22, 0xb080
	v_lshl_add_u64 v[212:213], v[214:215], 0, s[74:75]
	s_addc_u32 s19, s23, 0
	s_add_i32 s22, s50, s30
	global_load_lds_dwordx4 v[212:213], off
	v_lshl_add_u64 v[212:213], s[18:19], 0, v[188:189]
	s_mov_b32 m0, s22
	s_nop 0
	global_load_lds_dwordx4 v[212:213], off
	v_lshl_add_u64 v[212:213], s[18:19], 0, v[198:199]
	s_add_i32 m0, s22, 0x2000
	s_nop 0
	global_load_lds_dwordx4 v[212:213], off
	v_lshl_add_u64 v[212:213], v[216:217], 0, s[74:75]
	s_mov_b32 m0, s39
	s_nop 0
	global_load_lds_dwordx4 v[212:213], off
	v_lshl_add_u64 v[212:213], v[218:219], 0, s[74:75]
	s_mov_b32 m0, s40
	s_nop 0
	global_load_lds_dwordx4 v[212:213], off
	s_waitcnt vmcnt(8)
	s_waitcnt lgkmcnt(0)
	s_barrier
	s_waitcnt lgkmcnt(0)
	v_mfma_f32_16x16x32_bf16 v[60:63], v[112:115], v[160:163], v[60:63]
	v_mfma_f32_16x16x32_bf16 v[56:59], v[120:123], v[160:163], v[56:59]
	v_mfma_f32_16x16x32_bf16 v[44:47], v[112:115], v[168:171], v[44:47]
	v_mfma_f32_16x16x32_bf16 v[40:43], v[120:123], v[168:171], v[40:43]
	v_mfma_f32_16x16x32_bf16 v[28:31], v[112:115], v[176:179], v[28:31]
	v_mfma_f32_16x16x32_bf16 v[24:27], v[120:123], v[176:179], v[24:27]
	v_mfma_f32_16x16x32_bf16 v[12:15], v[112:115], v[184:187], v[12:15]
	v_mfma_f32_16x16x32_bf16 v[8:11], v[120:123], v[184:187], v[8:11]
	v_mfma_f32_16x16x32_bf16 v[60:63], v[116:119], v[164:167], v[60:63]
	v_mfma_f32_16x16x32_bf16 v[56:59], v[124:127], v[164:167], v[56:59]
	v_mfma_f32_16x16x32_bf16 v[44:47], v[116:119], v[172:175], v[44:47]
	v_mfma_f32_16x16x32_bf16 v[40:43], v[124:127], v[172:175], v[40:43]
	v_mfma_f32_16x16x32_bf16 v[28:31], v[116:119], v[180:183], v[28:31]
	v_mfma_f32_16x16x32_bf16 v[24:27], v[124:127], v[180:183], v[24:27]
	v_mfma_f32_16x16x32_bf16 v[12:15], v[116:119], v[208:211], v[12:15]
	v_mfma_f32_16x16x32_bf16 v[8:11], v[124:127], v[208:211], v[8:11]
	v_mfma_f32_16x16x32_bf16 v[52:55], v[128:131], v[160:163], v[52:55]
	v_mfma_f32_16x16x32_bf16 v[48:51], v[152:155], v[160:163], v[48:51]
	v_mfma_f32_16x16x32_bf16 v[36:39], v[128:131], v[168:171], v[36:39]
	v_mfma_f32_16x16x32_bf16 v[32:35], v[152:155], v[168:171], v[32:35]
	v_mfma_f32_16x16x32_bf16 v[20:23], v[128:131], v[176:179], v[20:23]
	v_mfma_f32_16x16x32_bf16 v[16:19], v[152:155], v[176:179], v[16:19]
	v_mfma_f32_16x16x32_bf16 v[4:7], v[128:131], v[184:187], v[4:7]
	v_mfma_f32_16x16x32_bf16 v[0:3], v[152:155], v[184:187], v[0:3]
	v_mfma_f32_16x16x32_bf16 v[52:55], v[140:143], v[164:167], v[52:55]
	v_mfma_f32_16x16x32_bf16 v[48:51], v[156:159], v[164:167], v[48:51]
	v_mfma_f32_16x16x32_bf16 v[36:39], v[140:143], v[172:175], v[36:39]
	v_mfma_f32_16x16x32_bf16 v[32:35], v[156:159], v[172:175], v[32:35]
	v_mfma_f32_16x16x32_bf16 v[20:23], v[140:143], v[180:183], v[20:23]
	v_mfma_f32_16x16x32_bf16 v[16:19], v[156:159], v[180:183], v[16:19]
	v_mfma_f32_16x16x32_bf16 v[4:7], v[140:143], v[208:211], v[4:7]
	v_mfma_f32_16x16x32_bf16 v[0:3], v[156:159], v[208:211], v[0:3]
	s_barrier
	s_add_i32 s48, s48, 2
	s_add_u32 s46, s46, 0x100
	s_addc_u32 s47, s47, 0
	s_cmp_gt_u32 s48, 41
	s_mov_b64 s[18:19], s[20:21]
	s_cbranch_scc0 .LBB0_255
	s_and_b64 vcc, exec, s[14:15]
	s_cbranch_vccz .LBB0_258
	s_barrier

; #define PG8_STAGE(bufoff, gbase, voff) do { _Pragma("unroll") for (int _i = 0; _i < 2; ++_i) \
;         __builtin_amdgcn_global_load_lds((const unsigned*)((const char*)(gbase) + (voff)[_i]), (LAS unsigned*)(lds + (bufoff) + ldsw + _i * 8192), 16, 0, 0); } while (0)
; #define PG8_LDA(dst, b, h) do { _Pragma("unroll") for (int m = 0; m < 4; ++m) _Pragma("unroll") for (int k = 0; k < 2; ++k) dst[m][k] = *(const LAS bf16x8*)(lds + PG8_SA(b, h) + aoff + m * 2048 + k * 1024); } while (0)
; #define PG8_LDB(dst, b, h) do { _Pragma("unroll") for (int n = 0; n < 2; ++n) _Pragma("unroll") for (int k = 0; k < 2; ++k) dst[n][k] = *(const LAS bf16x8*)(lds + PG8_SB(b, h) + boff + n * 2048 + k * 1024); } while (0)
; #define PG8_MMA(ai, bj, At, Bt) do { __builtin_amdgcn_s_setprio(1); _Pragma("unroll") for (int m = 0; m < 4; ++m) _Pragma("unroll") for (int n = 0; n < 2; ++n) _Pragma("unroll") for (int k = 0; k < 2; ++k) \
;         acc[ai][bj][m][n] = __builtin_amdgcn_mfma_f32_16x16x32_bf16(Bt[n][k], At[m][k], acc[ai][bj][m][n], 0, 0, 0); __builtin_amdgcn_s_setprio(0); } while (0)
; #define PG8_WAIT_V(n) asm volatile("s_waitcnt vmcnt(" #n ")" ::: "memory")
; #define PG8_WAIT_L(n) asm volatile("s_waitcnt lgkmcnt(" #n ")" ::: "memory")
; #define PG8_BAR __builtin_amdgcn_s_barrier()
; #define PG8_SCHED __builtin_amdgcn_sched_barrier(0)
; template <class Epi, class Sched>
; __device__ __forceinline__ void gemm_phase(int wv, LAS unsigned char* lds, const Gemm g, const Sched& S, const Epi& E) {
;     ...
;             const bool last = (t == nt - 2);
;             const char* a1 = cA + (size_t)(t + 1) * kstep;
;             const char* a2 = last ? nA : cA + (size_t)(t + 2) * kstep; const char* b2 = last ? nB : cB + (size_t)(t + 2) * kstep;
;             const char* a3 = a2 + kstep; const char* b3 = b2 + kstep;
;             PG8_LDB(B0, 0, 0); PG8_LDB(B1, 0, 1); PG8_SCHED; PG8_LDA(At, 0, 0); PG8_STAGE(PG8_SA(1, 1), a1 + hstep, voffA);
;             PG8_WAIT_V(8); PG8_WAIT_L(0); PG8_BAR; PG8_MMA(0, 0, At, B0); PG8_MMA(0, 1, At, B1); PG8_BAR; PG8_SCHED;
;             PG8_LDA(At, 0, 1); PG8_STAGE(PG8_SB(0, 0), b2, voffB); PG8_STAGE(PG8_SB(0, 1), b2 + hstepB, voffB); PG8_STAGE(PG8_SA(0, 0), a2, voffA);
;             PG8_WAIT_V(8); PG8_WAIT_L(0); PG8_BAR; PG8_MMA(1, 0, At, B0); PG8_MMA(1, 1, At, B1); PG8_BAR; PG8_SCHED;
.LBB0_344:
	s_add_u32 s18, s2, 0xfffc0080
	s_addc_u32 s19, s3, -1
	s_add_i32 s47, 0, 0x10000
	s_cmp_eq_u32 s46, 12
	s_cselect_b32 s21, s11, s19
	s_cselect_b32 s20, s41, s18
	s_cselect_b32 s19, s13, s45
	s_cselect_b32 s18, s42, s43
	s_add_i32 s50, 0, 0x14000
	v_add_u32_e32 v156, s47, v145
	v_add_u32_e32 v172, s50, v145
	ds_read_b128 v[140:143], v156
	ds_read_b128 v[148:151], v156 offset:1024
	ds_read_b128 v[152:155], v156 offset:2048
	ds_read_b128 v[156:159], v156 offset:3072
	ds_read_b128 v[160:163], v172
	ds_read_b128 v[164:167], v172 offset:1024
	ds_read_b128 v[168:171], v172 offset:2048
	ds_read_b128 v[172:175], v172 offset:3072
	v_lshl_add_u64 v[218:219], s[2:3], 0, v[136:137]
	s_add_i32 m0, s27, 0xc000
	ds_read_b128 v[176:179], v147
	ds_read_b128 v[180:183], v147 offset:1024
	ds_read_b128 v[184:187], v147 offset:2048
	ds_read_b128 v[198:201], v147 offset:3072
	ds_read_b128 v[202:205], v147 offset:4096
	ds_read_b128 v[206:209], v147 offset:5120
	ds_read_b128 v[210:213], v147 offset:6144
	ds_read_b128 v[214:217], v147 offset:7168
	global_load_lds_dwordx4 v[218:219], off
	v_lshl_add_u64 v[218:219], s[2:3], 0, v[138:139]
	s_add_i32 m0, s27, 0xe000
	s_nop 0
	global_load_lds_dwordx4 v[218:219], off
	s_waitcnt vmcnt(8)
	s_waitcnt lgkmcnt(0)
	s_barrier
	s_waitcnt lgkmcnt(0)
	v_mfma_f32_16x16x32_bf16 v[124:127], v[140:143], v[176:179], v[124:127]
	v_mfma_f32_16x16x32_bf16 v[120:123], v[152:155], v[176:179], v[120:123]
	v_mfma_f32_16x16x32_bf16 v[108:111], v[140:143], v[184:187], v[108:111]
	v_mfma_f32_16x16x32_bf16 v[104:107], v[152:155], v[184:187], v[104:107]
	v_mfma_f32_16x16x32_bf16 v[92:95], v[140:143], v[202:205], v[92:95]
	v_mfma_f32_16x16x32_bf16 v[88:91], v[152:155], v[202:205], v[88:91]
	v_mfma_f32_16x16x32_bf16 v[76:79], v[140:143], v[210:213], v[76:79]
	v_mfma_f32_16x16x32_bf16 v[72:75], v[152:155], v[210:213], v[72:75]
	v_mfma_f32_16x16x32_bf16 v[124:127], v[148:151], v[180:183], v[124:127]
	v_mfma_f32_16x16x32_bf16 v[120:123], v[156:159], v[180:183], v[120:123]
	v_mfma_f32_16x16x32_bf16 v[108:111], v[148:151], v[198:201], v[108:111]
	v_mfma_f32_16x16x32_bf16 v[104:107], v[156:159], v[198:201], v[104:107]
	v_mfma_f32_16x16x32_bf16 v[92:95], v[148:151], v[206:209], v[92:95]
	v_mfma_f32_16x16x32_bf16 v[88:91], v[156:159], v[206:209], v[88:91]
	v_mfma_f32_16x16x32_bf16 v[76:79], v[148:151], v[214:217], v[76:79]
	v_mfma_f32_16x16x32_bf16 v[72:75], v[156:159], v[214:217], v[72:75]
	v_mfma_f32_16x16x32_bf16 v[116:119], v[160:163], v[176:179], v[116:119]
	v_mfma_f32_16x16x32_bf16 v[112:115], v[168:171], v[176:179], v[112:115]
	v_mfma_f32_16x16x32_bf16 v[100:103], v[160:163], v[184:187], v[100:103]
	v_mfma_f32_16x16x32_bf16 v[96:99], v[168:171], v[184:187], v[96:99]
	v_mfma_f32_16x16x32_bf16 v[84:87], v[160:163], v[202:205], v[84:87]
	v_mfma_f32_16x16x32_bf16 v[80:83], v[168:171], v[202:205], v[80:83]
	v_mfma_f32_16x16x32_bf16 v[68:71], v[160:163], v[210:213], v[68:71]
	v_mfma_f32_16x16x32_bf16 v[64:67], v[168:171], v[210:213], v[64:67]
	v_mfma_f32_16x16x32_bf16 v[116:119], v[164:167], v[180:183], v[116:119]
	v_mfma_f32_16x16x32_bf16 v[112:115], v[172:175], v[180:183], v[112:115]
	v_mfma_f32_16x16x32_bf16 v[100:103], v[164:167], v[198:201], v[100:103]
	v_mfma_f32_16x16x32_bf16 v[96:99], v[172:175], v[198:201], v[96:99]
	v_mfma_f32_16x16x32_bf16 v[84:87], v[164:167], v[206:209], v[84:87]
	v_mfma_f32_16x16x32_bf16 v[80:83], v[172:175], v[206:209], v[80:83]
	v_mfma_f32_16x16x32_bf16 v[68:71], v[164:167], v[214:217], v[68:71]
	v_mfma_f32_16x16x32_bf16 v[64:67], v[172:175], v[214:217], v[64:67]
	s_barrier
	s_add_i32 s47, s47, s26
	v_lshl_add_u64 v[218:219], s[18:19], 0, v[132:133]
	s_mov_b32 m0, s47
	ds_read_b128 v[176:179], v147 offset:16384
	ds_read_b128 v[180:183], v147 offset:17408
	ds_read_b128 v[184:187], v147 offset:18432
	ds_read_b128 v[198:201], v147 offset:19456
	ds_read_b128 v[202:205], v147 offset:20480
	ds_read_b128 v[206:209], v147 offset:21504
	ds_read_b128 v[210:213], v147 offset:22528
	ds_read_b128 v[214:217], v147 offset:23552
	global_load_lds_dwordx4 v[218:219], off
	s_add_i32 m0, s47, 0x2000
	s_add_u32 s48, s18, 0x4000
	v_lshl_add_u64 v[220:221], s[18:19], 0, v[128:129]
	s_addc_u32 s49, s19, 0
	s_add_i32 s47, s50, s26
	global_load_lds_dwordx4 v[220:221], off
	v_lshl_add_u64 v[222:223], s[48:49], 0, v[132:133]
	s_mov_b32 m0, s47
	v_lshl_add_u64 v[228:229], s[20:21], 0, v[130:131]
	global_load_lds_dwordx4 v[222:223], off
	v_lshl_add_u64 v[222:223], s[48:49], 0, v[128:129]
	s_add_i32 m0, s47, 0x2000
	s_nop 0
	global_load_lds_dwordx4 v[222:223], off
	v_lshl_add_u64 v[222:223], s[20:21], 0, v[134:135]
	s_mov_b32 m0, s27
	s_nop 0
	global_load_lds_dwordx4 v[222:223], off
	s_mov_b32 m0, s28
	s_nop 0
	global_load_lds_dwordx4 v[228:229], off
	s_waitcnt vmcnt(8)
	s_waitcnt lgkmcnt(0)
	s_barrier
; #define PG8_STAGE(bufoff, gbase, voff) do { _Pragma("unroll") for (int _i = 0; _i < 2; ++_i) \
;         __builtin_amdgcn_global_load_lds((const unsigned*)((const char*)(gbase) + (voff)[_i]), (LAS unsigned*)(lds + (bufoff) + ldsw + _i * 8192), 16, 0, 0); } while (0)
; #define PG8_LDA(dst, b, h) do { _Pragma("unroll") for (int m = 0; m < 4; ++m) _Pragma("unroll") for (int k = 0; k < 2; ++k) dst[m][k] = *(const LAS bf16x8*)(lds + PG8_SA(b, h) + aoff + m * 2048 + k * 1024); } while (0)
; #define PG8_LDB(dst, b, h) do { _Pragma("unroll") for (int n = 0; n < 2; ++n) _Pragma("unroll") for (int k = 0; k < 2; ++k) dst[n][k] = *(const LAS bf16x8*)(lds + PG8_SB(b, h) + boff + n * 2048 + k * 1024); } while (0)
; #define PG8_MMA(ai, bj, At, Bt) do { __builtin_amdgcn_s_setprio(1); _Pragma("unroll") for (int m = 0; m < 4; ++m) _Pragma("unroll") for (int n = 0; n < 2; ++n) _Pragma("unroll") for (int k = 0; k < 2; ++k) \
;         acc[ai][bj][m][n] = __builtin_amdgcn_mfma_f32_16x16x32_bf16(Bt[n][k], At[m][k], acc[ai][bj][m][n], 0, 0, 0); __builtin_amdgcn_s_setprio(0); } while (0)
; #define PG8_WAIT_V(n) asm volatile("s_waitcnt vmcnt(" #n ")" ::: "memory")
; #define PG8_WAIT_L(n) asm volatile("s_waitcnt lgkmcnt(" #n ")" ::: "memory")
; #define PG8_BAR __builtin_amdgcn_s_barrier()
; #define PG8_SCHED __builtin_amdgcn_sched_barrier(0)
; template <class Epi, class Sched>
; __device__ __forceinline__ void gemm_phase(int wv, LAS unsigned char* lds, const Gemm g, const Sched& S, const Epi& E) {
;     ...
;             PG8_WAIT_V(8); PG8_WAIT_L(0); PG8_BAR; PG8_MMA(1, 0, At, B0); PG8_MMA(1, 1, At, B1); PG8_BAR; PG8_SCHED;
;             PG8_LDB(B0, 1, 0); PG8_LDB(B1, 1, 1); PG8_SCHED; PG8_LDA(At, 1, 0); PG8_STAGE(PG8_SA(0, 1), a2 + hstep, voffA);
;             PG8_WAIT_V(8); PG8_WAIT_L(0); PG8_BAR; PG8_MMA(0, 0, At, B0); PG8_MMA(0, 1, At, B1); PG8_BAR; PG8_SCHED;
	s_waitcnt lgkmcnt(0)
	v_mfma_f32_16x16x32_bf16 v[60:63], v[140:143], v[176:179], v[60:63]
	v_mfma_f32_16x16x32_bf16 v[56:59], v[152:155], v[176:179], v[56:59]
	v_mfma_f32_16x16x32_bf16 v[44:47], v[140:143], v[184:187], v[44:47]
	v_mfma_f32_16x16x32_bf16 v[40:43], v[152:155], v[184:187], v[40:43]
	v_mfma_f32_16x16x32_bf16 v[28:31], v[140:143], v[202:205], v[28:31]
	v_mfma_f32_16x16x32_bf16 v[24:27], v[152:155], v[202:205], v[24:27]
	v_mfma_f32_16x16x32_bf16 v[12:15], v[140:143], v[210:213], v[12:15]
	v_mfma_f32_16x16x32_bf16 v[8:11], v[152:155], v[210:213], v[8:11]
	v_mfma_f32_16x16x32_bf16 v[60:63], v[148:151], v[180:183], v[60:63]
	v_mfma_f32_16x16x32_bf16 v[56:59], v[156:159], v[180:183], v[56:59]
	v_mfma_f32_16x16x32_bf16 v[44:47], v[148:151], v[198:201], v[44:47]
	v_mfma_f32_16x16x32_bf16 v[40:43], v[156:159], v[198:201], v[40:43]
	v_mfma_f32_16x16x32_bf16 v[28:31], v[148:151], v[206:209], v[28:31]
	v_mfma_f32_16x16x32_bf16 v[24:27], v[156:159], v[206:209], v[24:27]
	v_mfma_f32_16x16x32_bf16 v[12:15], v[148:151], v[214:217], v[12:15]
	v_mfma_f32_16x16x32_bf16 v[8:11], v[156:159], v[214:217], v[8:11]
	v_mfma_f32_16x16x32_bf16 v[52:55], v[160:163], v[176:179], v[52:55]
	v_mfma_f32_16x16x32_bf16 v[48:51], v[168:171], v[176:179], v[48:51]
	v_mfma_f32_16x16x32_bf16 v[36:39], v[160:163], v[184:187], v[36:39]
	v_mfma_f32_16x16x32_bf16 v[32:35], v[168:171], v[184:187], v[32:35]
	v_mfma_f32_16x16x32_bf16 v[20:23], v[160:163], v[202:205], v[20:23]
	v_mfma_f32_16x16x32_bf16 v[16:19], v[168:171], v[202:205], v[16:19]
	v_mfma_f32_16x16x32_bf16 v[4:7], v[160:163], v[210:213], v[4:7]
	v_mfma_f32_16x16x32_bf16 v[0:3], v[168:171], v[210:213], v[0:3]
	v_mfma_f32_16x16x32_bf16 v[52:55], v[164:167], v[180:183], v[52:55]
	v_mfma_f32_16x16x32_bf16 v[48:51], v[172:175], v[180:183], v[48:51]
	v_mfma_f32_16x16x32_bf16 v[36:39], v[164:167], v[198:201], v[36:39]
	v_mfma_f32_16x16x32_bf16 v[32:35], v[172:175], v[198:201], v[32:35]
	v_mfma_f32_16x16x32_bf16 v[20:23], v[164:167], v[206:209], v[20:23]
	v_mfma_f32_16x16x32_bf16 v[16:19], v[172:175], v[206:209], v[16:19]
	v_mfma_f32_16x16x32_bf16 v[4:7], v[164:167], v[214:217], v[4:7]
	v_mfma_f32_16x16x32_bf16 v[0:3], v[172:175], v[214:217], v[0:3]
	s_barrier
	s_add_i32 s47, 0, 0x18000
	s_add_i32 s48, 0, 0x1c000
	v_add_u32_e32 v156, s47, v145
	v_add_u32_e32 v172, s48, v145
	ds_read_b128 v[140:143], v156
	ds_read_b128 v[148:151], v156 offset:1024
	ds_read_b128 v[152:155], v156 offset:2048
	ds_read_b128 v[156:159], v156 offset:3072
	ds_read_b128 v[160:163], v172
	ds_read_b128 v[164:167], v172 offset:1024
	ds_read_b128 v[168:171], v172 offset:2048
	ds_read_b128 v[172:175], v172 offset:3072
	s_add_u32 s20, s20, 0x40000
	s_addc_u32 s21, s21, 0
	s_mov_b32 m0, s29
	v_lshl_add_u64 v[230:231], s[20:21], 0, v[134:135]
	ds_read_b128 v[176:179], v147 offset:32768
	ds_read_b128 v[180:183], v147 offset:33792
	ds_read_b128 v[184:187], v147 offset:34816
	ds_read_b128 v[198:201], v147 offset:35840
	ds_read_b128 v[202:205], v147 offset:36864
	ds_read_b128 v[206:209], v147 offset:37888
	ds_read_b128 v[210:213], v147 offset:38912
	ds_read_b128 v[214:217], v147 offset:39936
	global_load_lds_dwordx4 v[230:231], off
	v_lshl_add_u64 v[230:231], s[20:21], 0, v[130:131]
	s_mov_b32 m0, s30
	s_nop 0
	global_load_lds_dwordx4 v[230:231], off
	s_waitcnt vmcnt(8)
	s_waitcnt lgkmcnt(0)
	s_barrier
	s_waitcnt lgkmcnt(0)
	v_mfma_f32_16x16x32_bf16 v[124:127], v[140:143], v[176:179], v[124:127]
	v_mfma_f32_16x16x32_bf16 v[120:123], v[152:155], v[176:179], v[120:123]
	v_mfma_f32_16x16x32_bf16 v[108:111], v[140:143], v[184:187], v[108:111]
	v_mfma_f32_16x16x32_bf16 v[104:107], v[152:155], v[184:187], v[104:107]
	v_mfma_f32_16x16x32_bf16 v[92:95], v[140:143], v[202:205], v[92:95]
	v_mfma_f32_16x16x32_bf16 v[88:91], v[152:155], v[202:205], v[88:91]
	v_mfma_f32_16x16x32_bf16 v[76:79], v[140:143], v[210:213], v[76:79]
	v_mfma_f32_16x16x32_bf16 v[72:75], v[152:155], v[210:213], v[72:75]
	v_mfma_f32_16x16x32_bf16 v[124:127], v[148:151], v[180:183], v[124:127]
	v_mfma_f32_16x16x32_bf16 v[120:123], v[156:159], v[180:183], v[120:123]
	v_mfma_f32_16x16x32_bf16 v[108:111], v[148:151], v[198:201], v[108:111]
	v_mfma_f32_16x16x32_bf16 v[104:107], v[156:159], v[198:201], v[104:107]
	v_mfma_f32_16x16x32_bf16 v[92:95], v[148:151], v[206:209], v[92:95]
	v_mfma_f32_16x16x32_bf16 v[88:91], v[156:159], v[206:209], v[88:91]
	v_mfma_f32_16x16x32_bf16 v[76:79], v[148:151], v[214:217], v[76:79]
	v_mfma_f32_16x16x32_bf16 v[72:75], v[156:159], v[214:217], v[72:75]
	v_mfma_f32_16x16x32_bf16 v[116:119], v[160:163], v[176:179], v[116:119]
	v_mfma_f32_16x16x32_bf16 v[112:115], v[168:171], v[176:179], v[112:115]
	v_mfma_f32_16x16x32_bf16 v[100:103], v[160:163], v[184:187], v[100:103]
	v_mfma_f32_16x16x32_bf16 v[96:99], v[168:171], v[184:187], v[96:99]
	v_mfma_f32_16x16x32_bf16 v[84:87], v[160:163], v[202:205], v[84:87]
	v_mfma_f32_16x16x32_bf16 v[80:83], v[168:171], v[202:205], v[80:83]
	v_mfma_f32_16x16x32_bf16 v[68:71], v[160:163], v[210:213], v[68:71]
	v_mfma_f32_16x16x32_bf16 v[64:67], v[168:171], v[210:213], v[64:67]
	v_mfma_f32_16x16x32_bf16 v[116:119], v[164:167], v[180:183], v[116:119]
	v_mfma_f32_16x16x32_bf16 v[112:115], v[172:175], v[180:183], v[112:115]
	v_mfma_f32_16x16x32_bf16 v[100:103], v[164:167], v[198:201], v[100:103]
	v_mfma_f32_16x16x32_bf16 v[96:99], v[172:175], v[198:201], v[96:99]
	v_mfma_f32_16x16x32_bf16 v[84:87], v[164:167], v[206:209], v[84:87]
	v_mfma_f32_16x16x32_bf16 v[80:83], v[172:175], v[206:209], v[80:83]
	v_mfma_f32_16x16x32_bf16 v[68:71], v[164:167], v[214:217], v[68:71]
	v_mfma_f32_16x16x32_bf16 v[64:67], v[172:175], v[214:217], v[64:67]
	s_barrier
; #define PG8_STAGE(bufoff, gbase, voff) do { _Pragma("unroll") for (int _i = 0; _i < 2; ++_i) \
;         __builtin_amdgcn_global_load_lds((const unsigned*)((const char*)(gbase) + (voff)[_i]), (LAS unsigned*)(lds + (bufoff) + ldsw + _i * 8192), 16, 0, 0); } while (0)
; #define PG8_LDA(dst, b, h) do { _Pragma("unroll") for (int m = 0; m < 4; ++m) _Pragma("unroll") for (int k = 0; k < 2; ++k) dst[m][k] = *(const LAS bf16x8*)(lds + PG8_SA(b, h) + aoff + m * 2048 + k * 1024); } while (0)
; #define PG8_MMA(ai, bj, At, Bt) do { __builtin_amdgcn_s_setprio(1); _Pragma("unroll") for (int m = 0; m < 4; ++m) _Pragma("unroll") for (int n = 0; n < 2; ++n) _Pragma("unroll") for (int k = 0; k < 2; ++k) \
;         acc[ai][bj][m][n] = __builtin_amdgcn_mfma_f32_16x16x32_bf16(Bt[n][k], At[m][k], acc[ai][bj][m][n], 0, 0, 0); __builtin_amdgcn_s_setprio(0); } while (0)
; #define PG8_WAIT_V(n) asm volatile("s_waitcnt vmcnt(" #n ")" ::: "memory")
; #define PG8_WAIT_L(n) asm volatile("s_waitcnt lgkmcnt(" #n ")" ::: "memory")
; #define PG8_BAR __builtin_amdgcn_s_barrier()
; #define PG8_SCHED __builtin_amdgcn_sched_barrier(0)
; template <class Epi, class Sched>
; __device__ __forceinline__ void gemm_phase(int wv, LAS unsigned char* lds, const Gemm g, const Sched& S, const Epi& E) {
;     ...
;             PG8_LDA(At, 1, 1); PG8_STAGE(PG8_SB(1, 0), b3, voffB); PG8_STAGE(PG8_SB(1, 1), b3 + hstepB, voffB); PG8_STAGE(PG8_SA(1, 0), a3, voffA);
;             PG8_WAIT_V(8); PG8_WAIT_L(0); PG8_BAR; PG8_MMA(1, 0, At, B0); PG8_MMA(1, 1, At, B1); PG8_BAR; PG8_SCHED;
;         }
;         if (wr == 0) PG8_BAR;
	s_add_i32 s20, s47, s26
	v_lshl_add_u64 v[218:219], v[218:219], 0, s[74:75]
	s_mov_b32 m0, s20
	ds_read_b128 v[176:179], v147 offset:49152
	ds_read_b128 v[180:183], v147 offset:50176
	ds_read_b128 v[184:187], v147 offset:51200
	ds_read_b128 v[198:201], v147 offset:52224
	ds_read_b128 v[202:205], v147 offset:53248
	ds_read_b128 v[206:209], v147 offset:54272
	ds_read_b128 v[210:213], v147 offset:55296
	ds_read_b128 v[214:217], v147 offset:56320
	global_load_lds_dwordx4 v[218:219], off
	s_add_i32 m0, s20, 0x2000
	s_add_u32 s18, s18, 0x4080
	v_lshl_add_u64 v[218:219], v[220:221], 0, s[74:75]
	s_addc_u32 s19, s19, 0
	s_add_i32 s20, s48, s26
	global_load_lds_dwordx4 v[218:219], off
	v_lshl_add_u64 v[218:219], s[18:19], 0, v[132:133]
	s_mov_b32 m0, s20
	s_nop 0
	global_load_lds_dwordx4 v[218:219], off
	v_lshl_add_u64 v[218:219], s[18:19], 0, v[128:129]
	s_add_i32 m0, s20, 0x2000
	s_nop 0
	global_load_lds_dwordx4 v[218:219], off
	v_lshl_add_u64 v[218:219], v[222:223], 0, s[74:75]
	s_mov_b32 m0, s37
	s_nop 0
	global_load_lds_dwordx4 v[218:219], off
	v_lshl_add_u64 v[218:219], v[228:229], 0, s[74:75]
	s_mov_b32 m0, s38
	s_nop 0
	global_load_lds_dwordx4 v[218:219], off
	s_waitcnt vmcnt(8)
	s_waitcnt lgkmcnt(0)
	s_barrier
	s_waitcnt lgkmcnt(0)
	v_mfma_f32_16x16x32_bf16 v[60:63], v[140:143], v[176:179], v[60:63]
	v_mfma_f32_16x16x32_bf16 v[56:59], v[152:155], v[176:179], v[56:59]
	v_mfma_f32_16x16x32_bf16 v[44:47], v[140:143], v[184:187], v[44:47]
	v_mfma_f32_16x16x32_bf16 v[40:43], v[152:155], v[184:187], v[40:43]
	v_mfma_f32_16x16x32_bf16 v[28:31], v[140:143], v[202:205], v[28:31]
	v_mfma_f32_16x16x32_bf16 v[24:27], v[152:155], v[202:205], v[24:27]
	v_mfma_f32_16x16x32_bf16 v[12:15], v[140:143], v[210:213], v[12:15]
	v_mfma_f32_16x16x32_bf16 v[8:11], v[152:155], v[210:213], v[8:11]
	v_mfma_f32_16x16x32_bf16 v[60:63], v[148:151], v[180:183], v[60:63]
	v_mfma_f32_16x16x32_bf16 v[56:59], v[156:159], v[180:183], v[56:59]
	v_mfma_f32_16x16x32_bf16 v[44:47], v[148:151], v[198:201], v[44:47]
	v_mfma_f32_16x16x32_bf16 v[40:43], v[156:159], v[198:201], v[40:43]
	v_mfma_f32_16x16x32_bf16 v[28:31], v[148:151], v[206:209], v[28:31]
	v_mfma_f32_16x16x32_bf16 v[24:27], v[156:159], v[206:209], v[24:27]
	v_mfma_f32_16x16x32_bf16 v[12:15], v[148:151], v[214:217], v[12:15]
	v_mfma_f32_16x16x32_bf16 v[8:11], v[156:159], v[214:217], v[8:11]
	v_mfma_f32_16x16x32_bf16 v[52:55], v[160:163], v[176:179], v[52:55]
	v_mfma_f32_16x16x32_bf16 v[48:51], v[168:171], v[176:179], v[48:51]
	v_mfma_f32_16x16x32_bf16 v[36:39], v[160:163], v[184:187], v[36:39]
	v_mfma_f32_16x16x32_bf16 v[32:35], v[168:171], v[184:187], v[32:35]
	v_mfma_f32_16x16x32_bf16 v[20:23], v[160:163], v[202:205], v[20:23]
	v_mfma_f32_16x16x32_bf16 v[16:19], v[168:171], v[202:205], v[16:19]
	v_mfma_f32_16x16x32_bf16 v[4:7], v[160:163], v[210:213], v[4:7]
	v_mfma_f32_16x16x32_bf16 v[0:3], v[168:171], v[210:213], v[0:3]
	v_mfma_f32_16x16x32_bf16 v[52:55], v[164:167], v[180:183], v[52:55]
	v_mfma_f32_16x16x32_bf16 v[48:51], v[172:175], v[180:183], v[48:51]
	v_mfma_f32_16x16x32_bf16 v[36:39], v[164:167], v[198:201], v[36:39]
	v_mfma_f32_16x16x32_bf16 v[32:35], v[172:175], v[198:201], v[32:35]
	v_mfma_f32_16x16x32_bf16 v[20:23], v[164:167], v[206:209], v[20:23]
	v_mfma_f32_16x16x32_bf16 v[16:19], v[172:175], v[206:209], v[16:19]
	v_mfma_f32_16x16x32_bf16 v[4:7], v[164:167], v[214:217], v[4:7]
	v_mfma_f32_16x16x32_bf16 v[0:3], v[172:175], v[214:217], v[0:3]
	s_barrier
	s_add_i32 s46, s46, 2
	s_add_u32 s2, s2, 0x100
	s_addc_u32 s3, s3, 0
	s_add_u32 s43, s43, 0x100
	s_addc_u32 s45, s45, 0
	s_cmp_gt_u32 s46, 13
	s_cbranch_scc0 .LBB0_344
	s_and_b64 vcc, exec, s[8:9]
	s_cbranch_vccz .LBB0_347
	s_barrier

; #define PG8_STAGE(bufoff, gbase, voff) do { _Pragma("unroll") for (int _i = 0; _i < 2; ++_i) \
;         __builtin_amdgcn_global_load_lds((const unsigned*)((const char*)(gbase) + (voff)[_i]), (LAS unsigned*)(lds + (bufoff) + ldsw + _i * 8192), 16, 0, 0); } while (0)
; #define PG8_LDA(dst, b, h) do { _Pragma("unroll") for (int m = 0; m < 4; ++m) _Pragma("unroll") for (int k = 0; k < 2; ++k) dst[m][k] = *(const LAS bf16x8*)(lds + PG8_SA(b, h) + aoff + m * 2048 + k * 1024); } while (0)
; #define PG8_LDB(dst, b, h) do { _Pragma("unroll") for (int n = 0; n < 2; ++n) _Pragma("unroll") for (int k = 0; k < 2; ++k) dst[n][k] = *(const LAS bf16x8*)(lds + PG8_SB(b, h) + boff + n * 2048 + k * 1024); } while (0)
; #define PG8_MMA(ai, bj, At, Bt) do { __builtin_amdgcn_s_setprio(1); _Pragma("unroll") for (int m = 0; m < 4; ++m) _Pragma("unroll") for (int n = 0; n < 2; ++n) _Pragma("unroll") for (int k = 0; k < 2; ++k) \
;         acc[ai][bj][m][n] = __builtin_amdgcn_mfma_f32_16x16x32_bf16(Bt[n][k], At[m][k], acc[ai][bj][m][n], 0, 0, 0); __builtin_amdgcn_s_setprio(0); } while (0)
; #define PG8_WAIT_V(n) asm volatile("s_waitcnt vmcnt(" #n ")" ::: "memory")
; #define PG8_WAIT_L(n) asm volatile("s_waitcnt lgkmcnt(" #n ")" ::: "memory")
; #define PG8_BAR __builtin_amdgcn_s_barrier()
; #define PG8_SCHED __builtin_amdgcn_sched_barrier(0)
; template <class Epi, class Sched>
; __device__ __forceinline__ void gemm_phase(int wv, LAS unsigned char* lds, const Gemm g, const Sched& S, const Epi& E) {
;     ...
;             const bool last = (t == nt - 2);
;             const char* a1 = cA + (size_t)(t + 1) * kstep;
;             const char* a2 = last ? nA : cA + (size_t)(t + 2) * kstep; const char* b2 = last ? nB : cB + (size_t)(t + 2) * kstep;
;             const char* a3 = a2 + kstep; const char* b3 = b2 + kstep;
;             PG8_LDB(B0, 0, 0); PG8_LDB(B1, 0, 1); PG8_SCHED; PG8_LDA(At, 0, 0); PG8_STAGE(PG8_SA(1, 1), a1 + hstep, voffA);
;             PG8_WAIT_V(8); PG8_WAIT_L(0); PG8_BAR; PG8_MMA(0, 0, At, B0); PG8_MMA(0, 1, At, B1); PG8_BAR; PG8_SCHED;
;             PG8_LDA(At, 0, 1); PG8_STAGE(PG8_SB(0, 0), b2, voffB); PG8_STAGE(PG8_SB(0, 1), b2 + hstepB, voffB); PG8_STAGE(PG8_SA(0, 0), a2, voffA);
;             PG8_WAIT_V(8); PG8_WAIT_L(0); PG8_BAR; PG8_MMA(1, 0, At, B0); PG8_MMA(1, 1, At, B1); PG8_BAR; PG8_SCHED;
.LBB0_542:
	s_add_u32 s28, s4, 0xfffc0080
	s_addc_u32 s29, s5, -1
	s_add_i32 s55, 0, 0x10000
	s_cmp_eq_u32 s54, 12
	s_cselect_b32 s31, s21, s29
	s_cselect_b32 s30, s50, s28
	s_cselect_b32 s29, s23, s53
	s_cselect_b32 s28, s51, s52
	s_add_i32 s58, 0, 0x14000
	v_add_u32_e32 v60, s55, v206
	s_waitcnt vmcnt(0)
	v_add_u32_e32 v92, s58, v206
	ds_read_b128 v[48:51], v60
	ds_read_b128 v[52:55], v60 offset:1024
	ds_read_b128 v[56:59], v60 offset:2048
	ds_read_b128 v[60:63], v60 offset:3072
	ds_read_b128 v[64:67], v92
	ds_read_b128 v[68:71], v92 offset:1024
	ds_read_b128 v[88:91], v92 offset:2048
	ds_read_b128 v[92:95], v92 offset:3072
	v_lshl_add_u64 v[222:223], s[4:5], 0, v[174:175]
	s_add_i32 m0, s41, 0xc000
	ds_read_b128 v[180:183], v209
	ds_read_b128 v[184:187], v209 offset:1024
	ds_read_b128 v[198:201], v209 offset:2048
	ds_read_b128 v[202:205], v209 offset:3072
	ds_read_b128 v[210:213], v209 offset:4096
	ds_read_b128 v[214:217], v209 offset:5120
	ds_read_b128 v[218:221], v209 offset:6144
	ds_read_b128 v[228:231], v209 offset:7168
	global_load_lds_dwordx4 v[222:223], off
	v_lshl_add_u64 v[222:223], s[4:5], 0, v[176:177]
	s_add_i32 m0, s41, 0xe000
	s_nop 0
	global_load_lds_dwordx4 v[222:223], off
	s_waitcnt vmcnt(8)
	s_waitcnt lgkmcnt(0)
	s_barrier
	s_waitcnt lgkmcnt(0)
	v_mfma_f32_16x16x32_bf16 v[156:159], v[48:51], v[180:183], v[156:159]
	v_mfma_f32_16x16x32_bf16 v[152:155], v[56:59], v[180:183], v[152:155]
	v_mfma_f32_16x16x32_bf16 v[140:143], v[48:51], v[198:201], v[140:143]
	v_mfma_f32_16x16x32_bf16 v[136:139], v[56:59], v[198:201], v[136:139]
	v_mfma_f32_16x16x32_bf16 v[124:127], v[48:51], v[210:213], v[124:127]
	v_mfma_f32_16x16x32_bf16 v[120:123], v[56:59], v[210:213], v[120:123]
	v_mfma_f32_16x16x32_bf16 v[108:111], v[48:51], v[218:221], v[108:111]
	v_mfma_f32_16x16x32_bf16 v[104:107], v[56:59], v[218:221], v[104:107]
	v_mfma_f32_16x16x32_bf16 v[156:159], v[52:55], v[184:187], v[156:159]
	v_mfma_f32_16x16x32_bf16 v[152:155], v[60:63], v[184:187], v[152:155]
	v_mfma_f32_16x16x32_bf16 v[140:143], v[52:55], v[202:205], v[140:143]
	v_mfma_f32_16x16x32_bf16 v[136:139], v[60:63], v[202:205], v[136:139]
	v_mfma_f32_16x16x32_bf16 v[124:127], v[52:55], v[214:217], v[124:127]
	v_mfma_f32_16x16x32_bf16 v[120:123], v[60:63], v[214:217], v[120:123]
	v_mfma_f32_16x16x32_bf16 v[108:111], v[52:55], v[228:231], v[108:111]
	v_mfma_f32_16x16x32_bf16 v[104:107], v[60:63], v[228:231], v[104:107]
	v_mfma_f32_16x16x32_bf16 v[148:151], v[64:67], v[180:183], v[148:151]
	v_mfma_f32_16x16x32_bf16 v[144:147], v[88:91], v[180:183], v[144:147]
	v_mfma_f32_16x16x32_bf16 v[132:135], v[64:67], v[198:201], v[132:135]
	v_mfma_f32_16x16x32_bf16 v[128:131], v[88:91], v[198:201], v[128:131]
	v_mfma_f32_16x16x32_bf16 v[116:119], v[64:67], v[210:213], v[116:119]
	v_mfma_f32_16x16x32_bf16 v[112:115], v[88:91], v[210:213], v[112:115]
	v_mfma_f32_16x16x32_bf16 v[100:103], v[64:67], v[218:221], v[100:103]
	v_mfma_f32_16x16x32_bf16 v[96:99], v[88:91], v[218:221], v[96:99]
	v_mfma_f32_16x16x32_bf16 v[148:151], v[68:71], v[184:187], v[148:151]
	v_mfma_f32_16x16x32_bf16 v[144:147], v[92:95], v[184:187], v[144:147]
	v_mfma_f32_16x16x32_bf16 v[132:135], v[68:71], v[202:205], v[132:135]
	v_mfma_f32_16x16x32_bf16 v[128:131], v[92:95], v[202:205], v[128:131]
	v_mfma_f32_16x16x32_bf16 v[116:119], v[68:71], v[214:217], v[116:119]
	v_mfma_f32_16x16x32_bf16 v[112:115], v[92:95], v[214:217], v[112:115]
	v_mfma_f32_16x16x32_bf16 v[100:103], v[68:71], v[228:231], v[100:103]
	v_mfma_f32_16x16x32_bf16 v[96:99], v[92:95], v[228:231], v[96:99]
	s_barrier
	s_add_i32 s55, s55, s40
	v_lshl_add_u64 v[222:223], s[28:29], 0, v[164:165]
	s_mov_b32 m0, s55
	ds_read_b128 v[180:183], v209 offset:16384
	ds_read_b128 v[184:187], v209 offset:17408
	ds_read_b128 v[198:201], v209 offset:18432
	ds_read_b128 v[202:205], v209 offset:19456
	ds_read_b128 v[210:213], v209 offset:20480
	ds_read_b128 v[214:217], v209 offset:21504
	ds_read_b128 v[218:221], v209 offset:22528
	ds_read_b128 v[228:231], v209 offset:23552
	global_load_lds_dwordx4 v[222:223], off
	s_add_i32 m0, s55, 0x2000
	s_add_u32 s56, s28, 0x20000
	v_lshl_add_u64 v[240:241], s[28:29], 0, v[160:161]
	s_addc_u32 s57, s29, 0
	s_add_i32 s55, s58, s40
	global_load_lds_dwordx4 v[240:241], off
	v_lshl_add_u64 v[232:233], s[56:57], 0, v[164:165]
	s_mov_b32 m0, s55
	v_lshl_add_u64 v[242:243], s[30:31], 0, v[166:167]
	global_load_lds_dwordx4 v[232:233], off
	v_lshl_add_u64 v[232:233], s[56:57], 0, v[160:161]
	s_add_i32 m0, s55, 0x2000
	v_lshl_add_u64 v[244:245], s[30:31], 0, v[162:163]
	global_load_lds_dwordx4 v[232:233], off
	s_mov_b32 m0, s41
	s_nop 0
	global_load_lds_dwordx4 v[242:243], off
	s_mov_b32 m0, s42
	s_nop 0
	global_load_lds_dwordx4 v[244:245], off
	s_waitcnt vmcnt(8)
	s_waitcnt lgkmcnt(0)
	s_barrier
; #define PG8_STAGE(bufoff, gbase, voff) do { _Pragma("unroll") for (int _i = 0; _i < 2; ++_i) \
;         __builtin_amdgcn_global_load_lds((const unsigned*)((const char*)(gbase) + (voff)[_i]), (LAS unsigned*)(lds + (bufoff) + ldsw + _i * 8192), 16, 0, 0); } while (0)
; #define PG8_LDA(dst, b, h) do { _Pragma("unroll") for (int m = 0; m < 4; ++m) _Pragma("unroll") for (int k = 0; k < 2; ++k) dst[m][k] = *(const LAS bf16x8*)(lds + PG8_SA(b, h) + aoff + m * 2048 + k * 1024); } while (0)
; #define PG8_LDB(dst, b, h) do { _Pragma("unroll") for (int n = 0; n < 2; ++n) _Pragma("unroll") for (int k = 0; k < 2; ++k) dst[n][k] = *(const LAS bf16x8*)(lds + PG8_SB(b, h) + boff + n * 2048 + k * 1024); } while (0)
; #define PG8_MMA(ai, bj, At, Bt) do { __builtin_amdgcn_s_setprio(1); _Pragma("unroll") for (int m = 0; m < 4; ++m) _Pragma("unroll") for (int n = 0; n < 2; ++n) _Pragma("unroll") for (int k = 0; k < 2; ++k) \
;         acc[ai][bj][m][n] = __builtin_amdgcn_mfma_f32_16x16x32_bf16(Bt[n][k], At[m][k], acc[ai][bj][m][n], 0, 0, 0); __builtin_amdgcn_s_setprio(0); } while (0)
; #define PG8_WAIT_V(n) asm volatile("s_waitcnt vmcnt(" #n ")" ::: "memory")
; #define PG8_WAIT_L(n) asm volatile("s_waitcnt lgkmcnt(" #n ")" ::: "memory")
; #define PG8_BAR __builtin_amdgcn_s_barrier()
; #define PG8_SCHED __builtin_amdgcn_sched_barrier(0)
; template <class Epi, class Sched>
; __device__ __forceinline__ void gemm_phase(int wv, LAS unsigned char* lds, const Gemm g, const Sched& S, const Epi& E) {
;     ...
;             PG8_WAIT_V(8); PG8_WAIT_L(0); PG8_BAR; PG8_MMA(1, 0, At, B0); PG8_MMA(1, 1, At, B1); PG8_BAR; PG8_SCHED;
;             PG8_LDB(B0, 1, 0); PG8_LDB(B1, 1, 1); PG8_SCHED; PG8_LDA(At, 1, 0); PG8_STAGE(PG8_SA(0, 1), a2 + hstep, voffA);
;             PG8_WAIT_V(8); PG8_WAIT_L(0); PG8_BAR; PG8_MMA(0, 0, At, B0); PG8_MMA(0, 1, At, B1); PG8_BAR; PG8_SCHED;
	s_waitcnt lgkmcnt(0)
	v_mfma_f32_16x16x32_bf16 v[84:87], v[48:51], v[180:183], v[84:87]
	v_mfma_f32_16x16x32_bf16 v[80:83], v[56:59], v[180:183], v[80:83]
	v_mfma_f32_16x16x32_bf16 v[44:47], v[48:51], v[198:201], v[44:47]
	v_mfma_f32_16x16x32_bf16 v[40:43], v[56:59], v[198:201], v[40:43]
	v_mfma_f32_16x16x32_bf16 v[28:31], v[48:51], v[210:213], v[28:31]
	v_mfma_f32_16x16x32_bf16 v[24:27], v[56:59], v[210:213], v[24:27]
	v_mfma_f32_16x16x32_bf16 v[12:15], v[48:51], v[218:221], v[12:15]
	v_mfma_f32_16x16x32_bf16 v[8:11], v[56:59], v[218:221], v[8:11]
	v_mfma_f32_16x16x32_bf16 v[84:87], v[52:55], v[184:187], v[84:87]
	v_mfma_f32_16x16x32_bf16 v[80:83], v[60:63], v[184:187], v[80:83]
	v_mfma_f32_16x16x32_bf16 v[44:47], v[52:55], v[202:205], v[44:47]
	v_mfma_f32_16x16x32_bf16 v[40:43], v[60:63], v[202:205], v[40:43]
	v_mfma_f32_16x16x32_bf16 v[28:31], v[52:55], v[214:217], v[28:31]
	v_mfma_f32_16x16x32_bf16 v[24:27], v[60:63], v[214:217], v[24:27]
	v_mfma_f32_16x16x32_bf16 v[12:15], v[52:55], v[228:231], v[12:15]
	v_mfma_f32_16x16x32_bf16 v[8:11], v[60:63], v[228:231], v[8:11]
	v_mfma_f32_16x16x32_bf16 v[36:39], v[64:67], v[198:201], v[36:39]
	v_mfma_f32_16x16x32_bf16 v[32:35], v[88:91], v[198:201], v[32:35]
	v_mfma_f32_16x16x32_bf16 v[20:23], v[64:67], v[210:213], v[20:23]
	v_mfma_f32_16x16x32_bf16 v[16:19], v[88:91], v[210:213], v[16:19]
	v_mfma_f32_16x16x32_bf16 v[4:7], v[64:67], v[218:221], v[4:7]
	v_mfma_f32_16x16x32_bf16 v[0:3], v[88:91], v[218:221], v[0:3]
	v_mfma_f32_16x16x32_bf16 v[48:51], v[64:67], v[180:183], v[76:79]
	v_mfma_f32_16x16x32_bf16 v[52:55], v[88:91], v[180:183], v[72:75]
	v_mfma_f32_16x16x32_bf16 v[36:39], v[68:71], v[202:205], v[36:39]
	v_mfma_f32_16x16x32_bf16 v[32:35], v[92:95], v[202:205], v[32:35]
	v_mfma_f32_16x16x32_bf16 v[20:23], v[68:71], v[214:217], v[20:23]
	v_mfma_f32_16x16x32_bf16 v[16:19], v[92:95], v[214:217], v[16:19]
	v_mfma_f32_16x16x32_bf16 v[4:7], v[68:71], v[228:231], v[4:7]
	v_mfma_f32_16x16x32_bf16 v[0:3], v[92:95], v[228:231], v[0:3]
	v_mfma_f32_16x16x32_bf16 v[48:51], v[68:71], v[184:187], v[48:51]
	v_mfma_f32_16x16x32_bf16 v[52:55], v[92:95], v[184:187], v[52:55]
	s_barrier
	s_add_i32 s55, 0, 0x1c000
	v_add_u32_e32 v68, s95, v206
	v_add_u32_e32 v72, s55, v206
	ds_read_b128 v[56:59], v68
	ds_read_b128 v[60:63], v68 offset:1024
	ds_read_b128 v[64:67], v68 offset:2048
	ds_read_b128 v[68:71], v68 offset:3072
	ds_read_b128 v[88:91], v72
	ds_read_b128 v[92:95], v72 offset:1024
	ds_read_b128 v[180:183], v72 offset:2048
	ds_read_b128 v[184:187], v72 offset:3072
	s_add_u32 s30, s30, 0x40000
	s_addc_u32 s31, s31, 0
	s_mov_b32 m0, s43
	v_lshl_add_u64 v[232:233], s[30:31], 0, v[166:167]
	ds_read_b128 v[72:75], v209 offset:32768
	ds_read_b128 v[76:79], v209 offset:33792
	ds_read_b128 v[198:201], v209 offset:34816
	ds_read_b128 v[202:205], v209 offset:35840
	ds_read_b128 v[210:213], v209 offset:36864
	ds_read_b128 v[214:217], v209 offset:37888
	ds_read_b128 v[218:221], v209 offset:38912
	ds_read_b128 v[228:231], v209 offset:39936
	global_load_lds_dwordx4 v[232:233], off
	v_lshl_add_u64 v[232:233], s[30:31], 0, v[162:163]
	s_mov_b32 m0, s45
	s_nop 0
	global_load_lds_dwordx4 v[232:233], off
	s_waitcnt vmcnt(8)
	s_waitcnt lgkmcnt(0)
	s_barrier
	s_waitcnt lgkmcnt(0)
	v_mfma_f32_16x16x32_bf16 v[156:159], v[56:59], v[72:75], v[156:159]
	v_mfma_f32_16x16x32_bf16 v[152:155], v[64:67], v[72:75], v[152:155]
	v_mfma_f32_16x16x32_bf16 v[140:143], v[56:59], v[198:201], v[140:143]
	v_mfma_f32_16x16x32_bf16 v[136:139], v[64:67], v[198:201], v[136:139]
	v_mfma_f32_16x16x32_bf16 v[124:127], v[56:59], v[210:213], v[124:127]
	v_mfma_f32_16x16x32_bf16 v[120:123], v[64:67], v[210:213], v[120:123]
	v_mfma_f32_16x16x32_bf16 v[108:111], v[56:59], v[218:221], v[108:111]
	v_mfma_f32_16x16x32_bf16 v[104:107], v[64:67], v[218:221], v[104:107]
	v_mfma_f32_16x16x32_bf16 v[156:159], v[60:63], v[76:79], v[156:159]
	v_mfma_f32_16x16x32_bf16 v[152:155], v[68:71], v[76:79], v[152:155]
	v_mfma_f32_16x16x32_bf16 v[140:143], v[60:63], v[202:205], v[140:143]
	v_mfma_f32_16x16x32_bf16 v[136:139], v[68:71], v[202:205], v[136:139]
	v_mfma_f32_16x16x32_bf16 v[124:127], v[60:63], v[214:217], v[124:127]
	v_mfma_f32_16x16x32_bf16 v[120:123], v[68:71], v[214:217], v[120:123]
	v_mfma_f32_16x16x32_bf16 v[108:111], v[60:63], v[228:231], v[108:111]
	v_mfma_f32_16x16x32_bf16 v[104:107], v[68:71], v[228:231], v[104:107]
	v_mfma_f32_16x16x32_bf16 v[148:151], v[88:91], v[72:75], v[148:151]
	v_mfma_f32_16x16x32_bf16 v[72:75], v[180:183], v[72:75], v[144:147]
	v_mfma_f32_16x16x32_bf16 v[144:147], v[184:187], v[76:79], v[72:75]
	v_mfma_f32_16x16x32_bf16 v[72:75], v[88:91], v[198:201], v[132:135]
	v_mfma_f32_16x16x32_bf16 v[132:135], v[92:95], v[202:205], v[72:75]
	v_mfma_f32_16x16x32_bf16 v[72:75], v[180:183], v[198:201], v[128:131]
	v_mfma_f32_16x16x32_bf16 v[128:131], v[184:187], v[202:205], v[72:75]
	v_mfma_f32_16x16x32_bf16 v[72:75], v[88:91], v[210:213], v[116:119]
	v_mfma_f32_16x16x32_bf16 v[116:119], v[92:95], v[214:217], v[72:75]
	v_mfma_f32_16x16x32_bf16 v[72:75], v[180:183], v[210:213], v[112:115]
	v_mfma_f32_16x16x32_bf16 v[112:115], v[184:187], v[214:217], v[72:75]
	v_mfma_f32_16x16x32_bf16 v[72:75], v[88:91], v[218:221], v[100:103]
	v_mfma_f32_16x16x32_bf16 v[100:103], v[92:95], v[228:231], v[72:75]
	v_mfma_f32_16x16x32_bf16 v[72:75], v[180:183], v[218:221], v[96:99]
	v_mfma_f32_16x16x32_bf16 v[148:151], v[92:95], v[76:79], v[148:151]
	v_mfma_f32_16x16x32_bf16 v[96:99], v[184:187], v[228:231], v[72:75]
	s_barrier
; #define PG8_STAGE(bufoff, gbase, voff) do { _Pragma("unroll") for (int _i = 0; _i < 2; ++_i) \
;         __builtin_amdgcn_global_load_lds((const unsigned*)((const char*)(gbase) + (voff)[_i]), (LAS unsigned*)(lds + (bufoff) + ldsw + _i * 8192), 16, 0, 0); } while (0)
; #define PG8_LDA(dst, b, h) do { _Pragma("unroll") for (int m = 0; m < 4; ++m) _Pragma("unroll") for (int k = 0; k < 2; ++k) dst[m][k] = *(const LAS bf16x8*)(lds + PG8_SA(b, h) + aoff + m * 2048 + k * 1024); } while (0)
; #define PG8_MMA(ai, bj, At, Bt) do { __builtin_amdgcn_s_setprio(1); _Pragma("unroll") for (int m = 0; m < 4; ++m) _Pragma("unroll") for (int n = 0; n < 2; ++n) _Pragma("unroll") for (int k = 0; k < 2; ++k) \
;         acc[ai][bj][m][n] = __builtin_amdgcn_mfma_f32_16x16x32_bf16(Bt[n][k], At[m][k], acc[ai][bj][m][n], 0, 0, 0); __builtin_amdgcn_s_setprio(0); } while (0)
; #define PG8_WAIT_V(n) asm volatile("s_waitcnt vmcnt(" #n ")" ::: "memory")
; #define PG8_WAIT_L(n) asm volatile("s_waitcnt lgkmcnt(" #n ")" ::: "memory")
; #define PG8_BAR __builtin_amdgcn_s_barrier()
; #define PG8_SCHED __builtin_amdgcn_sched_barrier(0)
; template <class Epi, class Sched>
; __device__ __forceinline__ void gemm_phase(int wv, LAS unsigned char* lds, const Gemm g, const Sched& S, const Epi& E) {
;     ...
;             PG8_LDA(At, 1, 1); PG8_STAGE(PG8_SB(1, 0), b3, voffB); PG8_STAGE(PG8_SB(1, 1), b3 + hstepB, voffB); PG8_STAGE(PG8_SA(1, 0), a3, voffA);
;             PG8_WAIT_V(8); PG8_WAIT_L(0); PG8_BAR; PG8_MMA(1, 0, At, B0); PG8_MMA(1, 1, At, B1); PG8_BAR; PG8_SCHED;
;         }
;         if (wr == 0) PG8_BAR;
	s_add_i32 s30, s95, s40
	v_lshl_add_u64 v[76:77], v[222:223], 0, s[74:75]
	s_mov_b32 m0, s30
	s_nop 0
	ds_read_b128 v[72:75], v209 offset:49152
	ds_read_b128 v[198:201], v209 offset:50176
	ds_read_b128 v[202:205], v209 offset:51200
	ds_read_b128 v[210:213], v209 offset:52224
	ds_read_b128 v[214:217], v209 offset:53248
	ds_read_b128 v[218:221], v209 offset:54272
	ds_read_b128 v[228:231], v209 offset:55296
	ds_read_b128 v[232:235], v209 offset:56320
	global_load_lds_dwordx4 v[76:77], off
	s_add_i32 m0, s30, 0x2000
	s_add_u32 s28, s28, 0x20080
	v_lshl_add_u64 v[76:77], v[240:241], 0, s[74:75]
	s_addc_u32 s29, s29, 0
	s_add_i32 s30, s55, s40
	global_load_lds_dwordx4 v[76:77], off
	v_lshl_add_u64 v[76:77], s[28:29], 0, v[164:165]
	s_mov_b32 m0, s30
	s_nop 0
	global_load_lds_dwordx4 v[76:77], off
	v_lshl_add_u64 v[76:77], s[28:29], 0, v[160:161]
	s_add_i32 m0, s30, 0x2000
	s_nop 0
	global_load_lds_dwordx4 v[76:77], off
	v_lshl_add_u64 v[76:77], v[242:243], 0, s[74:75]
	s_mov_b32 m0, s48
	s_nop 0
	global_load_lds_dwordx4 v[76:77], off
	v_lshl_add_u64 v[76:77], v[244:245], 0, s[74:75]
	s_mov_b32 m0, s49
	s_nop 0
	global_load_lds_dwordx4 v[76:77], off
	s_waitcnt vmcnt(8)
	s_waitcnt lgkmcnt(0)
	s_barrier
	s_waitcnt lgkmcnt(0)
	v_mfma_f32_16x16x32_bf16 v[76:79], v[56:59], v[72:75], v[84:87]
	v_mfma_f32_16x16x32_bf16 v[84:87], v[60:63], v[198:201], v[76:79]
	v_mfma_f32_16x16x32_bf16 v[76:79], v[64:67], v[72:75], v[80:83]
	v_mfma_f32_16x16x32_bf16 v[44:47], v[56:59], v[202:205], v[44:47]
	v_mfma_f32_16x16x32_bf16 v[40:43], v[64:67], v[202:205], v[40:43]
	v_mfma_f32_16x16x32_bf16 v[28:31], v[56:59], v[214:217], v[28:31]
	v_mfma_f32_16x16x32_bf16 v[24:27], v[64:67], v[214:217], v[24:27]
	v_mfma_f32_16x16x32_bf16 v[12:15], v[56:59], v[228:231], v[12:15]
	v_mfma_f32_16x16x32_bf16 v[8:11], v[64:67], v[228:231], v[8:11]
	v_mfma_f32_16x16x32_bf16 v[80:83], v[68:71], v[198:201], v[76:79]
	v_mfma_f32_16x16x32_bf16 v[44:47], v[60:63], v[210:213], v[44:47]
	v_mfma_f32_16x16x32_bf16 v[40:43], v[68:71], v[210:213], v[40:43]
	v_mfma_f32_16x16x32_bf16 v[28:31], v[60:63], v[218:221], v[28:31]
	v_mfma_f32_16x16x32_bf16 v[24:27], v[68:71], v[218:221], v[24:27]
	v_mfma_f32_16x16x32_bf16 v[12:15], v[60:63], v[232:235], v[12:15]
	v_mfma_f32_16x16x32_bf16 v[8:11], v[68:71], v[232:235], v[8:11]
	v_mfma_f32_16x16x32_bf16 v[48:51], v[88:91], v[72:75], v[48:51]
	v_mfma_f32_16x16x32_bf16 v[76:79], v[92:95], v[198:201], v[48:51]
	v_mfma_f32_16x16x32_bf16 v[48:51], v[180:183], v[72:75], v[52:55]
	v_mfma_f32_16x16x32_bf16 v[36:39], v[88:91], v[202:205], v[36:39]
	v_mfma_f32_16x16x32_bf16 v[32:35], v[180:183], v[202:205], v[32:35]
	v_mfma_f32_16x16x32_bf16 v[20:23], v[88:91], v[214:217], v[20:23]
	v_mfma_f32_16x16x32_bf16 v[16:19], v[180:183], v[214:217], v[16:19]
	v_mfma_f32_16x16x32_bf16 v[4:7], v[88:91], v[228:231], v[4:7]
	v_mfma_f32_16x16x32_bf16 v[0:3], v[180:183], v[228:231], v[0:3]
	v_mfma_f32_16x16x32_bf16 v[72:75], v[184:187], v[198:201], v[48:51]
	v_mfma_f32_16x16x32_bf16 v[36:39], v[92:95], v[210:213], v[36:39]
	v_mfma_f32_16x16x32_bf16 v[32:35], v[184:187], v[210:213], v[32:35]
	v_mfma_f32_16x16x32_bf16 v[20:23], v[92:95], v[218:221], v[20:23]
	v_mfma_f32_16x16x32_bf16 v[16:19], v[184:187], v[218:221], v[16:19]
	v_mfma_f32_16x16x32_bf16 v[4:7], v[92:95], v[232:235], v[4:7]
	v_mfma_f32_16x16x32_bf16 v[0:3], v[184:187], v[232:235], v[0:3]
	s_barrier
	s_add_i32 s54, s54, 2
	s_add_u32 s4, s4, 0x100
	s_addc_u32 s5, s5, 0
	s_add_u32 s52, s52, 0x100
	s_addc_u32 s53, s53, 0
	s_cmp_gt_u32 s54, 13
	s_cbranch_scc0 .LBB0_542
	s_and_b64 vcc, exec, s[16:17]
	s_cbranch_vccz .LBB0_545
	s_barrier

; #define PG8_STAGE(bufoff, gbase, voff) do { _Pragma("unroll") for (int _i = 0; _i < 2; ++_i) \
;         __builtin_amdgcn_global_load_lds((const unsigned*)((const char*)(gbase) + (voff)[_i]), (LAS unsigned*)(lds + (bufoff) + ldsw + _i * 8192), 16, 0, 0); } while (0)
; #define PG8_LDA(dst, b, h) do { _Pragma("unroll") for (int m = 0; m < 4; ++m) _Pragma("unroll") for (int k = 0; k < 2; ++k) dst[m][k] = *(const LAS bf16x8*)(lds + PG8_SA(b, h) + aoff + m * 2048 + k * 1024); } while (0)
; #define PG8_LDB(dst, b, h) do { _Pragma("unroll") for (int n = 0; n < 2; ++n) _Pragma("unroll") for (int k = 0; k < 2; ++k) dst[n][k] = *(const LAS bf16x8*)(lds + PG8_SB(b, h) + boff + n * 2048 + k * 1024); } while (0)
; #define PG8_MMA(ai, bj, At, Bt) do { __builtin_amdgcn_s_setprio(1); _Pragma("unroll") for (int m = 0; m < 4; ++m) _Pragma("unroll") for (int n = 0; n < 2; ++n) _Pragma("unroll") for (int k = 0; k < 2; ++k) \
;         acc[ai][bj][m][n] = __builtin_amdgcn_mfma_f32_16x16x32_bf16(Bt[n][k], At[m][k], acc[ai][bj][m][n], 0, 0, 0); __builtin_amdgcn_s_setprio(0); } while (0)
; #define PG8_WAIT_V(n) asm volatile("s_waitcnt vmcnt(" #n ")" ::: "memory")
; #define PG8_WAIT_L(n) asm volatile("s_waitcnt lgkmcnt(" #n ")" ::: "memory")
; #define PG8_BAR __builtin_amdgcn_s_barrier()
; #define PG8_SCHED __builtin_amdgcn_sched_barrier(0)
; template <class Epi, class Sched>
; __device__ __forceinline__ void gemm_phase(int wv, LAS unsigned char* lds, const Gemm g, const Sched& S, const Epi& E) {
;     ...
;             const bool last = (t == nt - 2);
;             const char* a1 = cA + (size_t)(t + 1) * kstep;
;             const char* a2 = last ? nA : cA + (size_t)(t + 2) * kstep; const char* b2 = last ? nB : cB + (size_t)(t + 2) * kstep;
;             const char* a3 = a2 + kstep; const char* b3 = b2 + kstep;
;             PG8_LDB(B0, 0, 0); PG8_LDB(B1, 0, 1); PG8_SCHED; PG8_LDA(At, 0, 0); PG8_STAGE(PG8_SA(1, 1), a1 + hstep, voffA);
;             PG8_WAIT_V(8); PG8_WAIT_L(0); PG8_BAR; PG8_MMA(0, 0, At, B0); PG8_MMA(0, 1, At, B1); PG8_BAR; PG8_SCHED;
;             PG8_LDA(At, 0, 1); PG8_STAGE(PG8_SB(0, 0), b2, voffB); PG8_STAGE(PG8_SB(0, 1), b2 + hstepB, voffB); PG8_STAGE(PG8_SA(0, 0), a2, voffA);
;             PG8_WAIT_V(8); PG8_WAIT_L(0); PG8_BAR; PG8_MMA(1, 0, At, B0); PG8_MMA(1, 1, At, B1); PG8_BAR; PG8_SCHED;
.LBB0_781:
	s_add_u32 s22, s20, 0xfffc0080
	s_addc_u32 s23, s21, -1
	s_add_i32 s44, 0, 0x10000
	s_cmp_eq_u32 s43, 12
	s_cselect_b32 s25, s13, s23
	s_cselect_b32 s24, s39, s22
	s_cselect_b32 s23, s15, s42
	s_cselect_b32 s22, s40, s41
	s_add_i32 s46, 0, 0x14000
	v_add_u32_e32 v154, s44, v139
	v_add_u32_e32 v170, s46, v139
	ds_read_b128 v[142:145], v154
	ds_read_b128 v[146:149], v154 offset:1024
	ds_read_b128 v[150:153], v154 offset:2048
	ds_read_b128 v[154:157], v154 offset:3072
	ds_read_b128 v[158:161], v170
	ds_read_b128 v[162:165], v170 offset:1024
	ds_read_b128 v[166:169], v170 offset:2048
	ds_read_b128 v[170:173], v170 offset:3072
	v_lshl_add_u64 v[186:187], s[20:21], 0, v[134:135]
	s_add_i32 m0, s29, 0xc000
	ds_read_b128 v[174:177], v141
	ds_read_b128 v[178:181], v141 offset:1024
	ds_read_b128 v[182:185], v141 offset:2048
	ds_read_b128 v[198:201], v141 offset:3072
	ds_read_b128 v[202:205], v141 offset:4096
	ds_read_b128 v[206:209], v141 offset:5120
	ds_read_b128 v[210:213], v141 offset:6144
	ds_read_b128 v[214:217], v141 offset:7168
	global_load_lds_dwordx4 v[186:187], off
	v_lshl_add_u64 v[186:187], s[20:21], 0, v[136:137]
	s_add_i32 m0, s29, 0xe000
	s_nop 0
	global_load_lds_dwordx4 v[186:187], off
	s_waitcnt vmcnt(8)
	s_waitcnt lgkmcnt(0)
	s_barrier
	s_waitcnt lgkmcnt(0)
	v_mfma_f32_16x16x32_bf16 v[124:127], v[142:145], v[174:177], v[124:127]
	v_mfma_f32_16x16x32_bf16 v[120:123], v[150:153], v[174:177], v[120:123]
	v_mfma_f32_16x16x32_bf16 v[116:119], v[142:145], v[182:185], v[116:119]
	v_mfma_f32_16x16x32_bf16 v[108:111], v[150:153], v[182:185], v[108:111]
	v_mfma_f32_16x16x32_bf16 v[100:103], v[142:145], v[202:205], v[100:103]
	v_mfma_f32_16x16x32_bf16 v[96:99], v[150:153], v[202:205], v[96:99]
	v_mfma_f32_16x16x32_bf16 v[84:87], v[142:145], v[210:213], v[84:87]
	v_mfma_f32_16x16x32_bf16 v[80:83], v[150:153], v[210:213], v[80:83]
	v_mfma_f32_16x16x32_bf16 v[124:127], v[146:149], v[178:181], v[124:127]
	v_mfma_f32_16x16x32_bf16 v[120:123], v[154:157], v[178:181], v[120:123]
	v_mfma_f32_16x16x32_bf16 v[116:119], v[146:149], v[198:201], v[116:119]
	v_mfma_f32_16x16x32_bf16 v[108:111], v[154:157], v[198:201], v[108:111]
	v_mfma_f32_16x16x32_bf16 v[100:103], v[146:149], v[206:209], v[100:103]
	v_mfma_f32_16x16x32_bf16 v[96:99], v[154:157], v[206:209], v[96:99]
	v_mfma_f32_16x16x32_bf16 v[84:87], v[146:149], v[214:217], v[84:87]
	v_mfma_f32_16x16x32_bf16 v[80:83], v[154:157], v[214:217], v[80:83]
	v_mfma_f32_16x16x32_bf16 v[112:115], v[158:161], v[174:177], v[112:115]
	v_mfma_f32_16x16x32_bf16 v[104:107], v[166:169], v[174:177], v[104:107]
	v_mfma_f32_16x16x32_bf16 v[92:95], v[158:161], v[182:185], v[92:95]
	v_mfma_f32_16x16x32_bf16 v[88:91], v[166:169], v[182:185], v[88:91]
	v_mfma_f32_16x16x32_bf16 v[76:79], v[158:161], v[202:205], v[76:79]
	v_mfma_f32_16x16x32_bf16 v[72:75], v[166:169], v[202:205], v[72:75]
	v_mfma_f32_16x16x32_bf16 v[68:71], v[158:161], v[210:213], v[68:71]
	v_mfma_f32_16x16x32_bf16 v[64:67], v[166:169], v[210:213], v[64:67]
	v_mfma_f32_16x16x32_bf16 v[112:115], v[162:165], v[178:181], v[112:115]
	v_mfma_f32_16x16x32_bf16 v[104:107], v[170:173], v[178:181], v[104:107]
	v_mfma_f32_16x16x32_bf16 v[92:95], v[162:165], v[198:201], v[92:95]
	v_mfma_f32_16x16x32_bf16 v[88:91], v[170:173], v[198:201], v[88:91]
	v_mfma_f32_16x16x32_bf16 v[76:79], v[162:165], v[206:209], v[76:79]
	v_mfma_f32_16x16x32_bf16 v[72:75], v[170:173], v[206:209], v[72:75]
	v_mfma_f32_16x16x32_bf16 v[68:71], v[162:165], v[214:217], v[68:71]
	v_mfma_f32_16x16x32_bf16 v[64:67], v[170:173], v[214:217], v[64:67]
	s_barrier
	s_add_i32 s44, s44, s28
	v_lshl_add_u64 v[186:187], s[22:23], 0, v[188:189]
	s_mov_b32 m0, s44
	ds_read_b128 v[174:177], v141 offset:16384
	ds_read_b128 v[178:181], v141 offset:17408
	ds_read_b128 v[182:185], v141 offset:18432
	ds_read_b128 v[198:201], v141 offset:19456
	ds_read_b128 v[202:205], v141 offset:20480
	ds_read_b128 v[206:209], v141 offset:21504
	ds_read_b128 v[210:213], v141 offset:22528
	ds_read_b128 v[214:217], v141 offset:23552
	global_load_lds_dwordx4 v[186:187], off
	s_add_i32 m0, s44, 0x2000
	s_add_u32 s44, s22, 0x4000
	v_lshl_add_u64 v[218:219], s[22:23], 0, v[128:129]
	s_addc_u32 s45, s23, 0
	s_add_i32 s46, s46, s28
	global_load_lds_dwordx4 v[218:219], off
	v_lshl_add_u64 v[220:221], s[44:45], 0, v[188:189]
	s_mov_b32 m0, s46
	v_lshl_add_u64 v[222:223], s[24:25], 0, v[130:131]
	global_load_lds_dwordx4 v[220:221], off
	v_lshl_add_u64 v[220:221], s[44:45], 0, v[128:129]
	s_add_i32 m0, s46, 0x2000
	s_nop 0
	global_load_lds_dwordx4 v[220:221], off
	v_lshl_add_u64 v[220:221], s[24:25], 0, v[132:133]
	s_mov_b32 m0, s29
	s_nop 0
	global_load_lds_dwordx4 v[220:221], off
	s_mov_b32 m0, s30
	s_nop 0
	global_load_lds_dwordx4 v[222:223], off
	s_waitcnt vmcnt(8)
	s_waitcnt lgkmcnt(0)
	s_barrier
; #define PG8_STAGE(bufoff, gbase, voff) do { _Pragma("unroll") for (int _i = 0; _i < 2; ++_i) \
;         __builtin_amdgcn_global_load_lds((const unsigned*)((const char*)(gbase) + (voff)[_i]), (LAS unsigned*)(lds + (bufoff) + ldsw + _i * 8192), 16, 0, 0); } while (0)
; #define PG8_LDA(dst, b, h) do { _Pragma("unroll") for (int m = 0; m < 4; ++m) _Pragma("unroll") for (int k = 0; k < 2; ++k) dst[m][k] = *(const LAS bf16x8*)(lds + PG8_SA(b, h) + aoff + m * 2048 + k * 1024); } while (0)
; #define PG8_LDB(dst, b, h) do { _Pragma("unroll") for (int n = 0; n < 2; ++n) _Pragma("unroll") for (int k = 0; k < 2; ++k) dst[n][k] = *(const LAS bf16x8*)(lds + PG8_SB(b, h) + boff + n * 2048 + k * 1024); } while (0)
; #define PG8_MMA(ai, bj, At, Bt) do { __builtin_amdgcn_s_setprio(1); _Pragma("unroll") for (int m = 0; m < 4; ++m) _Pragma("unroll") for (int n = 0; n < 2; ++n) _Pragma("unroll") for (int k = 0; k < 2; ++k) \
;         acc[ai][bj][m][n] = __builtin_amdgcn_mfma_f32_16x16x32_bf16(Bt[n][k], At[m][k], acc[ai][bj][m][n], 0, 0, 0); __builtin_amdgcn_s_setprio(0); } while (0)
; #define PG8_WAIT_V(n) asm volatile("s_waitcnt vmcnt(" #n ")" ::: "memory")
; #define PG8_WAIT_L(n) asm volatile("s_waitcnt lgkmcnt(" #n ")" ::: "memory")
; #define PG8_BAR __builtin_amdgcn_s_barrier()
; #define PG8_SCHED __builtin_amdgcn_sched_barrier(0)
; template <class Epi, class Sched>
; __device__ __forceinline__ void gemm_phase(int wv, LAS unsigned char* lds, const Gemm g, const Sched& S, const Epi& E) {
;     ...
;             PG8_WAIT_V(8); PG8_WAIT_L(0); PG8_BAR; PG8_MMA(1, 0, At, B0); PG8_MMA(1, 1, At, B1); PG8_BAR; PG8_SCHED;
;             PG8_LDB(B0, 1, 0); PG8_LDB(B1, 1, 1); PG8_SCHED; PG8_LDA(At, 1, 0); PG8_STAGE(PG8_SA(0, 1), a2 + hstep, voffA);
;             PG8_WAIT_V(8); PG8_WAIT_L(0); PG8_BAR; PG8_MMA(0, 0, At, B0); PG8_MMA(0, 1, At, B1); PG8_BAR; PG8_SCHED;
	s_waitcnt lgkmcnt(0)
	v_mfma_f32_16x16x32_bf16 v[60:63], v[142:145], v[174:177], v[60:63]
	v_mfma_f32_16x16x32_bf16 v[56:59], v[150:153], v[174:177], v[56:59]
	v_mfma_f32_16x16x32_bf16 v[52:55], v[142:145], v[182:185], v[52:55]
	v_mfma_f32_16x16x32_bf16 v[48:51], v[150:153], v[182:185], v[48:51]
	v_mfma_f32_16x16x32_bf16 v[36:39], v[142:145], v[202:205], v[36:39]
	v_mfma_f32_16x16x32_bf16 v[32:35], v[150:153], v[202:205], v[32:35]
	v_mfma_f32_16x16x32_bf16 v[20:23], v[142:145], v[210:213], v[20:23]
	v_mfma_f32_16x16x32_bf16 v[16:19], v[150:153], v[210:213], v[16:19]
	v_mfma_f32_16x16x32_bf16 v[60:63], v[146:149], v[178:181], v[60:63]
	v_mfma_f32_16x16x32_bf16 v[56:59], v[154:157], v[178:181], v[56:59]
	v_mfma_f32_16x16x32_bf16 v[52:55], v[146:149], v[198:201], v[52:55]
	v_mfma_f32_16x16x32_bf16 v[48:51], v[154:157], v[198:201], v[48:51]
	v_mfma_f32_16x16x32_bf16 v[36:39], v[146:149], v[206:209], v[36:39]
	v_mfma_f32_16x16x32_bf16 v[32:35], v[154:157], v[206:209], v[32:35]
	v_mfma_f32_16x16x32_bf16 v[20:23], v[146:149], v[214:217], v[20:23]
	v_mfma_f32_16x16x32_bf16 v[16:19], v[154:157], v[214:217], v[16:19]
	v_mfma_f32_16x16x32_bf16 v[44:47], v[158:161], v[174:177], v[44:47]
	v_mfma_f32_16x16x32_bf16 v[40:43], v[166:169], v[174:177], v[40:43]
	v_mfma_f32_16x16x32_bf16 v[28:31], v[158:161], v[182:185], v[28:31]
	v_mfma_f32_16x16x32_bf16 v[24:27], v[166:169], v[182:185], v[24:27]
	v_mfma_f32_16x16x32_bf16 v[12:15], v[158:161], v[202:205], v[12:15]
	v_mfma_f32_16x16x32_bf16 v[8:11], v[166:169], v[202:205], v[8:11]
	v_mfma_f32_16x16x32_bf16 v[4:7], v[158:161], v[210:213], v[4:7]
	v_mfma_f32_16x16x32_bf16 v[0:3], v[166:169], v[210:213], v[0:3]
	v_mfma_f32_16x16x32_bf16 v[44:47], v[162:165], v[178:181], v[44:47]
	v_mfma_f32_16x16x32_bf16 v[40:43], v[170:173], v[178:181], v[40:43]
	v_mfma_f32_16x16x32_bf16 v[28:31], v[162:165], v[198:201], v[28:31]
	v_mfma_f32_16x16x32_bf16 v[24:27], v[170:173], v[198:201], v[24:27]
	v_mfma_f32_16x16x32_bf16 v[12:15], v[162:165], v[206:209], v[12:15]
	v_mfma_f32_16x16x32_bf16 v[8:11], v[170:173], v[206:209], v[8:11]
	v_mfma_f32_16x16x32_bf16 v[4:7], v[162:165], v[214:217], v[4:7]
	v_mfma_f32_16x16x32_bf16 v[0:3], v[170:173], v[214:217], v[0:3]
	s_barrier
	s_add_i32 s44, 0, 0x1c000
	v_add_u32_e32 v154, s95, v139
	v_add_u32_e32 v170, s44, v139
	ds_read_b128 v[142:145], v154
	ds_read_b128 v[146:149], v154 offset:1024
	ds_read_b128 v[150:153], v154 offset:2048
	ds_read_b128 v[154:157], v154 offset:3072
	ds_read_b128 v[158:161], v170
	ds_read_b128 v[162:165], v170 offset:1024
	ds_read_b128 v[166:169], v170 offset:2048
	ds_read_b128 v[170:173], v170 offset:3072
	s_add_u32 s24, s24, 0x40000
	s_addc_u32 s25, s25, 0
	s_mov_b32 m0, s31
	v_lshl_add_u64 v[228:229], s[24:25], 0, v[132:133]
	ds_read_b128 v[174:177], v141 offset:32768
	ds_read_b128 v[178:181], v141 offset:33792
	ds_read_b128 v[182:185], v141 offset:34816
	ds_read_b128 v[198:201], v141 offset:35840
	ds_read_b128 v[202:205], v141 offset:36864
	ds_read_b128 v[206:209], v141 offset:37888
	ds_read_b128 v[210:213], v141 offset:38912
	ds_read_b128 v[214:217], v141 offset:39936
	global_load_lds_dwordx4 v[228:229], off
	v_lshl_add_u64 v[228:229], s[24:25], 0, v[130:131]
	s_mov_b32 m0, s34
	s_nop 0
	global_load_lds_dwordx4 v[228:229], off
	s_waitcnt vmcnt(8)
	s_waitcnt lgkmcnt(0)
	s_barrier
	s_waitcnt lgkmcnt(0)
	v_mfma_f32_16x16x32_bf16 v[124:127], v[142:145], v[174:177], v[124:127]
	v_mfma_f32_16x16x32_bf16 v[120:123], v[150:153], v[174:177], v[120:123]
	v_mfma_f32_16x16x32_bf16 v[116:119], v[142:145], v[182:185], v[116:119]
	v_mfma_f32_16x16x32_bf16 v[108:111], v[150:153], v[182:185], v[108:111]
	v_mfma_f32_16x16x32_bf16 v[100:103], v[142:145], v[202:205], v[100:103]
	v_mfma_f32_16x16x32_bf16 v[96:99], v[150:153], v[202:205], v[96:99]
	v_mfma_f32_16x16x32_bf16 v[84:87], v[142:145], v[210:213], v[84:87]
	v_mfma_f32_16x16x32_bf16 v[80:83], v[150:153], v[210:213], v[80:83]
	v_mfma_f32_16x16x32_bf16 v[124:127], v[146:149], v[178:181], v[124:127]
	v_mfma_f32_16x16x32_bf16 v[120:123], v[154:157], v[178:181], v[120:123]
	v_mfma_f32_16x16x32_bf16 v[116:119], v[146:149], v[198:201], v[116:119]
	v_mfma_f32_16x16x32_bf16 v[108:111], v[154:157], v[198:201], v[108:111]
	v_mfma_f32_16x16x32_bf16 v[100:103], v[146:149], v[206:209], v[100:103]
	v_mfma_f32_16x16x32_bf16 v[96:99], v[154:157], v[206:209], v[96:99]
	v_mfma_f32_16x16x32_bf16 v[84:87], v[146:149], v[214:217], v[84:87]
	v_mfma_f32_16x16x32_bf16 v[80:83], v[154:157], v[214:217], v[80:83]
	v_mfma_f32_16x16x32_bf16 v[112:115], v[158:161], v[174:177], v[112:115]
	v_mfma_f32_16x16x32_bf16 v[104:107], v[166:169], v[174:177], v[104:107]
	v_mfma_f32_16x16x32_bf16 v[92:95], v[158:161], v[182:185], v[92:95]
	v_mfma_f32_16x16x32_bf16 v[88:91], v[166:169], v[182:185], v[88:91]
	v_mfma_f32_16x16x32_bf16 v[76:79], v[158:161], v[202:205], v[76:79]
	v_mfma_f32_16x16x32_bf16 v[72:75], v[166:169], v[202:205], v[72:75]
	v_mfma_f32_16x16x32_bf16 v[68:71], v[158:161], v[210:213], v[68:71]
	v_mfma_f32_16x16x32_bf16 v[64:67], v[166:169], v[210:213], v[64:67]
	v_mfma_f32_16x16x32_bf16 v[112:115], v[162:165], v[178:181], v[112:115]
	v_mfma_f32_16x16x32_bf16 v[104:107], v[170:173], v[178:181], v[104:107]
	v_mfma_f32_16x16x32_bf16 v[92:95], v[162:165], v[198:201], v[92:95]
	v_mfma_f32_16x16x32_bf16 v[88:91], v[170:173], v[198:201], v[88:91]
	v_mfma_f32_16x16x32_bf16 v[76:79], v[162:165], v[206:209], v[76:79]
	v_mfma_f32_16x16x32_bf16 v[72:75], v[170:173], v[206:209], v[72:75]
	v_mfma_f32_16x16x32_bf16 v[68:71], v[162:165], v[214:217], v[68:71]
	v_mfma_f32_16x16x32_bf16 v[64:67], v[170:173], v[214:217], v[64:67]
	s_barrier
; #define PG8_STAGE(bufoff, gbase, voff) do { _Pragma("unroll") for (int _i = 0; _i < 2; ++_i) \
;         __builtin_amdgcn_global_load_lds((const unsigned*)((const char*)(gbase) + (voff)[_i]), (LAS unsigned*)(lds + (bufoff) + ldsw + _i * 8192), 16, 0, 0); } while (0)
; #define PG8_LDA(dst, b, h) do { _Pragma("unroll") for (int m = 0; m < 4; ++m) _Pragma("unroll") for (int k = 0; k < 2; ++k) dst[m][k] = *(const LAS bf16x8*)(lds + PG8_SA(b, h) + aoff + m * 2048 + k * 1024); } while (0)
; #define PG8_MMA(ai, bj, At, Bt) do { __builtin_amdgcn_s_setprio(1); _Pragma("unroll") for (int m = 0; m < 4; ++m) _Pragma("unroll") for (int n = 0; n < 2; ++n) _Pragma("unroll") for (int k = 0; k < 2; ++k) \
;         acc[ai][bj][m][n] = __builtin_amdgcn_mfma_f32_16x16x32_bf16(Bt[n][k], At[m][k], acc[ai][bj][m][n], 0, 0, 0); __builtin_amdgcn_s_setprio(0); } while (0)
; #define PG8_WAIT_V(n) asm volatile("s_waitcnt vmcnt(" #n ")" ::: "memory")
; #define PG8_WAIT_L(n) asm volatile("s_waitcnt lgkmcnt(" #n ")" ::: "memory")
; #define PG8_BAR __builtin_amdgcn_s_barrier()
; #define PG8_SCHED __builtin_amdgcn_sched_barrier(0)
; template <class Epi, class Sched>
; __device__ __forceinline__ void gemm_phase(int wv, LAS unsigned char* lds, const Gemm g, const Sched& S, const Epi& E) {
;     ...
;             PG8_LDA(At, 1, 1); PG8_STAGE(PG8_SB(1, 0), b3, voffB); PG8_STAGE(PG8_SB(1, 1), b3 + hstepB, voffB); PG8_STAGE(PG8_SA(1, 0), a3, voffA);
;             PG8_WAIT_V(8); PG8_WAIT_L(0); PG8_BAR; PG8_MMA(1, 0, At, B0); PG8_MMA(1, 1, At, B1); PG8_BAR; PG8_SCHED;
;         }
;         if (wr == 0) PG8_BAR;
	s_add_i32 s24, s95, s28
	v_lshl_add_u64 v[186:187], v[186:187], 0, s[74:75]
	s_mov_b32 m0, s24
	ds_read_b128 v[174:177], v141 offset:49152
	ds_read_b128 v[178:181], v141 offset:50176
	ds_read_b128 v[182:185], v141 offset:51200
	ds_read_b128 v[198:201], v141 offset:52224
	ds_read_b128 v[202:205], v141 offset:53248
	ds_read_b128 v[206:209], v141 offset:54272
	ds_read_b128 v[210:213], v141 offset:55296
	ds_read_b128 v[214:217], v141 offset:56320
	global_load_lds_dwordx4 v[186:187], off
	s_add_i32 m0, s24, 0x2000
	s_add_u32 s22, s22, 0x4080
	v_lshl_add_u64 v[186:187], v[218:219], 0, s[74:75]
	s_addc_u32 s23, s23, 0
	s_add_i32 s24, s44, s28
	global_load_lds_dwordx4 v[186:187], off
	v_lshl_add_u64 v[186:187], s[22:23], 0, v[188:189]
	s_mov_b32 m0, s24
	s_nop 0
	global_load_lds_dwordx4 v[186:187], off
	v_lshl_add_u64 v[186:187], s[22:23], 0, v[128:129]
	s_add_i32 m0, s24, 0x2000
	s_nop 0
	global_load_lds_dwordx4 v[186:187], off
	v_lshl_add_u64 v[186:187], v[220:221], 0, s[74:75]
	s_mov_b32 m0, s35
	s_nop 0
	global_load_lds_dwordx4 v[186:187], off
	v_lshl_add_u64 v[186:187], v[222:223], 0, s[74:75]
	s_mov_b32 m0, s36
	s_nop 0
	global_load_lds_dwordx4 v[186:187], off
	s_waitcnt vmcnt(8)
	s_waitcnt lgkmcnt(0)
	s_barrier
	s_waitcnt lgkmcnt(0)
	v_mfma_f32_16x16x32_bf16 v[60:63], v[142:145], v[174:177], v[60:63]
	v_mfma_f32_16x16x32_bf16 v[56:59], v[150:153], v[174:177], v[56:59]
	v_mfma_f32_16x16x32_bf16 v[52:55], v[142:145], v[182:185], v[52:55]
	v_mfma_f32_16x16x32_bf16 v[48:51], v[150:153], v[182:185], v[48:51]
	v_mfma_f32_16x16x32_bf16 v[36:39], v[142:145], v[202:205], v[36:39]
	v_mfma_f32_16x16x32_bf16 v[32:35], v[150:153], v[202:205], v[32:35]
	v_mfma_f32_16x16x32_bf16 v[20:23], v[142:145], v[210:213], v[20:23]
	v_mfma_f32_16x16x32_bf16 v[16:19], v[150:153], v[210:213], v[16:19]
	v_mfma_f32_16x16x32_bf16 v[60:63], v[146:149], v[178:181], v[60:63]
	v_mfma_f32_16x16x32_bf16 v[56:59], v[154:157], v[178:181], v[56:59]
	v_mfma_f32_16x16x32_bf16 v[52:55], v[146:149], v[198:201], v[52:55]
	v_mfma_f32_16x16x32_bf16 v[48:51], v[154:157], v[198:201], v[48:51]
	v_mfma_f32_16x16x32_bf16 v[36:39], v[146:149], v[206:209], v[36:39]
	v_mfma_f32_16x16x32_bf16 v[32:35], v[154:157], v[206:209], v[32:35]
	v_mfma_f32_16x16x32_bf16 v[20:23], v[146:149], v[214:217], v[20:23]
	v_mfma_f32_16x16x32_bf16 v[16:19], v[154:157], v[214:217], v[16:19]
	v_mfma_f32_16x16x32_bf16 v[44:47], v[158:161], v[174:177], v[44:47]
	v_mfma_f32_16x16x32_bf16 v[40:43], v[166:169], v[174:177], v[40:43]
	v_mfma_f32_16x16x32_bf16 v[28:31], v[158:161], v[182:185], v[28:31]
	v_mfma_f32_16x16x32_bf16 v[24:27], v[166:169], v[182:185], v[24:27]
	v_mfma_f32_16x16x32_bf16 v[12:15], v[158:161], v[202:205], v[12:15]
	v_mfma_f32_16x16x32_bf16 v[8:11], v[166:169], v[202:205], v[8:11]
	v_mfma_f32_16x16x32_bf16 v[4:7], v[158:161], v[210:213], v[4:7]
	v_mfma_f32_16x16x32_bf16 v[0:3], v[166:169], v[210:213], v[0:3]
	v_mfma_f32_16x16x32_bf16 v[44:47], v[162:165], v[178:181], v[44:47]
	v_mfma_f32_16x16x32_bf16 v[40:43], v[170:173], v[178:181], v[40:43]
	v_mfma_f32_16x16x32_bf16 v[28:31], v[162:165], v[198:201], v[28:31]
	v_mfma_f32_16x16x32_bf16 v[24:27], v[170:173], v[198:201], v[24:27]
	v_mfma_f32_16x16x32_bf16 v[12:15], v[162:165], v[206:209], v[12:15]
	v_mfma_f32_16x16x32_bf16 v[8:11], v[170:173], v[206:209], v[8:11]
	v_mfma_f32_16x16x32_bf16 v[4:7], v[162:165], v[214:217], v[4:7]
	v_mfma_f32_16x16x32_bf16 v[0:3], v[170:173], v[214:217], v[0:3]
	s_barrier
	s_add_i32 s43, s43, 2
	s_add_u32 s20, s20, 0x100
	s_addc_u32 s21, s21, 0
	s_add_u32 s41, s41, 0x100
	s_addc_u32 s42, s42, 0
	s_cmp_gt_u32 s43, 13
	s_cbranch_scc0 .LBB0_781
	s_and_b64 vcc, exec, s[10:11]
	s_cbranch_vccz .LBB0_784
	s_barrier

; #define PG8_STAGE(bufoff, gbase, voff) do { _Pragma("unroll") for (int _i = 0; _i < 2; ++_i) \
;         __builtin_amdgcn_global_load_lds((const unsigned*)((const char*)(gbase) + (voff)[_i]), (LAS unsigned*)(lds + (bufoff) + ldsw + _i * 8192), 16, 0, 0); } while (0)
; #define PG8_LDA(dst, b, h) do { _Pragma("unroll") for (int m = 0; m < 4; ++m) _Pragma("unroll") for (int k = 0; k < 2; ++k) dst[m][k] = *(const LAS bf16x8*)(lds + PG8_SA(b, h) + aoff + m * 2048 + k * 1024); } while (0)
; #define PG8_LDB(dst, b, h) do { _Pragma("unroll") for (int n = 0; n < 2; ++n) _Pragma("unroll") for (int k = 0; k < 2; ++k) dst[n][k] = *(const LAS bf16x8*)(lds + PG8_SB(b, h) + boff + n * 2048 + k * 1024); } while (0)
; #define PG8_MMA(ai, bj, At, Bt) do { __builtin_amdgcn_s_setprio(1); _Pragma("unroll") for (int m = 0; m < 4; ++m) _Pragma("unroll") for (int n = 0; n < 2; ++n) _Pragma("unroll") for (int k = 0; k < 2; ++k) \
;         acc[ai][bj][m][n] = __builtin_amdgcn_mfma_f32_16x16x32_bf16(Bt[n][k], At[m][k], acc[ai][bj][m][n], 0, 0, 0); __builtin_amdgcn_s_setprio(0); } while (0)
; #define PG8_WAIT_V(n) asm volatile("s_waitcnt vmcnt(" #n ")" ::: "memory")
; #define PG8_WAIT_L(n) asm volatile("s_waitcnt lgkmcnt(" #n ")" ::: "memory")
; #define PG8_BAR __builtin_amdgcn_s_barrier()
; #define PG8_SCHED __builtin_amdgcn_sched_barrier(0)
; template <class Epi, class Sched>
; __device__ __forceinline__ void gemm_phase(int wv, LAS unsigned char* lds, const Gemm g, const Sched& S, const Epi& E) {
;     ...
;             const bool last = (t == nt - 2);
;             const char* a1 = cA + (size_t)(t + 1) * kstep;
;             const char* a2 = last ? nA : cA + (size_t)(t + 2) * kstep; const char* b2 = last ? nB : cB + (size_t)(t + 2) * kstep;
;             const char* a3 = a2 + kstep; const char* b3 = b2 + kstep;
;             PG8_LDB(B0, 0, 0); PG8_LDB(B1, 0, 1); PG8_SCHED; PG8_LDA(At, 0, 0); PG8_STAGE(PG8_SA(1, 1), a1 + hstep, voffA);
;             PG8_WAIT_V(8); PG8_WAIT_L(0); PG8_BAR; PG8_MMA(0, 0, At, B0); PG8_MMA(0, 1, At, B1); PG8_BAR; PG8_SCHED;
;             PG8_LDA(At, 0, 1); PG8_STAGE(PG8_SB(0, 0), b2, voffB); PG8_STAGE(PG8_SB(0, 1), b2 + hstepB, voffB); PG8_STAGE(PG8_SA(0, 0), a2, voffA);
;             PG8_WAIT_V(8); PG8_WAIT_L(0); PG8_BAR; PG8_MMA(1, 0, At, B0); PG8_MMA(1, 1, At, B1); PG8_BAR; PG8_SCHED;
.LBB0_801:
	s_add_u32 s20, s18, 0xfffe0080
	s_addc_u32 s21, s19, -1
	s_add_i32 s44, 0, 0x10000
	s_cmp_eq_u32 s43, 4
	s_cselect_b32 s23, s11, s21
	s_cselect_b32 s22, s39, s20
	s_cselect_b32 s21, s13, s42
	s_cselect_b32 s20, s40, s41
	s_add_i32 s46, 0, 0x14000
	v_add_u32_e32 v154, s44, v139
	v_add_u32_e32 v170, s46, v139
	ds_read_b128 v[142:145], v154
	ds_read_b128 v[146:149], v154 offset:1024
	ds_read_b128 v[150:153], v154 offset:2048
	ds_read_b128 v[154:157], v154 offset:3072
	ds_read_b128 v[158:161], v170
	ds_read_b128 v[162:165], v170 offset:1024
	ds_read_b128 v[166:169], v170 offset:2048
	ds_read_b128 v[170:173], v170 offset:3072
	v_lshl_add_u64 v[186:187], s[18:19], 0, v[134:135]
	s_add_i32 m0, s29, 0xc000
	ds_read_b128 v[174:177], v141
	ds_read_b128 v[178:181], v141 offset:1024
	ds_read_b128 v[182:185], v141 offset:2048
	ds_read_b128 v[198:201], v141 offset:3072
	ds_read_b128 v[202:205], v141 offset:4096
	ds_read_b128 v[206:209], v141 offset:5120
	ds_read_b128 v[210:213], v141 offset:6144
	ds_read_b128 v[214:217], v141 offset:7168
	global_load_lds_dwordx4 v[186:187], off
	v_lshl_add_u64 v[186:187], s[18:19], 0, v[136:137]
	s_add_i32 m0, s29, 0xe000
	s_nop 0
	global_load_lds_dwordx4 v[186:187], off
	s_waitcnt vmcnt(8)
	s_waitcnt lgkmcnt(0)
	s_barrier
	s_waitcnt lgkmcnt(0)
	v_mfma_f32_16x16x32_bf16 v[124:127], v[142:145], v[174:177], v[124:127]
	v_mfma_f32_16x16x32_bf16 v[120:123], v[150:153], v[174:177], v[120:123]
	v_mfma_f32_16x16x32_bf16 v[116:119], v[142:145], v[182:185], v[116:119]
	v_mfma_f32_16x16x32_bf16 v[108:111], v[150:153], v[182:185], v[108:111]
	v_mfma_f32_16x16x32_bf16 v[100:103], v[142:145], v[202:205], v[100:103]
	v_mfma_f32_16x16x32_bf16 v[96:99], v[150:153], v[202:205], v[96:99]
	v_mfma_f32_16x16x32_bf16 v[84:87], v[142:145], v[210:213], v[84:87]
	v_mfma_f32_16x16x32_bf16 v[80:83], v[150:153], v[210:213], v[80:83]
	v_mfma_f32_16x16x32_bf16 v[124:127], v[146:149], v[178:181], v[124:127]
	v_mfma_f32_16x16x32_bf16 v[120:123], v[154:157], v[178:181], v[120:123]
	v_mfma_f32_16x16x32_bf16 v[116:119], v[146:149], v[198:201], v[116:119]
	v_mfma_f32_16x16x32_bf16 v[108:111], v[154:157], v[198:201], v[108:111]
	v_mfma_f32_16x16x32_bf16 v[100:103], v[146:149], v[206:209], v[100:103]
	v_mfma_f32_16x16x32_bf16 v[96:99], v[154:157], v[206:209], v[96:99]
	v_mfma_f32_16x16x32_bf16 v[84:87], v[146:149], v[214:217], v[84:87]
	v_mfma_f32_16x16x32_bf16 v[80:83], v[154:157], v[214:217], v[80:83]
	v_mfma_f32_16x16x32_bf16 v[112:115], v[158:161], v[174:177], v[112:115]
	v_mfma_f32_16x16x32_bf16 v[104:107], v[166:169], v[174:177], v[104:107]
	v_mfma_f32_16x16x32_bf16 v[92:95], v[158:161], v[182:185], v[92:95]
	v_mfma_f32_16x16x32_bf16 v[88:91], v[166:169], v[182:185], v[88:91]
	v_mfma_f32_16x16x32_bf16 v[76:79], v[158:161], v[202:205], v[76:79]
	v_mfma_f32_16x16x32_bf16 v[72:75], v[166:169], v[202:205], v[72:75]
	v_mfma_f32_16x16x32_bf16 v[68:71], v[158:161], v[210:213], v[68:71]
	v_mfma_f32_16x16x32_bf16 v[64:67], v[166:169], v[210:213], v[64:67]
	v_mfma_f32_16x16x32_bf16 v[112:115], v[162:165], v[178:181], v[112:115]
	v_mfma_f32_16x16x32_bf16 v[104:107], v[170:173], v[178:181], v[104:107]
	v_mfma_f32_16x16x32_bf16 v[92:95], v[162:165], v[198:201], v[92:95]
	v_mfma_f32_16x16x32_bf16 v[88:91], v[170:173], v[198:201], v[88:91]
	v_mfma_f32_16x16x32_bf16 v[76:79], v[162:165], v[206:209], v[76:79]
	v_mfma_f32_16x16x32_bf16 v[72:75], v[170:173], v[206:209], v[72:75]
	v_mfma_f32_16x16x32_bf16 v[68:71], v[162:165], v[214:217], v[68:71]
	v_mfma_f32_16x16x32_bf16 v[64:67], v[170:173], v[214:217], v[64:67]
	s_barrier
	s_add_i32 s44, s44, s28
	v_lshl_add_u64 v[186:187], s[20:21], 0, v[188:189]
	s_mov_b32 m0, s44
	ds_read_b128 v[174:177], v141 offset:16384
	ds_read_b128 v[178:181], v141 offset:17408
	ds_read_b128 v[182:185], v141 offset:18432
	ds_read_b128 v[198:201], v141 offset:19456
	ds_read_b128 v[202:205], v141 offset:20480
	ds_read_b128 v[206:209], v141 offset:21504
	ds_read_b128 v[210:213], v141 offset:22528
	ds_read_b128 v[214:217], v141 offset:23552
	global_load_lds_dwordx4 v[186:187], off
	s_add_i32 m0, s44, 0x2000
	s_add_u32 s44, s20, 0x2000
	v_lshl_add_u64 v[218:219], s[20:21], 0, v[128:129]
	s_addc_u32 s45, s21, 0
	s_add_i32 s46, s46, s28
	global_load_lds_dwordx4 v[218:219], off
	v_lshl_add_u64 v[220:221], s[44:45], 0, v[188:189]
	s_mov_b32 m0, s46
	v_lshl_add_u64 v[222:223], s[22:23], 0, v[130:131]
	global_load_lds_dwordx4 v[220:221], off
	v_lshl_add_u64 v[220:221], s[44:45], 0, v[128:129]
	s_add_i32 m0, s46, 0x2000
	s_nop 0
	global_load_lds_dwordx4 v[220:221], off
	v_lshl_add_u64 v[220:221], s[22:23], 0, v[132:133]
	s_mov_b32 m0, s29
	s_nop 0
	global_load_lds_dwordx4 v[220:221], off
	s_mov_b32 m0, s30
	s_nop 0
	global_load_lds_dwordx4 v[222:223], off
	s_waitcnt vmcnt(8)
	s_waitcnt lgkmcnt(0)
	s_barrier
; #define PG8_STAGE(bufoff, gbase, voff) do { _Pragma("unroll") for (int _i = 0; _i < 2; ++_i) \
;         __builtin_amdgcn_global_load_lds((const unsigned*)((const char*)(gbase) + (voff)[_i]), (LAS unsigned*)(lds + (bufoff) + ldsw + _i * 8192), 16, 0, 0); } while (0)
; #define PG8_LDA(dst, b, h) do { _Pragma("unroll") for (int m = 0; m < 4; ++m) _Pragma("unroll") for (int k = 0; k < 2; ++k) dst[m][k] = *(const LAS bf16x8*)(lds + PG8_SA(b, h) + aoff + m * 2048 + k * 1024); } while (0)
; #define PG8_LDB(dst, b, h) do { _Pragma("unroll") for (int n = 0; n < 2; ++n) _Pragma("unroll") for (int k = 0; k < 2; ++k) dst[n][k] = *(const LAS bf16x8*)(lds + PG8_SB(b, h) + boff + n * 2048 + k * 1024); } while (0)
; #define PG8_MMA(ai, bj, At, Bt) do { __builtin_amdgcn_s_setprio(1); _Pragma("unroll") for (int m = 0; m < 4; ++m) _Pragma("unroll") for (int n = 0; n < 2; ++n) _Pragma("unroll") for (int k = 0; k < 2; ++k) \
;         acc[ai][bj][m][n] = __builtin_amdgcn_mfma_f32_16x16x32_bf16(Bt[n][k], At[m][k], acc[ai][bj][m][n], 0, 0, 0); __builtin_amdgcn_s_setprio(0); } while (0)
; #define PG8_WAIT_V(n) asm volatile("s_waitcnt vmcnt(" #n ")" ::: "memory")
; #define PG8_WAIT_L(n) asm volatile("s_waitcnt lgkmcnt(" #n ")" ::: "memory")
; #define PG8_BAR __builtin_amdgcn_s_barrier()
; #define PG8_SCHED __builtin_amdgcn_sched_barrier(0)
; template <class Epi, class Sched>
; __device__ __forceinline__ void gemm_phase(int wv, LAS unsigned char* lds, const Gemm g, const Sched& S, const Epi& E) {
;     ...
;             PG8_WAIT_V(8); PG8_WAIT_L(0); PG8_BAR; PG8_MMA(1, 0, At, B0); PG8_MMA(1, 1, At, B1); PG8_BAR; PG8_SCHED;
;             PG8_LDB(B0, 1, 0); PG8_LDB(B1, 1, 1); PG8_SCHED; PG8_LDA(At, 1, 0); PG8_STAGE(PG8_SA(0, 1), a2 + hstep, voffA);
;             PG8_WAIT_V(8); PG8_WAIT_L(0); PG8_BAR; PG8_MMA(0, 0, At, B0); PG8_MMA(0, 1, At, B1); PG8_BAR; PG8_SCHED;
	s_waitcnt lgkmcnt(0)
	v_mfma_f32_16x16x32_bf16 v[60:63], v[142:145], v[174:177], v[60:63]
	v_mfma_f32_16x16x32_bf16 v[56:59], v[150:153], v[174:177], v[56:59]
	v_mfma_f32_16x16x32_bf16 v[52:55], v[142:145], v[182:185], v[52:55]
	v_mfma_f32_16x16x32_bf16 v[48:51], v[150:153], v[182:185], v[48:51]
	v_mfma_f32_16x16x32_bf16 v[36:39], v[142:145], v[202:205], v[36:39]
	v_mfma_f32_16x16x32_bf16 v[32:35], v[150:153], v[202:205], v[32:35]
	v_mfma_f32_16x16x32_bf16 v[20:23], v[142:145], v[210:213], v[20:23]
	v_mfma_f32_16x16x32_bf16 v[16:19], v[150:153], v[210:213], v[16:19]
	v_mfma_f32_16x16x32_bf16 v[60:63], v[146:149], v[178:181], v[60:63]
	v_mfma_f32_16x16x32_bf16 v[56:59], v[154:157], v[178:181], v[56:59]
	v_mfma_f32_16x16x32_bf16 v[52:55], v[146:149], v[198:201], v[52:55]
	v_mfma_f32_16x16x32_bf16 v[48:51], v[154:157], v[198:201], v[48:51]
	v_mfma_f32_16x16x32_bf16 v[36:39], v[146:149], v[206:209], v[36:39]
	v_mfma_f32_16x16x32_bf16 v[32:35], v[154:157], v[206:209], v[32:35]
	v_mfma_f32_16x16x32_bf16 v[20:23], v[146:149], v[214:217], v[20:23]
	v_mfma_f32_16x16x32_bf16 v[16:19], v[154:157], v[214:217], v[16:19]
	v_mfma_f32_16x16x32_bf16 v[44:47], v[158:161], v[174:177], v[44:47]
	v_mfma_f32_16x16x32_bf16 v[40:43], v[166:169], v[174:177], v[40:43]
	v_mfma_f32_16x16x32_bf16 v[28:31], v[158:161], v[182:185], v[28:31]
	v_mfma_f32_16x16x32_bf16 v[24:27], v[166:169], v[182:185], v[24:27]
	v_mfma_f32_16x16x32_bf16 v[12:15], v[158:161], v[202:205], v[12:15]
	v_mfma_f32_16x16x32_bf16 v[8:11], v[166:169], v[202:205], v[8:11]
	v_mfma_f32_16x16x32_bf16 v[4:7], v[158:161], v[210:213], v[4:7]
	v_mfma_f32_16x16x32_bf16 v[0:3], v[166:169], v[210:213], v[0:3]
	v_mfma_f32_16x16x32_bf16 v[44:47], v[162:165], v[178:181], v[44:47]
	v_mfma_f32_16x16x32_bf16 v[40:43], v[170:173], v[178:181], v[40:43]
	v_mfma_f32_16x16x32_bf16 v[28:31], v[162:165], v[198:201], v[28:31]
	v_mfma_f32_16x16x32_bf16 v[24:27], v[170:173], v[198:201], v[24:27]
	v_mfma_f32_16x16x32_bf16 v[12:15], v[162:165], v[206:209], v[12:15]
	v_mfma_f32_16x16x32_bf16 v[8:11], v[170:173], v[206:209], v[8:11]
	v_mfma_f32_16x16x32_bf16 v[4:7], v[162:165], v[214:217], v[4:7]
	v_mfma_f32_16x16x32_bf16 v[0:3], v[170:173], v[214:217], v[0:3]
	s_barrier
	s_add_i32 s44, 0, 0x1c000
	v_add_u32_e32 v154, s95, v139
	v_add_u32_e32 v170, s44, v139
	ds_read_b128 v[142:145], v154
	ds_read_b128 v[146:149], v154 offset:1024
	ds_read_b128 v[150:153], v154 offset:2048
	ds_read_b128 v[154:157], v154 offset:3072
	ds_read_b128 v[158:161], v170
	ds_read_b128 v[162:165], v170 offset:1024
	ds_read_b128 v[166:169], v170 offset:2048
	ds_read_b128 v[170:173], v170 offset:3072
	s_add_u32 s22, s22, 0x20000
	s_addc_u32 s23, s23, 0
	s_mov_b32 m0, s31
	v_lshl_add_u64 v[228:229], s[22:23], 0, v[132:133]
	ds_read_b128 v[174:177], v141 offset:32768
	ds_read_b128 v[178:181], v141 offset:33792
	ds_read_b128 v[182:185], v141 offset:34816
	ds_read_b128 v[198:201], v141 offset:35840
	ds_read_b128 v[202:205], v141 offset:36864
	ds_read_b128 v[206:209], v141 offset:37888
	ds_read_b128 v[210:213], v141 offset:38912
	ds_read_b128 v[214:217], v141 offset:39936
	global_load_lds_dwordx4 v[228:229], off
	v_lshl_add_u64 v[228:229], s[22:23], 0, v[130:131]
	s_mov_b32 m0, s34
	s_nop 0
	global_load_lds_dwordx4 v[228:229], off
	s_waitcnt vmcnt(8)
	s_waitcnt lgkmcnt(0)
	s_barrier
	s_waitcnt lgkmcnt(0)
	v_mfma_f32_16x16x32_bf16 v[124:127], v[142:145], v[174:177], v[124:127]
	v_mfma_f32_16x16x32_bf16 v[120:123], v[150:153], v[174:177], v[120:123]
	v_mfma_f32_16x16x32_bf16 v[116:119], v[142:145], v[182:185], v[116:119]
	v_mfma_f32_16x16x32_bf16 v[108:111], v[150:153], v[182:185], v[108:111]
	v_mfma_f32_16x16x32_bf16 v[100:103], v[142:145], v[202:205], v[100:103]
	v_mfma_f32_16x16x32_bf16 v[96:99], v[150:153], v[202:205], v[96:99]
	v_mfma_f32_16x16x32_bf16 v[84:87], v[142:145], v[210:213], v[84:87]
	v_mfma_f32_16x16x32_bf16 v[80:83], v[150:153], v[210:213], v[80:83]
	v_mfma_f32_16x16x32_bf16 v[124:127], v[146:149], v[178:181], v[124:127]
	v_mfma_f32_16x16x32_bf16 v[120:123], v[154:157], v[178:181], v[120:123]
	v_mfma_f32_16x16x32_bf16 v[116:119], v[146:149], v[198:201], v[116:119]
	v_mfma_f32_16x16x32_bf16 v[108:111], v[154:157], v[198:201], v[108:111]
	v_mfma_f32_16x16x32_bf16 v[100:103], v[146:149], v[206:209], v[100:103]
	v_mfma_f32_16x16x32_bf16 v[96:99], v[154:157], v[206:209], v[96:99]
	v_mfma_f32_16x16x32_bf16 v[84:87], v[146:149], v[214:217], v[84:87]
	v_mfma_f32_16x16x32_bf16 v[80:83], v[154:157], v[214:217], v[80:83]
	v_mfma_f32_16x16x32_bf16 v[112:115], v[158:161], v[174:177], v[112:115]
	v_mfma_f32_16x16x32_bf16 v[104:107], v[166:169], v[174:177], v[104:107]
	v_mfma_f32_16x16x32_bf16 v[92:95], v[158:161], v[182:185], v[92:95]
	v_mfma_f32_16x16x32_bf16 v[88:91], v[166:169], v[182:185], v[88:91]
	v_mfma_f32_16x16x32_bf16 v[76:79], v[158:161], v[202:205], v[76:79]
	v_mfma_f32_16x16x32_bf16 v[72:75], v[166:169], v[202:205], v[72:75]
	v_mfma_f32_16x16x32_bf16 v[68:71], v[158:161], v[210:213], v[68:71]
	v_mfma_f32_16x16x32_bf16 v[64:67], v[166:169], v[210:213], v[64:67]
	v_mfma_f32_16x16x32_bf16 v[112:115], v[162:165], v[178:181], v[112:115]
	v_mfma_f32_16x16x32_bf16 v[104:107], v[170:173], v[178:181], v[104:107]
	v_mfma_f32_16x16x32_bf16 v[92:95], v[162:165], v[198:201], v[92:95]
	v_mfma_f32_16x16x32_bf16 v[88:91], v[170:173], v[198:201], v[88:91]
	v_mfma_f32_16x16x32_bf16 v[76:79], v[162:165], v[206:209], v[76:79]
	v_mfma_f32_16x16x32_bf16 v[72:75], v[170:173], v[206:209], v[72:75]
	v_mfma_f32_16x16x32_bf16 v[68:71], v[162:165], v[214:217], v[68:71]
	v_mfma_f32_16x16x32_bf16 v[64:67], v[170:173], v[214:217], v[64:67]
	s_barrier
; #define PG8_STAGE(bufoff, gbase, voff) do { _Pragma("unroll") for (int _i = 0; _i < 2; ++_i) \
;         __builtin_amdgcn_global_load_lds((const unsigned*)((const char*)(gbase) + (voff)[_i]), (LAS unsigned*)(lds + (bufoff) + ldsw + _i * 8192), 16, 0, 0); } while (0)
; #define PG8_LDA(dst, b, h) do { _Pragma("unroll") for (int m = 0; m < 4; ++m) _Pragma("unroll") for (int k = 0; k < 2; ++k) dst[m][k] = *(const LAS bf16x8*)(lds + PG8_SA(b, h) + aoff + m * 2048 + k * 1024); } while (0)
; #define PG8_MMA(ai, bj, At, Bt) do { __builtin_amdgcn_s_setprio(1); _Pragma("unroll") for (int m = 0; m < 4; ++m) _Pragma("unroll") for (int n = 0; n < 2; ++n) _Pragma("unroll") for (int k = 0; k < 2; ++k) \
;         acc[ai][bj][m][n] = __builtin_amdgcn_mfma_f32_16x16x32_bf16(Bt[n][k], At[m][k], acc[ai][bj][m][n], 0, 0, 0); __builtin_amdgcn_s_setprio(0); } while (0)
; #define PG8_WAIT_V(n) asm volatile("s_waitcnt vmcnt(" #n ")" ::: "memory")
; #define PG8_WAIT_L(n) asm volatile("s_waitcnt lgkmcnt(" #n ")" ::: "memory")
; #define PG8_BAR __builtin_amdgcn_s_barrier()
; #define PG8_SCHED __builtin_amdgcn_sched_barrier(0)
; template <class Epi, class Sched>
; __device__ __forceinline__ void gemm_phase(int wv, LAS unsigned char* lds, const Gemm g, const Sched& S, const Epi& E) {
;     ...
;             PG8_LDA(At, 1, 1); PG8_STAGE(PG8_SB(1, 0), b3, voffB); PG8_STAGE(PG8_SB(1, 1), b3 + hstepB, voffB); PG8_STAGE(PG8_SA(1, 0), a3, voffA);
;             PG8_WAIT_V(8); PG8_WAIT_L(0); PG8_BAR; PG8_MMA(1, 0, At, B0); PG8_MMA(1, 1, At, B1); PG8_BAR; PG8_SCHED;
;         }
;         if (wr == 0) PG8_BAR;
	s_add_i32 s22, s95, s28
	v_lshl_add_u64 v[186:187], v[186:187], 0, s[74:75]
	s_mov_b32 m0, s22
	ds_read_b128 v[174:177], v141 offset:49152
	ds_read_b128 v[178:181], v141 offset:50176
	ds_read_b128 v[182:185], v141 offset:51200
	ds_read_b128 v[198:201], v141 offset:52224
	ds_read_b128 v[202:205], v141 offset:53248
	ds_read_b128 v[206:209], v141 offset:54272
	ds_read_b128 v[210:213], v141 offset:55296
	ds_read_b128 v[214:217], v141 offset:56320
	global_load_lds_dwordx4 v[186:187], off
	s_add_i32 m0, s22, 0x2000
	s_add_u32 s20, s20, 0x2080
	v_lshl_add_u64 v[186:187], v[218:219], 0, s[74:75]
	s_addc_u32 s21, s21, 0
	s_add_i32 s22, s44, s28
	global_load_lds_dwordx4 v[186:187], off
	v_lshl_add_u64 v[186:187], s[20:21], 0, v[188:189]
	s_mov_b32 m0, s22
	s_nop 0
	global_load_lds_dwordx4 v[186:187], off
	v_lshl_add_u64 v[186:187], s[20:21], 0, v[128:129]
	s_add_i32 m0, s22, 0x2000
	s_nop 0
	global_load_lds_dwordx4 v[186:187], off
	v_lshl_add_u64 v[186:187], v[220:221], 0, s[74:75]
	s_mov_b32 m0, s35
	s_nop 0
	global_load_lds_dwordx4 v[186:187], off
	v_lshl_add_u64 v[186:187], v[222:223], 0, s[74:75]
	s_mov_b32 m0, s36
	s_nop 0
	global_load_lds_dwordx4 v[186:187], off
	s_waitcnt vmcnt(8)
	s_waitcnt lgkmcnt(0)
	s_barrier
	s_waitcnt lgkmcnt(0)
	v_mfma_f32_16x16x32_bf16 v[60:63], v[142:145], v[174:177], v[60:63]
	v_mfma_f32_16x16x32_bf16 v[56:59], v[150:153], v[174:177], v[56:59]
	v_mfma_f32_16x16x32_bf16 v[52:55], v[142:145], v[182:185], v[52:55]
	v_mfma_f32_16x16x32_bf16 v[48:51], v[150:153], v[182:185], v[48:51]
	v_mfma_f32_16x16x32_bf16 v[36:39], v[142:145], v[202:205], v[36:39]
	v_mfma_f32_16x16x32_bf16 v[32:35], v[150:153], v[202:205], v[32:35]
	v_mfma_f32_16x16x32_bf16 v[20:23], v[142:145], v[210:213], v[20:23]
	v_mfma_f32_16x16x32_bf16 v[16:19], v[150:153], v[210:213], v[16:19]
	v_mfma_f32_16x16x32_bf16 v[60:63], v[146:149], v[178:181], v[60:63]
	v_mfma_f32_16x16x32_bf16 v[56:59], v[154:157], v[178:181], v[56:59]
	v_mfma_f32_16x16x32_bf16 v[52:55], v[146:149], v[198:201], v[52:55]
	v_mfma_f32_16x16x32_bf16 v[48:51], v[154:157], v[198:201], v[48:51]
	v_mfma_f32_16x16x32_bf16 v[36:39], v[146:149], v[206:209], v[36:39]
	v_mfma_f32_16x16x32_bf16 v[32:35], v[154:157], v[206:209], v[32:35]
	v_mfma_f32_16x16x32_bf16 v[20:23], v[146:149], v[214:217], v[20:23]
	v_mfma_f32_16x16x32_bf16 v[16:19], v[154:157], v[214:217], v[16:19]
	v_mfma_f32_16x16x32_bf16 v[44:47], v[158:161], v[174:177], v[44:47]
	v_mfma_f32_16x16x32_bf16 v[40:43], v[166:169], v[174:177], v[40:43]
	v_mfma_f32_16x16x32_bf16 v[28:31], v[158:161], v[182:185], v[28:31]
	v_mfma_f32_16x16x32_bf16 v[24:27], v[166:169], v[182:185], v[24:27]
	v_mfma_f32_16x16x32_bf16 v[12:15], v[158:161], v[202:205], v[12:15]
	v_mfma_f32_16x16x32_bf16 v[8:11], v[166:169], v[202:205], v[8:11]
	v_mfma_f32_16x16x32_bf16 v[4:7], v[158:161], v[210:213], v[4:7]
	v_mfma_f32_16x16x32_bf16 v[0:3], v[166:169], v[210:213], v[0:3]
	v_mfma_f32_16x16x32_bf16 v[44:47], v[162:165], v[178:181], v[44:47]
	v_mfma_f32_16x16x32_bf16 v[40:43], v[170:173], v[178:181], v[40:43]
	v_mfma_f32_16x16x32_bf16 v[28:31], v[162:165], v[198:201], v[28:31]
	v_mfma_f32_16x16x32_bf16 v[24:27], v[170:173], v[198:201], v[24:27]
	v_mfma_f32_16x16x32_bf16 v[12:15], v[162:165], v[206:209], v[12:15]
	v_mfma_f32_16x16x32_bf16 v[8:11], v[170:173], v[206:209], v[8:11]
	v_mfma_f32_16x16x32_bf16 v[4:7], v[162:165], v[214:217], v[4:7]
	v_mfma_f32_16x16x32_bf16 v[0:3], v[170:173], v[214:217], v[0:3]
	s_barrier
	s_add_i32 s43, s43, 2
	s_add_u32 s18, s18, 0x100
	s_addc_u32 s19, s19, 0
	s_add_u32 s41, s41, 0x100
	s_addc_u32 s42, s42, 0
	s_cmp_gt_u32 s43, 5
	s_cbranch_scc0 .LBB0_801
	s_and_b64 vcc, exec, s[8:9]
	s_cbranch_vccz .LBB0_804
	s_barrier

; #define PG8_STAGE(bufoff, gbase, voff) do { _Pragma("unroll") for (int _i = 0; _i < 2; ++_i) \
;         __builtin_amdgcn_global_load_lds((const unsigned*)((const char*)(gbase) + (voff)[_i]), (LAS unsigned*)(lds + (bufoff) + ldsw + _i * 8192), 16, 0, 0); } while (0)
; #define PG8_LDA(dst, b, h) do { _Pragma("unroll") for (int m = 0; m < 4; ++m) _Pragma("unroll") for (int k = 0; k < 2; ++k) dst[m][k] = *(const LAS bf16x8*)(lds + PG8_SA(b, h) + aoff + m * 2048 + k * 1024); } while (0)
; #define PG8_LDB(dst, b, h) do { _Pragma("unroll") for (int n = 0; n < 2; ++n) _Pragma("unroll") for (int k = 0; k < 2; ++k) dst[n][k] = *(const LAS bf16x8*)(lds + PG8_SB(b, h) + boff + n * 2048 + k * 1024); } while (0)
; #define PG8_MMA(ai, bj, At, Bt) do { __builtin_amdgcn_s_setprio(1); _Pragma("unroll") for (int m = 0; m < 4; ++m) _Pragma("unroll") for (int n = 0; n < 2; ++n) _Pragma("unroll") for (int k = 0; k < 2; ++k) \
;         acc[ai][bj][m][n] = __builtin_amdgcn_mfma_f32_16x16x32_bf16(Bt[n][k], At[m][k], acc[ai][bj][m][n], 0, 0, 0); __builtin_amdgcn_s_setprio(0); } while (0)
; #define PG8_WAIT_V(n) asm volatile("s_waitcnt vmcnt(" #n ")" ::: "memory")
; #define PG8_WAIT_L(n) asm volatile("s_waitcnt lgkmcnt(" #n ")" ::: "memory")
; #define PG8_BAR __builtin_amdgcn_s_barrier()
; #define PG8_SCHED __builtin_amdgcn_sched_barrier(0)
; template <class Epi, class Sched>
; __device__ __forceinline__ void gemm_phase(int wv, LAS unsigned char* lds, const Gemm g, const Sched& S, const Epi& E) {
;     ...
;             const bool last = (t == nt - 2);
;             const char* a1 = cA + (size_t)(t + 1) * kstep;
;             const char* a2 = last ? nA : cA + (size_t)(t + 2) * kstep; const char* b2 = last ? nB : cB + (size_t)(t + 2) * kstep;
;             const char* a3 = a2 + kstep; const char* b3 = b2 + kstep;
;             PG8_LDB(B0, 0, 0); PG8_LDB(B1, 0, 1); PG8_SCHED; PG8_LDA(At, 0, 0); PG8_STAGE(PG8_SA(1, 1), a1 + hstep, voffA);
;             PG8_WAIT_V(8); PG8_WAIT_L(0); PG8_BAR; PG8_MMA(0, 0, At, B0); PG8_MMA(0, 1, At, B1); PG8_BAR; PG8_SCHED;
;             PG8_LDA(At, 0, 1); PG8_STAGE(PG8_SB(0, 0), b2, voffB); PG8_STAGE(PG8_SB(0, 1), b2 + hstepB, voffB); PG8_STAGE(PG8_SA(0, 0), a2, voffA);
;             PG8_WAIT_V(8); PG8_WAIT_L(0); PG8_BAR; PG8_MMA(1, 0, At, B0); PG8_MMA(1, 1, At, B1); PG8_BAR; PG8_SCHED;
.LBB0_821:
	s_add_u32 s22, s20, 0xfffc0080
	s_addc_u32 s23, s21, -1
	s_add_i32 s47, 0, 0x10000
	s_cmp_eq_u32 s46, 12
	s_cselect_b32 s25, s13, s23
	s_cselect_b32 s24, s42, s22
	s_cselect_b32 s23, s15, s45
	s_cselect_b32 s22, s43, s44
	s_add_i32 s50, 0, 0x14000
	v_add_u32_e32 v140, s47, v201
	v_add_u32_e32 v156, s50, v201
	ds_read_b128 v[120:123], v140
	ds_read_b128 v[124:127], v140 offset:1024
	ds_read_b128 v[136:139], v140 offset:2048
	ds_read_b128 v[140:143], v140 offset:3072
	ds_read_b128 v[144:147], v156
	ds_read_b128 v[148:151], v156 offset:1024
	ds_read_b128 v[152:155], v156 offset:2048
	ds_read_b128 v[156:159], v156 offset:3072
	v_lshl_add_u64 v[186:187], s[20:21], 0, v[174:175]
	s_add_i32 m0, s31, 0xc000
	ds_read_b128 v[160:163], v203
	ds_read_b128 v[164:167], v203 offset:1024
	ds_read_b128 v[178:181], v203 offset:2048
	ds_read_b128 v[182:185], v203 offset:3072
	ds_read_b128 v[204:207], v203 offset:4096
	ds_read_b128 v[208:211], v203 offset:5120
	ds_read_b128 v[212:215], v203 offset:6144
	ds_read_b128 v[216:219], v203 offset:7168
	global_load_lds_dwordx4 v[186:187], off
	v_lshl_add_u64 v[186:187], s[20:21], 0, v[176:177]
	s_add_i32 m0, s31, 0xe000
	s_nop 0
	global_load_lds_dwordx4 v[186:187], off
	s_waitcnt vmcnt(8)
	s_waitcnt lgkmcnt(0)
	s_barrier
	s_waitcnt lgkmcnt(0)
	v_mfma_f32_16x16x32_bf16 v[132:135], v[120:123], v[160:163], v[132:135]
	v_mfma_f32_16x16x32_bf16 v[116:119], v[136:139], v[160:163], v[116:119]
	v_mfma_f32_16x16x32_bf16 v[108:111], v[120:123], v[178:181], v[108:111]
	v_mfma_f32_16x16x32_bf16 v[100:103], v[136:139], v[178:181], v[100:103]
	v_mfma_f32_16x16x32_bf16 v[92:95], v[120:123], v[204:207], v[92:95]
	v_mfma_f32_16x16x32_bf16 v[84:87], v[136:139], v[204:207], v[84:87]
	v_mfma_f32_16x16x32_bf16 v[76:79], v[120:123], v[212:215], v[76:79]
	v_mfma_f32_16x16x32_bf16 v[68:71], v[136:139], v[212:215], v[68:71]
	v_mfma_f32_16x16x32_bf16 v[132:135], v[124:127], v[164:167], v[132:135]
	v_mfma_f32_16x16x32_bf16 v[116:119], v[140:143], v[164:167], v[116:119]
	v_mfma_f32_16x16x32_bf16 v[108:111], v[124:127], v[182:185], v[108:111]
	v_mfma_f32_16x16x32_bf16 v[100:103], v[140:143], v[182:185], v[100:103]
	v_mfma_f32_16x16x32_bf16 v[92:95], v[124:127], v[208:211], v[92:95]
	v_mfma_f32_16x16x32_bf16 v[84:87], v[140:143], v[208:211], v[84:87]
	v_mfma_f32_16x16x32_bf16 v[76:79], v[124:127], v[216:219], v[76:79]
	v_mfma_f32_16x16x32_bf16 v[68:71], v[140:143], v[216:219], v[68:71]
	v_mfma_f32_16x16x32_bf16 v[128:131], v[144:147], v[160:163], v[128:131]
	v_mfma_f32_16x16x32_bf16 v[112:115], v[152:155], v[160:163], v[112:115]
	v_mfma_f32_16x16x32_bf16 v[104:107], v[144:147], v[178:181], v[104:107]
	v_mfma_f32_16x16x32_bf16 v[96:99], v[152:155], v[178:181], v[96:99]
	v_mfma_f32_16x16x32_bf16 v[88:91], v[144:147], v[204:207], v[88:91]
	v_mfma_f32_16x16x32_bf16 v[80:83], v[152:155], v[204:207], v[80:83]
	v_mfma_f32_16x16x32_bf16 v[72:75], v[144:147], v[212:215], v[72:75]
	v_mfma_f32_16x16x32_bf16 v[64:67], v[152:155], v[212:215], v[64:67]
	v_mfma_f32_16x16x32_bf16 v[128:131], v[148:151], v[164:167], v[128:131]
	v_mfma_f32_16x16x32_bf16 v[112:115], v[156:159], v[164:167], v[112:115]
	v_mfma_f32_16x16x32_bf16 v[104:107], v[148:151], v[182:185], v[104:107]
	v_mfma_f32_16x16x32_bf16 v[96:99], v[156:159], v[182:185], v[96:99]
	v_mfma_f32_16x16x32_bf16 v[88:91], v[148:151], v[208:211], v[88:91]
	v_mfma_f32_16x16x32_bf16 v[80:83], v[156:159], v[208:211], v[80:83]
	v_mfma_f32_16x16x32_bf16 v[72:75], v[148:151], v[216:219], v[72:75]
	v_mfma_f32_16x16x32_bf16 v[64:67], v[156:159], v[216:219], v[64:67]
	s_barrier
	s_add_i32 s47, s47, s30
	v_lshl_add_u64 v[186:187], s[22:23], 0, v[188:189]
	s_mov_b32 m0, s47
	ds_read_b128 v[160:163], v203 offset:16384
	ds_read_b128 v[164:167], v203 offset:17408
	ds_read_b128 v[178:181], v203 offset:18432
	ds_read_b128 v[182:185], v203 offset:19456
	ds_read_b128 v[204:207], v203 offset:20480
	ds_read_b128 v[208:211], v203 offset:21504
	ds_read_b128 v[212:215], v203 offset:22528
	ds_read_b128 v[216:219], v203 offset:23552
	global_load_lds_dwordx4 v[186:187], off
	s_add_i32 m0, s47, 0x2000
	s_add_u32 s48, s22, 0x200000
	v_lshl_add_u64 v[198:199], s[22:23], 0, v[168:169]
	s_addc_u32 s49, s23, 0
	s_add_i32 s47, s50, s30
	global_load_lds_dwordx4 v[198:199], off
	v_lshl_add_u64 v[220:221], s[48:49], 0, v[188:189]
	s_mov_b32 m0, s47
	v_lshl_add_u64 v[222:223], s[24:25], 0, v[170:171]
	global_load_lds_dwordx4 v[220:221], off
	v_lshl_add_u64 v[220:221], s[48:49], 0, v[168:169]
	s_add_i32 m0, s47, 0x2000
	s_nop 0
	global_load_lds_dwordx4 v[220:221], off
	v_lshl_add_u64 v[220:221], s[24:25], 0, v[172:173]
	s_mov_b32 m0, s31
	s_nop 0
	global_load_lds_dwordx4 v[220:221], off
	s_mov_b32 m0, s34
	s_nop 0
	global_load_lds_dwordx4 v[222:223], off
	s_waitcnt vmcnt(8)
	s_waitcnt lgkmcnt(0)
	s_barrier
; #define PG8_STAGE(bufoff, gbase, voff) do { _Pragma("unroll") for (int _i = 0; _i < 2; ++_i) \
;         __builtin_amdgcn_global_load_lds((const unsigned*)((const char*)(gbase) + (voff)[_i]), (LAS unsigned*)(lds + (bufoff) + ldsw + _i * 8192), 16, 0, 0); } while (0)
; #define PG8_LDA(dst, b, h) do { _Pragma("unroll") for (int m = 0; m < 4; ++m) _Pragma("unroll") for (int k = 0; k < 2; ++k) dst[m][k] = *(const LAS bf16x8*)(lds + PG8_SA(b, h) + aoff + m * 2048 + k * 1024); } while (0)
; #define PG8_LDB(dst, b, h) do { _Pragma("unroll") for (int n = 0; n < 2; ++n) _Pragma("unroll") for (int k = 0; k < 2; ++k) dst[n][k] = *(const LAS bf16x8*)(lds + PG8_SB(b, h) + boff + n * 2048 + k * 1024); } while (0)
; #define PG8_MMA(ai, bj, At, Bt) do { __builtin_amdgcn_s_setprio(1); _Pragma("unroll") for (int m = 0; m < 4; ++m) _Pragma("unroll") for (int n = 0; n < 2; ++n) _Pragma("unroll") for (int k = 0; k < 2; ++k) \
;         acc[ai][bj][m][n] = __builtin_amdgcn_mfma_f32_16x16x32_bf16(Bt[n][k], At[m][k], acc[ai][bj][m][n], 0, 0, 0); __builtin_amdgcn_s_setprio(0); } while (0)
; #define PG8_WAIT_V(n) asm volatile("s_waitcnt vmcnt(" #n ")" ::: "memory")
; #define PG8_WAIT_L(n) asm volatile("s_waitcnt lgkmcnt(" #n ")" ::: "memory")
; #define PG8_BAR __builtin_amdgcn_s_barrier()
; #define PG8_SCHED __builtin_amdgcn_sched_barrier(0)
; template <class Epi, class Sched>
; __device__ __forceinline__ void gemm_phase(int wv, LAS unsigned char* lds, const Gemm g, const Sched& S, const Epi& E) {
;     ...
;             PG8_WAIT_V(8); PG8_WAIT_L(0); PG8_BAR; PG8_MMA(1, 0, At, B0); PG8_MMA(1, 1, At, B1); PG8_BAR; PG8_SCHED;
;             PG8_LDB(B0, 1, 0); PG8_LDB(B1, 1, 1); PG8_SCHED; PG8_LDA(At, 1, 0); PG8_STAGE(PG8_SA(0, 1), a2 + hstep, voffA);
;             PG8_WAIT_V(8); PG8_WAIT_L(0); PG8_BAR; PG8_MMA(0, 0, At, B0); PG8_MMA(0, 1, At, B1); PG8_BAR; PG8_SCHED;
	s_waitcnt lgkmcnt(0)
	v_mfma_f32_16x16x32_bf16 v[60:63], v[120:123], v[160:163], v[60:63]
	v_mfma_f32_16x16x32_bf16 v[52:55], v[136:139], v[160:163], v[52:55]
	v_mfma_f32_16x16x32_bf16 v[44:47], v[120:123], v[178:181], v[44:47]
	v_mfma_f32_16x16x32_bf16 v[36:39], v[136:139], v[178:181], v[36:39]
	v_mfma_f32_16x16x32_bf16 v[28:31], v[120:123], v[204:207], v[28:31]
	v_mfma_f32_16x16x32_bf16 v[20:23], v[136:139], v[204:207], v[20:23]
	v_mfma_f32_16x16x32_bf16 v[12:15], v[120:123], v[212:215], v[12:15]
	v_mfma_f32_16x16x32_bf16 v[4:7], v[136:139], v[212:215], v[4:7]
	v_mfma_f32_16x16x32_bf16 v[60:63], v[124:127], v[164:167], v[60:63]
	v_mfma_f32_16x16x32_bf16 v[52:55], v[140:143], v[164:167], v[52:55]
	v_mfma_f32_16x16x32_bf16 v[44:47], v[124:127], v[182:185], v[44:47]
	v_mfma_f32_16x16x32_bf16 v[36:39], v[140:143], v[182:185], v[36:39]
	v_mfma_f32_16x16x32_bf16 v[28:31], v[124:127], v[208:211], v[28:31]
	v_mfma_f32_16x16x32_bf16 v[20:23], v[140:143], v[208:211], v[20:23]
	v_mfma_f32_16x16x32_bf16 v[12:15], v[124:127], v[216:219], v[12:15]
	v_mfma_f32_16x16x32_bf16 v[4:7], v[140:143], v[216:219], v[4:7]
	v_mfma_f32_16x16x32_bf16 v[56:59], v[144:147], v[160:163], v[56:59]
	v_mfma_f32_16x16x32_bf16 v[48:51], v[152:155], v[160:163], v[48:51]
	v_mfma_f32_16x16x32_bf16 v[40:43], v[144:147], v[178:181], v[40:43]
	v_mfma_f32_16x16x32_bf16 v[32:35], v[152:155], v[178:181], v[32:35]
	v_mfma_f32_16x16x32_bf16 v[24:27], v[144:147], v[204:207], v[24:27]
	v_mfma_f32_16x16x32_bf16 v[16:19], v[152:155], v[204:207], v[16:19]
	v_mfma_f32_16x16x32_bf16 v[8:11], v[144:147], v[212:215], v[8:11]
	v_mfma_f32_16x16x32_bf16 v[0:3], v[152:155], v[212:215], v[0:3]
	v_mfma_f32_16x16x32_bf16 v[56:59], v[148:151], v[164:167], v[56:59]
	v_mfma_f32_16x16x32_bf16 v[48:51], v[156:159], v[164:167], v[48:51]
	v_mfma_f32_16x16x32_bf16 v[40:43], v[148:151], v[182:185], v[40:43]
	v_mfma_f32_16x16x32_bf16 v[32:35], v[156:159], v[182:185], v[32:35]
	v_mfma_f32_16x16x32_bf16 v[24:27], v[148:151], v[208:211], v[24:27]
	v_mfma_f32_16x16x32_bf16 v[16:19], v[156:159], v[208:211], v[16:19]
	v_mfma_f32_16x16x32_bf16 v[8:11], v[148:151], v[216:219], v[8:11]
	v_mfma_f32_16x16x32_bf16 v[0:3], v[156:159], v[216:219], v[0:3]
	s_barrier
	s_add_i32 s47, 0, 0x1c000
	v_add_u32_e32 v140, s95, v201
	v_add_u32_e32 v156, s47, v201
	ds_read_b128 v[120:123], v140
	ds_read_b128 v[124:127], v140 offset:1024
	ds_read_b128 v[136:139], v140 offset:2048
	ds_read_b128 v[140:143], v140 offset:3072
	ds_read_b128 v[144:147], v156
	ds_read_b128 v[148:151], v156 offset:1024
	ds_read_b128 v[152:155], v156 offset:2048
	ds_read_b128 v[156:159], v156 offset:3072
	s_add_u32 s24, s24, 0x40000
	s_addc_u32 s25, s25, 0
	s_mov_b32 m0, s35
	v_lshl_add_u64 v[228:229], s[24:25], 0, v[172:173]
	ds_read_b128 v[160:163], v203 offset:32768
	ds_read_b128 v[164:167], v203 offset:33792
	ds_read_b128 v[178:181], v203 offset:34816
	ds_read_b128 v[182:185], v203 offset:35840
	ds_read_b128 v[204:207], v203 offset:36864
	ds_read_b128 v[208:211], v203 offset:37888
	ds_read_b128 v[212:215], v203 offset:38912
	ds_read_b128 v[216:219], v203 offset:39936
	global_load_lds_dwordx4 v[228:229], off
	v_lshl_add_u64 v[228:229], s[24:25], 0, v[170:171]
	s_mov_b32 m0, s36
	s_nop 0
	global_load_lds_dwordx4 v[228:229], off
	s_waitcnt vmcnt(8)
	s_waitcnt lgkmcnt(0)
	s_barrier
	s_waitcnt lgkmcnt(0)
	v_mfma_f32_16x16x32_bf16 v[132:135], v[120:123], v[160:163], v[132:135]
	v_mfma_f32_16x16x32_bf16 v[116:119], v[136:139], v[160:163], v[116:119]
	v_mfma_f32_16x16x32_bf16 v[108:111], v[120:123], v[178:181], v[108:111]
	v_mfma_f32_16x16x32_bf16 v[100:103], v[136:139], v[178:181], v[100:103]
	v_mfma_f32_16x16x32_bf16 v[92:95], v[120:123], v[204:207], v[92:95]
	v_mfma_f32_16x16x32_bf16 v[84:87], v[136:139], v[204:207], v[84:87]
	v_mfma_f32_16x16x32_bf16 v[76:79], v[120:123], v[212:215], v[76:79]
	v_mfma_f32_16x16x32_bf16 v[68:71], v[136:139], v[212:215], v[68:71]
	v_mfma_f32_16x16x32_bf16 v[132:135], v[124:127], v[164:167], v[132:135]
	v_mfma_f32_16x16x32_bf16 v[116:119], v[140:143], v[164:167], v[116:119]
	v_mfma_f32_16x16x32_bf16 v[108:111], v[124:127], v[182:185], v[108:111]
	v_mfma_f32_16x16x32_bf16 v[100:103], v[140:143], v[182:185], v[100:103]
	v_mfma_f32_16x16x32_bf16 v[92:95], v[124:127], v[208:211], v[92:95]
	v_mfma_f32_16x16x32_bf16 v[84:87], v[140:143], v[208:211], v[84:87]
	v_mfma_f32_16x16x32_bf16 v[76:79], v[124:127], v[216:219], v[76:79]
	v_mfma_f32_16x16x32_bf16 v[68:71], v[140:143], v[216:219], v[68:71]
	v_mfma_f32_16x16x32_bf16 v[128:131], v[144:147], v[160:163], v[128:131]
	v_mfma_f32_16x16x32_bf16 v[112:115], v[152:155], v[160:163], v[112:115]
	v_mfma_f32_16x16x32_bf16 v[104:107], v[144:147], v[178:181], v[104:107]
	v_mfma_f32_16x16x32_bf16 v[96:99], v[152:155], v[178:181], v[96:99]
	v_mfma_f32_16x16x32_bf16 v[88:91], v[144:147], v[204:207], v[88:91]
	v_mfma_f32_16x16x32_bf16 v[80:83], v[152:155], v[204:207], v[80:83]
	v_mfma_f32_16x16x32_bf16 v[72:75], v[144:147], v[212:215], v[72:75]
	v_mfma_f32_16x16x32_bf16 v[64:67], v[152:155], v[212:215], v[64:67]
	v_mfma_f32_16x16x32_bf16 v[128:131], v[148:151], v[164:167], v[128:131]
	v_mfma_f32_16x16x32_bf16 v[112:115], v[156:159], v[164:167], v[112:115]
	v_mfma_f32_16x16x32_bf16 v[104:107], v[148:151], v[182:185], v[104:107]
	v_mfma_f32_16x16x32_bf16 v[96:99], v[156:159], v[182:185], v[96:99]
	v_mfma_f32_16x16x32_bf16 v[88:91], v[148:151], v[208:211], v[88:91]
	v_mfma_f32_16x16x32_bf16 v[80:83], v[156:159], v[208:211], v[80:83]
	v_mfma_f32_16x16x32_bf16 v[72:75], v[148:151], v[216:219], v[72:75]
	v_mfma_f32_16x16x32_bf16 v[64:67], v[156:159], v[216:219], v[64:67]
	s_barrier
; #define PG8_STAGE(bufoff, gbase, voff) do { _Pragma("unroll") for (int _i = 0; _i < 2; ++_i) \
;         __builtin_amdgcn_global_load_lds((const unsigned*)((const char*)(gbase) + (voff)[_i]), (LAS unsigned*)(lds + (bufoff) + ldsw + _i * 8192), 16, 0, 0); } while (0)
; #define PG8_LDA(dst, b, h) do { _Pragma("unroll") for (int m = 0; m < 4; ++m) _Pragma("unroll") for (int k = 0; k < 2; ++k) dst[m][k] = *(const LAS bf16x8*)(lds + PG8_SA(b, h) + aoff + m * 2048 + k * 1024); } while (0)
; #define PG8_MMA(ai, bj, At, Bt) do { __builtin_amdgcn_s_setprio(1); _Pragma("unroll") for (int m = 0; m < 4; ++m) _Pragma("unroll") for (int n = 0; n < 2; ++n) _Pragma("unroll") for (int k = 0; k < 2; ++k) \
;         acc[ai][bj][m][n] = __builtin_amdgcn_mfma_f32_16x16x32_bf16(Bt[n][k], At[m][k], acc[ai][bj][m][n], 0, 0, 0); __builtin_amdgcn_s_setprio(0); } while (0)
; #define PG8_WAIT_V(n) asm volatile("s_waitcnt vmcnt(" #n ")" ::: "memory")
; #define PG8_WAIT_L(n) asm volatile("s_waitcnt lgkmcnt(" #n ")" ::: "memory")
; #define PG8_BAR __builtin_amdgcn_s_barrier()
; #define PG8_SCHED __builtin_amdgcn_sched_barrier(0)
; template <class Epi, class Sched>
; __device__ __forceinline__ void gemm_phase(int wv, LAS unsigned char* lds, const Gemm g, const Sched& S, const Epi& E) {
;     ...
;             PG8_LDA(At, 1, 1); PG8_STAGE(PG8_SB(1, 0), b3, voffB); PG8_STAGE(PG8_SB(1, 1), b3 + hstepB, voffB); PG8_STAGE(PG8_SA(1, 0), a3, voffA);
;             PG8_WAIT_V(8); PG8_WAIT_L(0); PG8_BAR; PG8_MMA(1, 0, At, B0); PG8_MMA(1, 1, At, B1); PG8_BAR; PG8_SCHED;
;         }
;         if (wr == 0) PG8_BAR;
	s_add_i32 s24, s95, s30
	v_lshl_add_u64 v[186:187], v[186:187], 0, s[74:75]
	s_mov_b32 m0, s24
	ds_read_b128 v[160:163], v203 offset:49152
	ds_read_b128 v[164:167], v203 offset:50176
	ds_read_b128 v[178:181], v203 offset:51200
	ds_read_b128 v[182:185], v203 offset:52224
	ds_read_b128 v[204:207], v203 offset:53248
	ds_read_b128 v[208:211], v203 offset:54272
	ds_read_b128 v[212:215], v203 offset:55296
	ds_read_b128 v[216:219], v203 offset:56320
	global_load_lds_dwordx4 v[186:187], off
	s_add_i32 m0, s24, 0x2000
	s_add_u32 s22, s22, 0x200080
	v_lshl_add_u64 v[186:187], v[198:199], 0, s[74:75]
	s_addc_u32 s23, s23, 0
	s_add_i32 s24, s47, s30
	global_load_lds_dwordx4 v[186:187], off
	v_lshl_add_u64 v[186:187], s[22:23], 0, v[188:189]
	s_mov_b32 m0, s24
	s_nop 0
	global_load_lds_dwordx4 v[186:187], off
	v_lshl_add_u64 v[186:187], s[22:23], 0, v[168:169]
	s_add_i32 m0, s24, 0x2000
	s_nop 0
	global_load_lds_dwordx4 v[186:187], off
	v_lshl_add_u64 v[186:187], v[220:221], 0, s[74:75]
	s_mov_b32 m0, s37
	s_nop 0
	global_load_lds_dwordx4 v[186:187], off
	v_lshl_add_u64 v[186:187], v[222:223], 0, s[74:75]
	s_mov_b32 m0, s38
	s_nop 0
	global_load_lds_dwordx4 v[186:187], off
	s_waitcnt vmcnt(8)
	s_waitcnt lgkmcnt(0)
	s_barrier
	s_waitcnt lgkmcnt(0)
	v_mfma_f32_16x16x32_bf16 v[60:63], v[120:123], v[160:163], v[60:63]
	v_mfma_f32_16x16x32_bf16 v[52:55], v[136:139], v[160:163], v[52:55]
	v_mfma_f32_16x16x32_bf16 v[44:47], v[120:123], v[178:181], v[44:47]
	v_mfma_f32_16x16x32_bf16 v[36:39], v[136:139], v[178:181], v[36:39]
	v_mfma_f32_16x16x32_bf16 v[28:31], v[120:123], v[204:207], v[28:31]
	v_mfma_f32_16x16x32_bf16 v[20:23], v[136:139], v[204:207], v[20:23]
	v_mfma_f32_16x16x32_bf16 v[12:15], v[120:123], v[212:215], v[12:15]
	v_mfma_f32_16x16x32_bf16 v[4:7], v[136:139], v[212:215], v[4:7]
	v_mfma_f32_16x16x32_bf16 v[60:63], v[124:127], v[164:167], v[60:63]
	v_mfma_f32_16x16x32_bf16 v[52:55], v[140:143], v[164:167], v[52:55]
	v_mfma_f32_16x16x32_bf16 v[44:47], v[124:127], v[182:185], v[44:47]
	v_mfma_f32_16x16x32_bf16 v[36:39], v[140:143], v[182:185], v[36:39]
	v_mfma_f32_16x16x32_bf16 v[28:31], v[124:127], v[208:211], v[28:31]
	v_mfma_f32_16x16x32_bf16 v[20:23], v[140:143], v[208:211], v[20:23]
	v_mfma_f32_16x16x32_bf16 v[12:15], v[124:127], v[216:219], v[12:15]
	v_mfma_f32_16x16x32_bf16 v[4:7], v[140:143], v[216:219], v[4:7]
	v_mfma_f32_16x16x32_bf16 v[56:59], v[144:147], v[160:163], v[56:59]
	v_mfma_f32_16x16x32_bf16 v[48:51], v[152:155], v[160:163], v[48:51]
	v_mfma_f32_16x16x32_bf16 v[40:43], v[144:147], v[178:181], v[40:43]
	v_mfma_f32_16x16x32_bf16 v[32:35], v[152:155], v[178:181], v[32:35]
	v_mfma_f32_16x16x32_bf16 v[24:27], v[144:147], v[204:207], v[24:27]
	v_mfma_f32_16x16x32_bf16 v[16:19], v[152:155], v[204:207], v[16:19]
	v_mfma_f32_16x16x32_bf16 v[8:11], v[144:147], v[212:215], v[8:11]
	v_mfma_f32_16x16x32_bf16 v[0:3], v[152:155], v[212:215], v[0:3]
	v_mfma_f32_16x16x32_bf16 v[56:59], v[148:151], v[164:167], v[56:59]
	v_mfma_f32_16x16x32_bf16 v[48:51], v[156:159], v[164:167], v[48:51]
	v_mfma_f32_16x16x32_bf16 v[40:43], v[148:151], v[182:185], v[40:43]
	v_mfma_f32_16x16x32_bf16 v[32:35], v[156:159], v[182:185], v[32:35]
	v_mfma_f32_16x16x32_bf16 v[24:27], v[148:151], v[208:211], v[24:27]
	v_mfma_f32_16x16x32_bf16 v[16:19], v[156:159], v[208:211], v[16:19]
	v_mfma_f32_16x16x32_bf16 v[8:11], v[148:151], v[216:219], v[8:11]
	v_mfma_f32_16x16x32_bf16 v[0:3], v[156:159], v[216:219], v[0:3]
	s_barrier
	s_add_i32 s46, s46, 2
	s_add_u32 s20, s20, 0x100
	s_addc_u32 s21, s21, 0
	s_add_u32 s44, s44, 0x100
	s_addc_u32 s45, s45, 0
	s_cmp_gt_u32 s46, 13
	s_cbranch_scc0 .LBB0_821
	s_and_b64 vcc, exec, s[10:11]
	s_cbranch_vccz .LBB0_824
	s_barrier

; #define PG8_STAGE(bufoff, gbase, voff) do { _Pragma("unroll") for (int _i = 0; _i < 2; ++_i) \
;         __builtin_amdgcn_global_load_lds((const unsigned*)((const char*)(gbase) + (voff)[_i]), (LAS unsigned*)(lds + (bufoff) + ldsw + _i * 8192), 16, 0, 0); } while (0)
; #define PG8_LDA(dst, b, h) do { _Pragma("unroll") for (int m = 0; m < 4; ++m) _Pragma("unroll") for (int k = 0; k < 2; ++k) dst[m][k] = *(const LAS bf16x8*)(lds + PG8_SA(b, h) + aoff + m * 2048 + k * 1024); } while (0)
; #define PG8_LDB(dst, b, h) do { _Pragma("unroll") for (int n = 0; n < 2; ++n) _Pragma("unroll") for (int k = 0; k < 2; ++k) dst[n][k] = *(const LAS bf16x8*)(lds + PG8_SB(b, h) + boff + n * 2048 + k * 1024); } while (0)
; #define PG8_MMA(ai, bj, At, Bt) do { __builtin_amdgcn_s_setprio(1); _Pragma("unroll") for (int m = 0; m < 4; ++m) _Pragma("unroll") for (int n = 0; n < 2; ++n) _Pragma("unroll") for (int k = 0; k < 2; ++k) \
;         acc[ai][bj][m][n] = __builtin_amdgcn_mfma_f32_16x16x32_bf16(Bt[n][k], At[m][k], acc[ai][bj][m][n], 0, 0, 0); __builtin_amdgcn_s_setprio(0); } while (0)
; #define PG8_WAIT_V(n) asm volatile("s_waitcnt vmcnt(" #n ")" ::: "memory")
; #define PG8_WAIT_L(n) asm volatile("s_waitcnt lgkmcnt(" #n ")" ::: "memory")
; #define PG8_BAR __builtin_amdgcn_s_barrier()
; #define PG8_SCHED __builtin_amdgcn_sched_barrier(0)
; template <class Epi, class Sched>
; __device__ __forceinline__ void gemm_phase(int wv, LAS unsigned char* lds, const Gemm g, const Sched& S, const Epi& E) {
;     ...
;             const bool last = (t == nt - 2);
;             const char* a1 = cA + (size_t)(t + 1) * kstep;
;             const char* a2 = last ? nA : cA + (size_t)(t + 2) * kstep; const char* b2 = last ? nB : cB + (size_t)(t + 2) * kstep;
;             const char* a3 = a2 + kstep; const char* b3 = b2 + kstep;
;             PG8_LDB(B0, 0, 0); PG8_LDB(B1, 0, 1); PG8_SCHED; PG8_LDA(At, 0, 0); PG8_STAGE(PG8_SA(1, 1), a1 + hstep, voffA);
;             PG8_WAIT_V(8); PG8_WAIT_L(0); PG8_BAR; PG8_MMA(0, 0, At, B0); PG8_MMA(0, 1, At, B1); PG8_BAR; PG8_SCHED;
;             PG8_LDA(At, 0, 1); PG8_STAGE(PG8_SB(0, 0), b2, voffB); PG8_STAGE(PG8_SB(0, 1), b2 + hstepB, voffB); PG8_STAGE(PG8_SA(0, 0), a2, voffA);
;             PG8_WAIT_V(8); PG8_WAIT_L(0); PG8_BAR; PG8_MMA(1, 0, At, B0); PG8_MMA(1, 1, At, B1); PG8_BAR; PG8_SCHED;
.LBB0_893:
	s_add_u32 s26, s24, 0xfffc0080
	s_addc_u32 s27, s25, -1
	s_add_i32 s50, 0, 0x10000
	s_cmp_eq_u32 s49, 12
	s_cselect_b32 s29, s17, s27
	s_cselect_b32 s28, s45, s26
	s_cselect_b32 s27, s19, s48
	s_cselect_b32 s26, s46, s47
	s_add_i32 s52, 0, 0x14000
	v_add_u32_e32 v124, s50, v240
	v_add_u32_e32 v156, s52, v240
	ds_read_b128 v[112:115], v124
	ds_read_b128 v[116:119], v124 offset:1024
	ds_read_b128 v[120:123], v124 offset:2048
	ds_read_b128 v[124:127], v124 offset:3072
	ds_read_b128 v[128:131], v156
	ds_read_b128 v[140:143], v156 offset:1024
	ds_read_b128 v[152:155], v156 offset:2048
	ds_read_b128 v[156:159], v156 offset:3072
	v_lshl_add_u64 v[212:213], s[24:25], 0, v[204:205]
	s_add_i32 m0, s37, 0xc000
	ds_read_b128 v[160:163], v244
	ds_read_b128 v[164:167], v244 offset:1024
	ds_read_b128 v[168:171], v244 offset:2048
	ds_read_b128 v[172:175], v244 offset:3072
	ds_read_b128 v[176:179], v244 offset:4096
	ds_read_b128 v[180:183], v244 offset:5120
	ds_read_b128 v[184:187], v244 offset:6144
	ds_read_b128 v[208:211], v244 offset:7168
	global_load_lds_dwordx4 v[212:213], off
	v_lshl_add_u64 v[212:213], s[24:25], 0, v[206:207]
	s_add_i32 m0, s37, 0xe000
	s_nop 0
	global_load_lds_dwordx4 v[212:213], off
	s_waitcnt vmcnt(8)
	s_waitcnt lgkmcnt(0)
	s_barrier
	s_waitcnt lgkmcnt(0)
	v_mfma_f32_16x16x32_bf16 v[148:151], v[112:115], v[160:163], v[148:151]
	v_mfma_f32_16x16x32_bf16 v[144:147], v[120:123], v[160:163], v[144:147]
	v_mfma_f32_16x16x32_bf16 v[108:111], v[112:115], v[168:171], v[108:111]
	v_mfma_f32_16x16x32_bf16 v[104:107], v[120:123], v[168:171], v[104:107]
	v_mfma_f32_16x16x32_bf16 v[92:95], v[112:115], v[176:179], v[92:95]
	v_mfma_f32_16x16x32_bf16 v[88:91], v[120:123], v[176:179], v[88:91]
	v_mfma_f32_16x16x32_bf16 v[76:79], v[112:115], v[184:187], v[76:79]
	v_mfma_f32_16x16x32_bf16 v[72:75], v[120:123], v[184:187], v[72:75]
	v_mfma_f32_16x16x32_bf16 v[148:151], v[116:119], v[164:167], v[148:151]
	v_mfma_f32_16x16x32_bf16 v[144:147], v[124:127], v[164:167], v[144:147]
	v_mfma_f32_16x16x32_bf16 v[108:111], v[116:119], v[172:175], v[108:111]
	v_mfma_f32_16x16x32_bf16 v[104:107], v[124:127], v[172:175], v[104:107]
	v_mfma_f32_16x16x32_bf16 v[92:95], v[116:119], v[180:183], v[92:95]
	v_mfma_f32_16x16x32_bf16 v[88:91], v[124:127], v[180:183], v[88:91]
	v_mfma_f32_16x16x32_bf16 v[76:79], v[116:119], v[208:211], v[76:79]
	v_mfma_f32_16x16x32_bf16 v[72:75], v[124:127], v[208:211], v[72:75]
	v_mfma_f32_16x16x32_bf16 v[136:139], v[128:131], v[160:163], v[136:139]
	v_mfma_f32_16x16x32_bf16 v[132:135], v[152:155], v[160:163], v[132:135]
	v_mfma_f32_16x16x32_bf16 v[100:103], v[128:131], v[168:171], v[100:103]
	v_mfma_f32_16x16x32_bf16 v[96:99], v[152:155], v[168:171], v[96:99]
	v_mfma_f32_16x16x32_bf16 v[84:87], v[128:131], v[176:179], v[84:87]
	v_mfma_f32_16x16x32_bf16 v[80:83], v[152:155], v[176:179], v[80:83]
	v_mfma_f32_16x16x32_bf16 v[68:71], v[128:131], v[184:187], v[68:71]
	v_mfma_f32_16x16x32_bf16 v[64:67], v[152:155], v[184:187], v[64:67]
	v_mfma_f32_16x16x32_bf16 v[136:139], v[140:143], v[164:167], v[136:139]
	v_mfma_f32_16x16x32_bf16 v[132:135], v[156:159], v[164:167], v[132:135]
	v_mfma_f32_16x16x32_bf16 v[100:103], v[140:143], v[172:175], v[100:103]
	v_mfma_f32_16x16x32_bf16 v[96:99], v[156:159], v[172:175], v[96:99]
	v_mfma_f32_16x16x32_bf16 v[84:87], v[140:143], v[180:183], v[84:87]
	v_mfma_f32_16x16x32_bf16 v[80:83], v[156:159], v[180:183], v[80:83]
	v_mfma_f32_16x16x32_bf16 v[68:71], v[140:143], v[208:211], v[68:71]
	v_mfma_f32_16x16x32_bf16 v[64:67], v[156:159], v[208:211], v[64:67]
	s_barrier
	s_add_i32 s50, s50, s36
	v_lshl_add_u64 v[212:213], s[26:27], 0, v[188:189]
	s_mov_b32 m0, s50
	ds_read_b128 v[160:163], v244 offset:16384
	ds_read_b128 v[164:167], v244 offset:17408
	ds_read_b128 v[168:171], v244 offset:18432
	ds_read_b128 v[172:175], v244 offset:19456
	ds_read_b128 v[176:179], v244 offset:20480
	ds_read_b128 v[180:183], v244 offset:21504
	ds_read_b128 v[184:187], v244 offset:22528
	ds_read_b128 v[208:211], v244 offset:23552
	global_load_lds_dwordx4 v[212:213], off
	s_add_i32 m0, s50, 0x2000
	s_add_u32 s50, s26, 0x4000
	v_lshl_add_u64 v[214:215], s[26:27], 0, v[198:199]
	s_addc_u32 s51, s27, 0
	s_add_i32 s52, s52, s36
	global_load_lds_dwordx4 v[214:215], off
	v_lshl_add_u64 v[216:217], s[50:51], 0, v[188:189]
	s_mov_b32 m0, s52
	v_lshl_add_u64 v[218:219], s[28:29], 0, v[200:201]
	global_load_lds_dwordx4 v[216:217], off
	v_lshl_add_u64 v[216:217], s[50:51], 0, v[198:199]
	s_add_i32 m0, s52, 0x2000
	s_nop 0
	global_load_lds_dwordx4 v[216:217], off
	v_lshl_add_u64 v[216:217], s[28:29], 0, v[202:203]
	s_mov_b32 m0, s37
	s_nop 0
	global_load_lds_dwordx4 v[216:217], off
	s_mov_b32 m0, s38
	s_nop 0
	global_load_lds_dwordx4 v[218:219], off
	s_waitcnt vmcnt(8)
	s_waitcnt lgkmcnt(0)
	s_barrier
; #define PG8_STAGE(bufoff, gbase, voff) do { _Pragma("unroll") for (int _i = 0; _i < 2; ++_i) \
;         __builtin_amdgcn_global_load_lds((const unsigned*)((const char*)(gbase) + (voff)[_i]), (LAS unsigned*)(lds + (bufoff) + ldsw + _i * 8192), 16, 0, 0); } while (0)
; #define PG8_LDA(dst, b, h) do { _Pragma("unroll") for (int m = 0; m < 4; ++m) _Pragma("unroll") for (int k = 0; k < 2; ++k) dst[m][k] = *(const LAS bf16x8*)(lds + PG8_SA(b, h) + aoff + m * 2048 + k * 1024); } while (0)
; #define PG8_LDB(dst, b, h) do { _Pragma("unroll") for (int n = 0; n < 2; ++n) _Pragma("unroll") for (int k = 0; k < 2; ++k) dst[n][k] = *(const LAS bf16x8*)(lds + PG8_SB(b, h) + boff + n * 2048 + k * 1024); } while (0)
; #define PG8_MMA(ai, bj, At, Bt) do { __builtin_amdgcn_s_setprio(1); _Pragma("unroll") for (int m = 0; m < 4; ++m) _Pragma("unroll") for (int n = 0; n < 2; ++n) _Pragma("unroll") for (int k = 0; k < 2; ++k) \
;         acc[ai][bj][m][n] = __builtin_amdgcn_mfma_f32_16x16x32_bf16(Bt[n][k], At[m][k], acc[ai][bj][m][n], 0, 0, 0); __builtin_amdgcn_s_setprio(0); } while (0)
; #define PG8_WAIT_V(n) asm volatile("s_waitcnt vmcnt(" #n ")" ::: "memory")
; #define PG8_WAIT_L(n) asm volatile("s_waitcnt lgkmcnt(" #n ")" ::: "memory")
; #define PG8_BAR __builtin_amdgcn_s_barrier()
; #define PG8_SCHED __builtin_amdgcn_sched_barrier(0)
; template <class Epi, class Sched>
; __device__ __forceinline__ void gemm_phase(int wv, LAS unsigned char* lds, const Gemm g, const Sched& S, const Epi& E) {
;     ...
;             PG8_WAIT_V(8); PG8_WAIT_L(0); PG8_BAR; PG8_MMA(1, 0, At, B0); PG8_MMA(1, 1, At, B1); PG8_BAR; PG8_SCHED;
;             PG8_LDB(B0, 1, 0); PG8_LDB(B1, 1, 1); PG8_SCHED; PG8_LDA(At, 1, 0); PG8_STAGE(PG8_SA(0, 1), a2 + hstep, voffA);
;             PG8_WAIT_V(8); PG8_WAIT_L(0); PG8_BAR; PG8_MMA(0, 0, At, B0); PG8_MMA(0, 1, At, B1); PG8_BAR; PG8_SCHED;
	s_waitcnt lgkmcnt(0)
	v_mfma_f32_16x16x32_bf16 v[60:63], v[112:115], v[160:163], v[60:63]
	v_mfma_f32_16x16x32_bf16 v[56:59], v[120:123], v[160:163], v[56:59]
	v_mfma_f32_16x16x32_bf16 v[44:47], v[112:115], v[168:171], v[44:47]
	v_mfma_f32_16x16x32_bf16 v[40:43], v[120:123], v[168:171], v[40:43]
	v_mfma_f32_16x16x32_bf16 v[28:31], v[112:115], v[176:179], v[28:31]
	v_mfma_f32_16x16x32_bf16 v[24:27], v[120:123], v[176:179], v[24:27]
	v_mfma_f32_16x16x32_bf16 v[12:15], v[112:115], v[184:187], v[12:15]
	v_mfma_f32_16x16x32_bf16 v[8:11], v[120:123], v[184:187], v[8:11]
	v_mfma_f32_16x16x32_bf16 v[60:63], v[116:119], v[164:167], v[60:63]
	v_mfma_f32_16x16x32_bf16 v[56:59], v[124:127], v[164:167], v[56:59]
	v_mfma_f32_16x16x32_bf16 v[44:47], v[116:119], v[172:175], v[44:47]
	v_mfma_f32_16x16x32_bf16 v[40:43], v[124:127], v[172:175], v[40:43]
	v_mfma_f32_16x16x32_bf16 v[28:31], v[116:119], v[180:183], v[28:31]
	v_mfma_f32_16x16x32_bf16 v[24:27], v[124:127], v[180:183], v[24:27]
	v_mfma_f32_16x16x32_bf16 v[12:15], v[116:119], v[208:211], v[12:15]
	v_mfma_f32_16x16x32_bf16 v[8:11], v[124:127], v[208:211], v[8:11]
	v_mfma_f32_16x16x32_bf16 v[52:55], v[128:131], v[160:163], v[52:55]
	v_mfma_f32_16x16x32_bf16 v[48:51], v[152:155], v[160:163], v[48:51]
	v_mfma_f32_16x16x32_bf16 v[36:39], v[128:131], v[168:171], v[36:39]
	v_mfma_f32_16x16x32_bf16 v[32:35], v[152:155], v[168:171], v[32:35]
	v_mfma_f32_16x16x32_bf16 v[20:23], v[128:131], v[176:179], v[20:23]
	v_mfma_f32_16x16x32_bf16 v[16:19], v[152:155], v[176:179], v[16:19]
	v_mfma_f32_16x16x32_bf16 v[4:7], v[128:131], v[184:187], v[4:7]
	v_mfma_f32_16x16x32_bf16 v[0:3], v[152:155], v[184:187], v[0:3]
	v_mfma_f32_16x16x32_bf16 v[52:55], v[140:143], v[164:167], v[52:55]
	v_mfma_f32_16x16x32_bf16 v[48:51], v[156:159], v[164:167], v[48:51]
	v_mfma_f32_16x16x32_bf16 v[36:39], v[140:143], v[172:175], v[36:39]
	v_mfma_f32_16x16x32_bf16 v[32:35], v[156:159], v[172:175], v[32:35]
	v_mfma_f32_16x16x32_bf16 v[20:23], v[140:143], v[180:183], v[20:23]
	v_mfma_f32_16x16x32_bf16 v[16:19], v[156:159], v[180:183], v[16:19]
	v_mfma_f32_16x16x32_bf16 v[4:7], v[140:143], v[208:211], v[4:7]
	v_mfma_f32_16x16x32_bf16 v[0:3], v[156:159], v[208:211], v[0:3]
	s_barrier
	s_add_i32 s50, 0, 0x1c000
	v_add_u32_e32 v124, s95, v240
	v_add_u32_e32 v156, s50, v240
	ds_read_b128 v[112:115], v124
	ds_read_b128 v[116:119], v124 offset:1024
	ds_read_b128 v[120:123], v124 offset:2048
	ds_read_b128 v[124:127], v124 offset:3072
	ds_read_b128 v[128:131], v156
	ds_read_b128 v[140:143], v156 offset:1024
	ds_read_b128 v[152:155], v156 offset:2048
	ds_read_b128 v[156:159], v156 offset:3072
	s_add_u32 s28, s28, 0x40000
	s_addc_u32 s29, s29, 0
	s_mov_b32 m0, s39
	v_lshl_add_u64 v[220:221], s[28:29], 0, v[202:203]
	ds_read_b128 v[160:163], v244 offset:32768
	ds_read_b128 v[164:167], v244 offset:33792
	ds_read_b128 v[168:171], v244 offset:34816
	ds_read_b128 v[172:175], v244 offset:35840
	ds_read_b128 v[176:179], v244 offset:36864
	ds_read_b128 v[180:183], v244 offset:37888
	ds_read_b128 v[184:187], v244 offset:38912
	ds_read_b128 v[208:211], v244 offset:39936
	global_load_lds_dwordx4 v[220:221], off
	v_lshl_add_u64 v[220:221], s[28:29], 0, v[200:201]
	s_mov_b32 m0, s40
	s_nop 0
	global_load_lds_dwordx4 v[220:221], off
	s_waitcnt vmcnt(8)
	s_waitcnt lgkmcnt(0)
	s_barrier
	s_waitcnt lgkmcnt(0)
	v_mfma_f32_16x16x32_bf16 v[148:151], v[112:115], v[160:163], v[148:151]
	v_mfma_f32_16x16x32_bf16 v[144:147], v[120:123], v[160:163], v[144:147]
	v_mfma_f32_16x16x32_bf16 v[108:111], v[112:115], v[168:171], v[108:111]
	v_mfma_f32_16x16x32_bf16 v[104:107], v[120:123], v[168:171], v[104:107]
	v_mfma_f32_16x16x32_bf16 v[92:95], v[112:115], v[176:179], v[92:95]
	v_mfma_f32_16x16x32_bf16 v[88:91], v[120:123], v[176:179], v[88:91]
	v_mfma_f32_16x16x32_bf16 v[76:79], v[112:115], v[184:187], v[76:79]
	v_mfma_f32_16x16x32_bf16 v[72:75], v[120:123], v[184:187], v[72:75]
	v_mfma_f32_16x16x32_bf16 v[148:151], v[116:119], v[164:167], v[148:151]
	v_mfma_f32_16x16x32_bf16 v[144:147], v[124:127], v[164:167], v[144:147]
	v_mfma_f32_16x16x32_bf16 v[108:111], v[116:119], v[172:175], v[108:111]
	v_mfma_f32_16x16x32_bf16 v[104:107], v[124:127], v[172:175], v[104:107]
	v_mfma_f32_16x16x32_bf16 v[92:95], v[116:119], v[180:183], v[92:95]
	v_mfma_f32_16x16x32_bf16 v[88:91], v[124:127], v[180:183], v[88:91]
	v_mfma_f32_16x16x32_bf16 v[76:79], v[116:119], v[208:211], v[76:79]
	v_mfma_f32_16x16x32_bf16 v[72:75], v[124:127], v[208:211], v[72:75]
	v_mfma_f32_16x16x32_bf16 v[136:139], v[128:131], v[160:163], v[136:139]
	v_mfma_f32_16x16x32_bf16 v[132:135], v[152:155], v[160:163], v[132:135]
	v_mfma_f32_16x16x32_bf16 v[100:103], v[128:131], v[168:171], v[100:103]
	v_mfma_f32_16x16x32_bf16 v[96:99], v[152:155], v[168:171], v[96:99]
	v_mfma_f32_16x16x32_bf16 v[84:87], v[128:131], v[176:179], v[84:87]
	v_mfma_f32_16x16x32_bf16 v[80:83], v[152:155], v[176:179], v[80:83]
	v_mfma_f32_16x16x32_bf16 v[68:71], v[128:131], v[184:187], v[68:71]
	v_mfma_f32_16x16x32_bf16 v[64:67], v[152:155], v[184:187], v[64:67]
	v_mfma_f32_16x16x32_bf16 v[136:139], v[140:143], v[164:167], v[136:139]
	v_mfma_f32_16x16x32_bf16 v[132:135], v[156:159], v[164:167], v[132:135]
	v_mfma_f32_16x16x32_bf16 v[100:103], v[140:143], v[172:175], v[100:103]
	v_mfma_f32_16x16x32_bf16 v[96:99], v[156:159], v[172:175], v[96:99]
	v_mfma_f32_16x16x32_bf16 v[84:87], v[140:143], v[180:183], v[84:87]
	v_mfma_f32_16x16x32_bf16 v[80:83], v[156:159], v[180:183], v[80:83]
	v_mfma_f32_16x16x32_bf16 v[68:71], v[140:143], v[208:211], v[68:71]
	v_mfma_f32_16x16x32_bf16 v[64:67], v[156:159], v[208:211], v[64:67]
	s_barrier
; #define PG8_STAGE(bufoff, gbase, voff) do { _Pragma("unroll") for (int _i = 0; _i < 2; ++_i) \
;         __builtin_amdgcn_global_load_lds((const unsigned*)((const char*)(gbase) + (voff)[_i]), (LAS unsigned*)(lds + (bufoff) + ldsw + _i * 8192), 16, 0, 0); } while (0)
; #define PG8_LDA(dst, b, h) do { _Pragma("unroll") for (int m = 0; m < 4; ++m) _Pragma("unroll") for (int k = 0; k < 2; ++k) dst[m][k] = *(const LAS bf16x8*)(lds + PG8_SA(b, h) + aoff + m * 2048 + k * 1024); } while (0)
; #define PG8_MMA(ai, bj, At, Bt) do { __builtin_amdgcn_s_setprio(1); _Pragma("unroll") for (int m = 0; m < 4; ++m) _Pragma("unroll") for (int n = 0; n < 2; ++n) _Pragma("unroll") for (int k = 0; k < 2; ++k) \
;         acc[ai][bj][m][n] = __builtin_amdgcn_mfma_f32_16x16x32_bf16(Bt[n][k], At[m][k], acc[ai][bj][m][n], 0, 0, 0); __builtin_amdgcn_s_setprio(0); } while (0)
; #define PG8_WAIT_V(n) asm volatile("s_waitcnt vmcnt(" #n ")" ::: "memory")
; #define PG8_WAIT_L(n) asm volatile("s_waitcnt lgkmcnt(" #n ")" ::: "memory")
; #define PG8_BAR __builtin_amdgcn_s_barrier()
; #define PG8_SCHED __builtin_amdgcn_sched_barrier(0)
; template <class Epi, class Sched>
; __device__ __forceinline__ void gemm_phase(int wv, LAS unsigned char* lds, const Gemm g, const Sched& S, const Epi& E) {
;     ...
;             PG8_LDA(At, 1, 1); PG8_STAGE(PG8_SB(1, 0), b3, voffB); PG8_STAGE(PG8_SB(1, 1), b3 + hstepB, voffB); PG8_STAGE(PG8_SA(1, 0), a3, voffA);
;             PG8_WAIT_V(8); PG8_WAIT_L(0); PG8_BAR; PG8_MMA(1, 0, At, B0); PG8_MMA(1, 1, At, B1); PG8_BAR; PG8_SCHED;
;         }
;         if (wr == 0) PG8_BAR;
	s_add_i32 s28, s95, s36
	v_lshl_add_u64 v[212:213], v[212:213], 0, s[74:75]
	s_mov_b32 m0, s28
	ds_read_b128 v[160:163], v244 offset:49152
	ds_read_b128 v[164:167], v244 offset:50176
	ds_read_b128 v[168:171], v244 offset:51200
	ds_read_b128 v[172:175], v244 offset:52224
	ds_read_b128 v[176:179], v244 offset:53248
	ds_read_b128 v[180:183], v244 offset:54272
	ds_read_b128 v[184:187], v244 offset:55296
	ds_read_b128 v[208:211], v244 offset:56320
	global_load_lds_dwordx4 v[212:213], off
	s_add_i32 m0, s28, 0x2000
	s_add_u32 s26, s26, 0x4080
	v_lshl_add_u64 v[212:213], v[214:215], 0, s[74:75]
	s_addc_u32 s27, s27, 0
	s_add_i32 s28, s50, s36
	global_load_lds_dwordx4 v[212:213], off
	v_lshl_add_u64 v[212:213], s[26:27], 0, v[188:189]
	s_mov_b32 m0, s28
	s_nop 0
	global_load_lds_dwordx4 v[212:213], off
	v_lshl_add_u64 v[212:213], s[26:27], 0, v[198:199]
	s_add_i32 m0, s28, 0x2000
	s_nop 0
	global_load_lds_dwordx4 v[212:213], off
	v_lshl_add_u64 v[212:213], v[216:217], 0, s[74:75]
	s_mov_b32 m0, s41
	s_nop 0
	global_load_lds_dwordx4 v[212:213], off
	v_lshl_add_u64 v[212:213], v[218:219], 0, s[74:75]
	s_mov_b32 m0, s42
	s_nop 0
	global_load_lds_dwordx4 v[212:213], off
	s_waitcnt vmcnt(8)
	s_waitcnt lgkmcnt(0)
	s_barrier
	s_waitcnt lgkmcnt(0)
	v_mfma_f32_16x16x32_bf16 v[60:63], v[112:115], v[160:163], v[60:63]
	v_mfma_f32_16x16x32_bf16 v[56:59], v[120:123], v[160:163], v[56:59]
	v_mfma_f32_16x16x32_bf16 v[44:47], v[112:115], v[168:171], v[44:47]
	v_mfma_f32_16x16x32_bf16 v[40:43], v[120:123], v[168:171], v[40:43]
	v_mfma_f32_16x16x32_bf16 v[28:31], v[112:115], v[176:179], v[28:31]
	v_mfma_f32_16x16x32_bf16 v[24:27], v[120:123], v[176:179], v[24:27]
	v_mfma_f32_16x16x32_bf16 v[12:15], v[112:115], v[184:187], v[12:15]
	v_mfma_f32_16x16x32_bf16 v[8:11], v[120:123], v[184:187], v[8:11]
	v_mfma_f32_16x16x32_bf16 v[60:63], v[116:119], v[164:167], v[60:63]
	v_mfma_f32_16x16x32_bf16 v[56:59], v[124:127], v[164:167], v[56:59]
	v_mfma_f32_16x16x32_bf16 v[44:47], v[116:119], v[172:175], v[44:47]
	v_mfma_f32_16x16x32_bf16 v[40:43], v[124:127], v[172:175], v[40:43]
	v_mfma_f32_16x16x32_bf16 v[28:31], v[116:119], v[180:183], v[28:31]
	v_mfma_f32_16x16x32_bf16 v[24:27], v[124:127], v[180:183], v[24:27]
	v_mfma_f32_16x16x32_bf16 v[12:15], v[116:119], v[208:211], v[12:15]
	v_mfma_f32_16x16x32_bf16 v[8:11], v[124:127], v[208:211], v[8:11]
	v_mfma_f32_16x16x32_bf16 v[52:55], v[128:131], v[160:163], v[52:55]
	v_mfma_f32_16x16x32_bf16 v[48:51], v[152:155], v[160:163], v[48:51]
	v_mfma_f32_16x16x32_bf16 v[36:39], v[128:131], v[168:171], v[36:39]
	v_mfma_f32_16x16x32_bf16 v[32:35], v[152:155], v[168:171], v[32:35]
	v_mfma_f32_16x16x32_bf16 v[20:23], v[128:131], v[176:179], v[20:23]
	v_mfma_f32_16x16x32_bf16 v[16:19], v[152:155], v[176:179], v[16:19]
	v_mfma_f32_16x16x32_bf16 v[4:7], v[128:131], v[184:187], v[4:7]
	v_mfma_f32_16x16x32_bf16 v[0:3], v[152:155], v[184:187], v[0:3]
	v_mfma_f32_16x16x32_bf16 v[52:55], v[140:143], v[164:167], v[52:55]
	v_mfma_f32_16x16x32_bf16 v[48:51], v[156:159], v[164:167], v[48:51]
	v_mfma_f32_16x16x32_bf16 v[36:39], v[140:143], v[172:175], v[36:39]
	v_mfma_f32_16x16x32_bf16 v[32:35], v[156:159], v[172:175], v[32:35]
	v_mfma_f32_16x16x32_bf16 v[20:23], v[140:143], v[180:183], v[20:23]
	v_mfma_f32_16x16x32_bf16 v[16:19], v[156:159], v[180:183], v[16:19]
	v_mfma_f32_16x16x32_bf16 v[4:7], v[140:143], v[208:211], v[4:7]
	v_mfma_f32_16x16x32_bf16 v[0:3], v[156:159], v[208:211], v[0:3]
	s_barrier
	s_add_i32 s49, s49, 2
	s_add_u32 s24, s24, 0x100
	s_addc_u32 s25, s25, 0
	s_add_u32 s47, s47, 0x100
	s_addc_u32 s48, s48, 0
	s_cmp_gt_u32 s49, 13
	s_cbranch_scc0 .LBB0_893
	s_and_b64 vcc, exec, s[14:15]
	s_cbranch_vccz .LBB0_896
	s_barrier

; #define PG8_STAGE(bufoff, gbase, voff) do { _Pragma("unroll") for (int _i = 0; _i < 2; ++_i) \
;         __builtin_amdgcn_global_load_lds((const unsigned*)((const char*)(gbase) + (voff)[_i]), (LAS unsigned*)(lds + (bufoff) + ldsw + _i * 8192), 16, 0, 0); } while (0)
; #define PG8_LDA(dst, b, h) do { _Pragma("unroll") for (int m = 0; m < 4; ++m) _Pragma("unroll") for (int k = 0; k < 2; ++k) dst[m][k] = *(const LAS bf16x8*)(lds + PG8_SA(b, h) + aoff + m * 2048 + k * 1024); } while (0)
; #define PG8_LDB(dst, b, h) do { _Pragma("unroll") for (int n = 0; n < 2; ++n) _Pragma("unroll") for (int k = 0; k < 2; ++k) dst[n][k] = *(const LAS bf16x8*)(lds + PG8_SB(b, h) + boff + n * 2048 + k * 1024); } while (0)
; #define PG8_MMA(ai, bj, At, Bt) do { __builtin_amdgcn_s_setprio(1); _Pragma("unroll") for (int m = 0; m < 4; ++m) _Pragma("unroll") for (int n = 0; n < 2; ++n) _Pragma("unroll") for (int k = 0; k < 2; ++k) \
;         acc[ai][bj][m][n] = __builtin_amdgcn_mfma_f32_16x16x32_bf16(Bt[n][k], At[m][k], acc[ai][bj][m][n], 0, 0, 0); __builtin_amdgcn_s_setprio(0); } while (0)
; #define PG8_WAIT_V(n) asm volatile("s_waitcnt vmcnt(" #n ")" ::: "memory")
; #define PG8_WAIT_L(n) asm volatile("s_waitcnt lgkmcnt(" #n ")" ::: "memory")
; #define PG8_BAR __builtin_amdgcn_s_barrier()
; #define PG8_SCHED __builtin_amdgcn_sched_barrier(0)
; template <class Epi, class Sched>
; __device__ __forceinline__ void gemm_phase(int wv, LAS unsigned char* lds, const Gemm g, const Sched& S, const Epi& E) {
;     ...
;             const bool last = (t == nt - 2);
;             const char* a1 = cA + (size_t)(t + 1) * kstep;
;             const char* a2 = last ? nA : cA + (size_t)(t + 2) * kstep; const char* b2 = last ? nB : cB + (size_t)(t + 2) * kstep;
;             const char* a3 = a2 + kstep; const char* b3 = b2 + kstep;
;             PG8_LDB(B0, 0, 0); PG8_LDB(B1, 0, 1); PG8_SCHED; PG8_LDA(At, 0, 0); PG8_STAGE(PG8_SA(1, 1), a1 + hstep, voffA);
;             PG8_WAIT_V(8); PG8_WAIT_L(0); PG8_BAR; PG8_MMA(0, 0, At, B0); PG8_MMA(0, 1, At, B1); PG8_BAR; PG8_SCHED;
;             PG8_LDA(At, 0, 1); PG8_STAGE(PG8_SB(0, 0), b2, voffB); PG8_STAGE(PG8_SB(0, 1), b2 + hstepB, voffB); PG8_STAGE(PG8_SA(0, 0), a2, voffA);
;             PG8_WAIT_V(8); PG8_WAIT_L(0); PG8_BAR; PG8_MMA(1, 0, At, B0); PG8_MMA(1, 1, At, B1); PG8_BAR; PG8_SCHED;
.LBB0_978:
	s_add_u32 s20, s18, 0xfffc0080
	s_addc_u32 s21, s19, -1
	s_add_i32 s44, 0, 0x10000
	s_cmp_eq_u32 s43, 12
	s_cselect_b32 s23, s11, s21
	s_cselect_b32 s22, s39, s20
	s_cselect_b32 s21, s13, s42
	s_cselect_b32 s20, s40, s41
	s_add_i32 s46, 0, 0x14000
	v_add_u32_e32 v154, s44, v143
	v_add_u32_e32 v170, s46, v143
	ds_read_b128 v[138:141], v154
	ds_read_b128 v[146:149], v154 offset:1024
	ds_read_b128 v[150:153], v154 offset:2048
	ds_read_b128 v[154:157], v154 offset:3072
	ds_read_b128 v[158:161], v170
	ds_read_b128 v[162:165], v170 offset:1024
	ds_read_b128 v[166:169], v170 offset:2048
	ds_read_b128 v[170:173], v170 offset:3072
	v_lshl_add_u64 v[186:187], s[18:19], 0, v[134:135]
	s_add_i32 m0, s29, 0xc000
	ds_read_b128 v[174:177], v145
	ds_read_b128 v[178:181], v145 offset:1024
	ds_read_b128 v[182:185], v145 offset:2048
	ds_read_b128 v[198:201], v145 offset:3072
	ds_read_b128 v[202:205], v145 offset:4096
	ds_read_b128 v[206:209], v145 offset:5120
	ds_read_b128 v[210:213], v145 offset:6144
	ds_read_b128 v[214:217], v145 offset:7168
	global_load_lds_dwordx4 v[186:187], off
	v_lshl_add_u64 v[186:187], s[18:19], 0, v[136:137]
	s_add_i32 m0, s29, 0xe000
	s_nop 0
	global_load_lds_dwordx4 v[186:187], off
	s_waitcnt vmcnt(8)
	s_waitcnt lgkmcnt(0)
	s_barrier
	s_waitcnt lgkmcnt(0)
	v_mfma_f32_16x16x32_bf16 v[124:127], v[138:141], v[174:177], v[124:127]
	v_mfma_f32_16x16x32_bf16 v[120:123], v[150:153], v[174:177], v[120:123]
	v_mfma_f32_16x16x32_bf16 v[108:111], v[138:141], v[182:185], v[108:111]
	v_mfma_f32_16x16x32_bf16 v[100:103], v[150:153], v[182:185], v[100:103]
	v_mfma_f32_16x16x32_bf16 v[92:95], v[138:141], v[202:205], v[92:95]
	v_mfma_f32_16x16x32_bf16 v[84:87], v[150:153], v[202:205], v[84:87]
	v_mfma_f32_16x16x32_bf16 v[76:79], v[138:141], v[210:213], v[76:79]
	v_mfma_f32_16x16x32_bf16 v[68:71], v[150:153], v[210:213], v[68:71]
	v_mfma_f32_16x16x32_bf16 v[124:127], v[146:149], v[178:181], v[124:127]
	v_mfma_f32_16x16x32_bf16 v[120:123], v[154:157], v[178:181], v[120:123]
	v_mfma_f32_16x16x32_bf16 v[108:111], v[146:149], v[198:201], v[108:111]
	v_mfma_f32_16x16x32_bf16 v[100:103], v[154:157], v[198:201], v[100:103]
	v_mfma_f32_16x16x32_bf16 v[92:95], v[146:149], v[206:209], v[92:95]
	v_mfma_f32_16x16x32_bf16 v[84:87], v[154:157], v[206:209], v[84:87]
	v_mfma_f32_16x16x32_bf16 v[76:79], v[146:149], v[214:217], v[76:79]
	v_mfma_f32_16x16x32_bf16 v[68:71], v[154:157], v[214:217], v[68:71]
	v_mfma_f32_16x16x32_bf16 v[116:119], v[158:161], v[174:177], v[116:119]
	v_mfma_f32_16x16x32_bf16 v[112:115], v[166:169], v[174:177], v[112:115]
	v_mfma_f32_16x16x32_bf16 v[104:107], v[158:161], v[182:185], v[104:107]
	v_mfma_f32_16x16x32_bf16 v[96:99], v[166:169], v[182:185], v[96:99]
	v_mfma_f32_16x16x32_bf16 v[88:91], v[158:161], v[202:205], v[88:91]
	v_mfma_f32_16x16x32_bf16 v[80:83], v[166:169], v[202:205], v[80:83]
	v_mfma_f32_16x16x32_bf16 v[72:75], v[158:161], v[210:213], v[72:75]
	v_mfma_f32_16x16x32_bf16 v[64:67], v[166:169], v[210:213], v[64:67]
	v_mfma_f32_16x16x32_bf16 v[116:119], v[162:165], v[178:181], v[116:119]
	v_mfma_f32_16x16x32_bf16 v[112:115], v[170:173], v[178:181], v[112:115]
	v_mfma_f32_16x16x32_bf16 v[104:107], v[162:165], v[198:201], v[104:107]
	v_mfma_f32_16x16x32_bf16 v[96:99], v[170:173], v[198:201], v[96:99]
	v_mfma_f32_16x16x32_bf16 v[88:91], v[162:165], v[206:209], v[88:91]
	v_mfma_f32_16x16x32_bf16 v[80:83], v[170:173], v[206:209], v[80:83]
	v_mfma_f32_16x16x32_bf16 v[72:75], v[162:165], v[214:217], v[72:75]
	v_mfma_f32_16x16x32_bf16 v[64:67], v[170:173], v[214:217], v[64:67]
	s_barrier
	s_add_i32 s44, s44, s28
	v_lshl_add_u64 v[186:187], s[20:21], 0, v[188:189]
	s_mov_b32 m0, s44
	ds_read_b128 v[174:177], v145 offset:16384
	ds_read_b128 v[178:181], v145 offset:17408
	ds_read_b128 v[182:185], v145 offset:18432
	ds_read_b128 v[198:201], v145 offset:19456
	ds_read_b128 v[202:205], v145 offset:20480
	ds_read_b128 v[206:209], v145 offset:21504
	ds_read_b128 v[210:213], v145 offset:22528
	ds_read_b128 v[214:217], v145 offset:23552
	global_load_lds_dwordx4 v[186:187], off
	s_add_i32 m0, s44, 0x2000
	s_add_u32 s44, s20, 0x40000
	v_lshl_add_u64 v[218:219], s[20:21], 0, v[128:129]
	s_addc_u32 s45, s21, 0
	s_add_i32 s46, s46, s28
	global_load_lds_dwordx4 v[218:219], off
	v_lshl_add_u64 v[220:221], s[44:45], 0, v[188:189]
	s_mov_b32 m0, s46
	v_lshl_add_u64 v[222:223], s[22:23], 0, v[130:131]
	global_load_lds_dwordx4 v[220:221], off
	v_lshl_add_u64 v[220:221], s[44:45], 0, v[128:129]
	s_add_i32 m0, s46, 0x2000
	s_nop 0
	global_load_lds_dwordx4 v[220:221], off
	v_lshl_add_u64 v[220:221], s[22:23], 0, v[132:133]
	s_mov_b32 m0, s29
	s_nop 0
	global_load_lds_dwordx4 v[220:221], off
	s_mov_b32 m0, s30
	s_nop 0
	global_load_lds_dwordx4 v[222:223], off
	s_waitcnt vmcnt(8)
	s_waitcnt lgkmcnt(0)
	s_barrier
; #define PG8_STAGE(bufoff, gbase, voff) do { _Pragma("unroll") for (int _i = 0; _i < 2; ++_i) \
;         __builtin_amdgcn_global_load_lds((const unsigned*)((const char*)(gbase) + (voff)[_i]), (LAS unsigned*)(lds + (bufoff) + ldsw + _i * 8192), 16, 0, 0); } while (0)
; #define PG8_LDA(dst, b, h) do { _Pragma("unroll") for (int m = 0; m < 4; ++m) _Pragma("unroll") for (int k = 0; k < 2; ++k) dst[m][k] = *(const LAS bf16x8*)(lds + PG8_SA(b, h) + aoff + m * 2048 + k * 1024); } while (0)
; #define PG8_LDB(dst, b, h) do { _Pragma("unroll") for (int n = 0; n < 2; ++n) _Pragma("unroll") for (int k = 0; k < 2; ++k) dst[n][k] = *(const LAS bf16x8*)(lds + PG8_SB(b, h) + boff + n * 2048 + k * 1024); } while (0)
; #define PG8_MMA(ai, bj, At, Bt) do { __builtin_amdgcn_s_setprio(1); _Pragma("unroll") for (int m = 0; m < 4; ++m) _Pragma("unroll") for (int n = 0; n < 2; ++n) _Pragma("unroll") for (int k = 0; k < 2; ++k) \
;         acc[ai][bj][m][n] = __builtin_amdgcn_mfma_f32_16x16x32_bf16(Bt[n][k], At[m][k], acc[ai][bj][m][n], 0, 0, 0); __builtin_amdgcn_s_setprio(0); } while (0)
; #define PG8_WAIT_V(n) asm volatile("s_waitcnt vmcnt(" #n ")" ::: "memory")
; #define PG8_WAIT_L(n) asm volatile("s_waitcnt lgkmcnt(" #n ")" ::: "memory")
; #define PG8_BAR __builtin_amdgcn_s_barrier()
; #define PG8_SCHED __builtin_amdgcn_sched_barrier(0)
; template <class Epi, class Sched>
; __device__ __forceinline__ void gemm_phase(int wv, LAS unsigned char* lds, const Gemm g, const Sched& S, const Epi& E) {
;     ...
;             PG8_WAIT_V(8); PG8_WAIT_L(0); PG8_BAR; PG8_MMA(1, 0, At, B0); PG8_MMA(1, 1, At, B1); PG8_BAR; PG8_SCHED;
;             PG8_LDB(B0, 1, 0); PG8_LDB(B1, 1, 1); PG8_SCHED; PG8_LDA(At, 1, 0); PG8_STAGE(PG8_SA(0, 1), a2 + hstep, voffA);
;             PG8_WAIT_V(8); PG8_WAIT_L(0); PG8_BAR; PG8_MMA(0, 0, At, B0); PG8_MMA(0, 1, At, B1); PG8_BAR; PG8_SCHED;
	s_waitcnt lgkmcnt(0)
	v_mfma_f32_16x16x32_bf16 v[60:63], v[138:141], v[174:177], v[60:63]
	v_mfma_f32_16x16x32_bf16 v[52:55], v[150:153], v[174:177], v[52:55]
	v_mfma_f32_16x16x32_bf16 v[44:47], v[138:141], v[182:185], v[44:47]
	v_mfma_f32_16x16x32_bf16 v[36:39], v[150:153], v[182:185], v[36:39]
	v_mfma_f32_16x16x32_bf16 v[28:31], v[138:141], v[202:205], v[28:31]
	v_mfma_f32_16x16x32_bf16 v[20:23], v[150:153], v[202:205], v[20:23]
	v_mfma_f32_16x16x32_bf16 v[12:15], v[138:141], v[210:213], v[12:15]
	v_mfma_f32_16x16x32_bf16 v[4:7], v[150:153], v[210:213], v[4:7]
	v_mfma_f32_16x16x32_bf16 v[60:63], v[146:149], v[178:181], v[60:63]
	v_mfma_f32_16x16x32_bf16 v[52:55], v[154:157], v[178:181], v[52:55]
	v_mfma_f32_16x16x32_bf16 v[44:47], v[146:149], v[198:201], v[44:47]
	v_mfma_f32_16x16x32_bf16 v[36:39], v[154:157], v[198:201], v[36:39]
	v_mfma_f32_16x16x32_bf16 v[28:31], v[146:149], v[206:209], v[28:31]
	v_mfma_f32_16x16x32_bf16 v[20:23], v[154:157], v[206:209], v[20:23]
	v_mfma_f32_16x16x32_bf16 v[12:15], v[146:149], v[214:217], v[12:15]
	v_mfma_f32_16x16x32_bf16 v[4:7], v[154:157], v[214:217], v[4:7]
	v_mfma_f32_16x16x32_bf16 v[56:59], v[158:161], v[174:177], v[56:59]
	v_mfma_f32_16x16x32_bf16 v[48:51], v[166:169], v[174:177], v[48:51]
	v_mfma_f32_16x16x32_bf16 v[40:43], v[158:161], v[182:185], v[40:43]
	v_mfma_f32_16x16x32_bf16 v[32:35], v[166:169], v[182:185], v[32:35]
	v_mfma_f32_16x16x32_bf16 v[24:27], v[158:161], v[202:205], v[24:27]
	v_mfma_f32_16x16x32_bf16 v[16:19], v[166:169], v[202:205], v[16:19]
	v_mfma_f32_16x16x32_bf16 v[8:11], v[158:161], v[210:213], v[8:11]
	v_mfma_f32_16x16x32_bf16 v[0:3], v[166:169], v[210:213], v[0:3]
	v_mfma_f32_16x16x32_bf16 v[56:59], v[162:165], v[178:181], v[56:59]
	v_mfma_f32_16x16x32_bf16 v[48:51], v[170:173], v[178:181], v[48:51]
	v_mfma_f32_16x16x32_bf16 v[40:43], v[162:165], v[198:201], v[40:43]
	v_mfma_f32_16x16x32_bf16 v[32:35], v[170:173], v[198:201], v[32:35]
	v_mfma_f32_16x16x32_bf16 v[24:27], v[162:165], v[206:209], v[24:27]
	v_mfma_f32_16x16x32_bf16 v[16:19], v[170:173], v[206:209], v[16:19]
	v_mfma_f32_16x16x32_bf16 v[8:11], v[162:165], v[214:217], v[8:11]
	v_mfma_f32_16x16x32_bf16 v[0:3], v[170:173], v[214:217], v[0:3]
	s_barrier
	s_add_i32 s44, 0, 0x1c000
	v_add_u32_e32 v154, s95, v143
	v_add_u32_e32 v170, s44, v143
	ds_read_b128 v[138:141], v154
	ds_read_b128 v[146:149], v154 offset:1024
	ds_read_b128 v[150:153], v154 offset:2048
	ds_read_b128 v[154:157], v154 offset:3072
	ds_read_b128 v[158:161], v170
	ds_read_b128 v[162:165], v170 offset:1024
	ds_read_b128 v[166:169], v170 offset:2048
	ds_read_b128 v[170:173], v170 offset:3072
	s_add_u32 s22, s22, 0x40000
	s_addc_u32 s23, s23, 0
	s_mov_b32 m0, s31
	v_lshl_add_u64 v[228:229], s[22:23], 0, v[132:133]
	ds_read_b128 v[174:177], v145 offset:32768
	ds_read_b128 v[178:181], v145 offset:33792
	ds_read_b128 v[182:185], v145 offset:34816
	ds_read_b128 v[198:201], v145 offset:35840
	ds_read_b128 v[202:205], v145 offset:36864
	ds_read_b128 v[206:209], v145 offset:37888
	ds_read_b128 v[210:213], v145 offset:38912
	ds_read_b128 v[214:217], v145 offset:39936
	global_load_lds_dwordx4 v[228:229], off
	v_lshl_add_u64 v[228:229], s[22:23], 0, v[130:131]
	s_mov_b32 m0, s34
	s_nop 0
	global_load_lds_dwordx4 v[228:229], off
	s_waitcnt vmcnt(8)
	s_waitcnt lgkmcnt(0)
	s_barrier
	s_waitcnt lgkmcnt(0)
	v_mfma_f32_16x16x32_bf16 v[124:127], v[138:141], v[174:177], v[124:127]
	v_mfma_f32_16x16x32_bf16 v[120:123], v[150:153], v[174:177], v[120:123]
	v_mfma_f32_16x16x32_bf16 v[108:111], v[138:141], v[182:185], v[108:111]
	v_mfma_f32_16x16x32_bf16 v[100:103], v[150:153], v[182:185], v[100:103]
	v_mfma_f32_16x16x32_bf16 v[92:95], v[138:141], v[202:205], v[92:95]
	v_mfma_f32_16x16x32_bf16 v[84:87], v[150:153], v[202:205], v[84:87]
	v_mfma_f32_16x16x32_bf16 v[76:79], v[138:141], v[210:213], v[76:79]
	v_mfma_f32_16x16x32_bf16 v[68:71], v[150:153], v[210:213], v[68:71]
	v_mfma_f32_16x16x32_bf16 v[124:127], v[146:149], v[178:181], v[124:127]
	v_mfma_f32_16x16x32_bf16 v[120:123], v[154:157], v[178:181], v[120:123]
	v_mfma_f32_16x16x32_bf16 v[108:111], v[146:149], v[198:201], v[108:111]
	v_mfma_f32_16x16x32_bf16 v[100:103], v[154:157], v[198:201], v[100:103]
	v_mfma_f32_16x16x32_bf16 v[92:95], v[146:149], v[206:209], v[92:95]
	v_mfma_f32_16x16x32_bf16 v[84:87], v[154:157], v[206:209], v[84:87]
	v_mfma_f32_16x16x32_bf16 v[76:79], v[146:149], v[214:217], v[76:79]
	v_mfma_f32_16x16x32_bf16 v[68:71], v[154:157], v[214:217], v[68:71]
	v_mfma_f32_16x16x32_bf16 v[116:119], v[158:161], v[174:177], v[116:119]
	v_mfma_f32_16x16x32_bf16 v[112:115], v[166:169], v[174:177], v[112:115]
	v_mfma_f32_16x16x32_bf16 v[104:107], v[158:161], v[182:185], v[104:107]
	v_mfma_f32_16x16x32_bf16 v[96:99], v[166:169], v[182:185], v[96:99]
	v_mfma_f32_16x16x32_bf16 v[88:91], v[158:161], v[202:205], v[88:91]
	v_mfma_f32_16x16x32_bf16 v[80:83], v[166:169], v[202:205], v[80:83]
	v_mfma_f32_16x16x32_bf16 v[72:75], v[158:161], v[210:213], v[72:75]
	v_mfma_f32_16x16x32_bf16 v[64:67], v[166:169], v[210:213], v[64:67]
	v_mfma_f32_16x16x32_bf16 v[116:119], v[162:165], v[178:181], v[116:119]
	v_mfma_f32_16x16x32_bf16 v[112:115], v[170:173], v[178:181], v[112:115]
	v_mfma_f32_16x16x32_bf16 v[104:107], v[162:165], v[198:201], v[104:107]
	v_mfma_f32_16x16x32_bf16 v[96:99], v[170:173], v[198:201], v[96:99]
	v_mfma_f32_16x16x32_bf16 v[88:91], v[162:165], v[206:209], v[88:91]
	v_mfma_f32_16x16x32_bf16 v[80:83], v[170:173], v[206:209], v[80:83]
	v_mfma_f32_16x16x32_bf16 v[72:75], v[162:165], v[214:217], v[72:75]
	v_mfma_f32_16x16x32_bf16 v[64:67], v[170:173], v[214:217], v[64:67]
	s_barrier
; #define PG8_STAGE(bufoff, gbase, voff) do { _Pragma("unroll") for (int _i = 0; _i < 2; ++_i) \
;         __builtin_amdgcn_global_load_lds((const unsigned*)((const char*)(gbase) + (voff)[_i]), (LAS unsigned*)(lds + (bufoff) + ldsw + _i * 8192), 16, 0, 0); } while (0)
; #define PG8_LDA(dst, b, h) do { _Pragma("unroll") for (int m = 0; m < 4; ++m) _Pragma("unroll") for (int k = 0; k < 2; ++k) dst[m][k] = *(const LAS bf16x8*)(lds + PG8_SA(b, h) + aoff + m * 2048 + k * 1024); } while (0)
; #define PG8_MMA(ai, bj, At, Bt) do { __builtin_amdgcn_s_setprio(1); _Pragma("unroll") for (int m = 0; m < 4; ++m) _Pragma("unroll") for (int n = 0; n < 2; ++n) _Pragma("unroll") for (int k = 0; k < 2; ++k) \
;         acc[ai][bj][m][n] = __builtin_amdgcn_mfma_f32_16x16x32_bf16(Bt[n][k], At[m][k], acc[ai][bj][m][n], 0, 0, 0); __builtin_amdgcn_s_setprio(0); } while (0)
; #define PG8_WAIT_V(n) asm volatile("s_waitcnt vmcnt(" #n ")" ::: "memory")
; #define PG8_WAIT_L(n) asm volatile("s_waitcnt lgkmcnt(" #n ")" ::: "memory")
; #define PG8_BAR __builtin_amdgcn_s_barrier()
; #define PG8_SCHED __builtin_amdgcn_sched_barrier(0)
; template <class Epi, class Sched>
; __device__ __forceinline__ void gemm_phase(int wv, LAS unsigned char* lds, const Gemm g, const Sched& S, const Epi& E) {
;     ...
;             PG8_LDA(At, 1, 1); PG8_STAGE(PG8_SB(1, 0), b3, voffB); PG8_STAGE(PG8_SB(1, 1), b3 + hstepB, voffB); PG8_STAGE(PG8_SA(1, 0), a3, voffA);
;             PG8_WAIT_V(8); PG8_WAIT_L(0); PG8_BAR; PG8_MMA(1, 0, At, B0); PG8_MMA(1, 1, At, B1); PG8_BAR; PG8_SCHED;
;         }
;         if (wr == 0) PG8_BAR;
	s_add_i32 s22, s95, s28
	v_lshl_add_u64 v[186:187], v[186:187], 0, s[74:75]
	s_mov_b32 m0, s22
	ds_read_b128 v[174:177], v145 offset:49152
	ds_read_b128 v[178:181], v145 offset:50176
	ds_read_b128 v[182:185], v145 offset:51200
	ds_read_b128 v[198:201], v145 offset:52224
	ds_read_b128 v[202:205], v145 offset:53248
	ds_read_b128 v[206:209], v145 offset:54272
	ds_read_b128 v[210:213], v145 offset:55296
	ds_read_b128 v[214:217], v145 offset:56320
	global_load_lds_dwordx4 v[186:187], off
	s_add_i32 m0, s22, 0x2000
	s_add_u32 s20, s20, 0x40080
	v_lshl_add_u64 v[186:187], v[218:219], 0, s[74:75]
	s_addc_u32 s21, s21, 0
	s_add_i32 s22, s44, s28
	global_load_lds_dwordx4 v[186:187], off
	v_lshl_add_u64 v[186:187], s[20:21], 0, v[188:189]
	s_mov_b32 m0, s22
	s_nop 0
	global_load_lds_dwordx4 v[186:187], off
	v_lshl_add_u64 v[186:187], s[20:21], 0, v[128:129]
	s_add_i32 m0, s22, 0x2000
	s_nop 0
	global_load_lds_dwordx4 v[186:187], off
	v_lshl_add_u64 v[186:187], v[220:221], 0, s[74:75]
	s_mov_b32 m0, s35
	s_nop 0
	global_load_lds_dwordx4 v[186:187], off
	v_lshl_add_u64 v[186:187], v[222:223], 0, s[74:75]
	s_mov_b32 m0, s36
	s_nop 0
	global_load_lds_dwordx4 v[186:187], off
	s_waitcnt vmcnt(8)
	s_waitcnt lgkmcnt(0)
	s_barrier
	s_waitcnt lgkmcnt(0)
	v_mfma_f32_16x16x32_bf16 v[60:63], v[138:141], v[174:177], v[60:63]
	v_mfma_f32_16x16x32_bf16 v[52:55], v[150:153], v[174:177], v[52:55]
	v_mfma_f32_16x16x32_bf16 v[44:47], v[138:141], v[182:185], v[44:47]
	v_mfma_f32_16x16x32_bf16 v[36:39], v[150:153], v[182:185], v[36:39]
	v_mfma_f32_16x16x32_bf16 v[28:31], v[138:141], v[202:205], v[28:31]
	v_mfma_f32_16x16x32_bf16 v[20:23], v[150:153], v[202:205], v[20:23]
	v_mfma_f32_16x16x32_bf16 v[12:15], v[138:141], v[210:213], v[12:15]
	v_mfma_f32_16x16x32_bf16 v[4:7], v[150:153], v[210:213], v[4:7]
	v_mfma_f32_16x16x32_bf16 v[60:63], v[146:149], v[178:181], v[60:63]
	v_mfma_f32_16x16x32_bf16 v[52:55], v[154:157], v[178:181], v[52:55]
	v_mfma_f32_16x16x32_bf16 v[44:47], v[146:149], v[198:201], v[44:47]
	v_mfma_f32_16x16x32_bf16 v[36:39], v[154:157], v[198:201], v[36:39]
	v_mfma_f32_16x16x32_bf16 v[28:31], v[146:149], v[206:209], v[28:31]
	v_mfma_f32_16x16x32_bf16 v[20:23], v[154:157], v[206:209], v[20:23]
	v_mfma_f32_16x16x32_bf16 v[12:15], v[146:149], v[214:217], v[12:15]
	v_mfma_f32_16x16x32_bf16 v[4:7], v[154:157], v[214:217], v[4:7]
	v_mfma_f32_16x16x32_bf16 v[56:59], v[158:161], v[174:177], v[56:59]
	v_mfma_f32_16x16x32_bf16 v[48:51], v[166:169], v[174:177], v[48:51]
	v_mfma_f32_16x16x32_bf16 v[40:43], v[158:161], v[182:185], v[40:43]
	v_mfma_f32_16x16x32_bf16 v[32:35], v[166:169], v[182:185], v[32:35]
	v_mfma_f32_16x16x32_bf16 v[24:27], v[158:161], v[202:205], v[24:27]
	v_mfma_f32_16x16x32_bf16 v[16:19], v[166:169], v[202:205], v[16:19]
	v_mfma_f32_16x16x32_bf16 v[8:11], v[158:161], v[210:213], v[8:11]
	v_mfma_f32_16x16x32_bf16 v[0:3], v[166:169], v[210:213], v[0:3]
	v_mfma_f32_16x16x32_bf16 v[56:59], v[162:165], v[178:181], v[56:59]
	v_mfma_f32_16x16x32_bf16 v[48:51], v[170:173], v[178:181], v[48:51]
	v_mfma_f32_16x16x32_bf16 v[40:43], v[162:165], v[198:201], v[40:43]
	v_mfma_f32_16x16x32_bf16 v[32:35], v[170:173], v[198:201], v[32:35]
	v_mfma_f32_16x16x32_bf16 v[24:27], v[162:165], v[206:209], v[24:27]
	v_mfma_f32_16x16x32_bf16 v[16:19], v[170:173], v[206:209], v[16:19]
	v_mfma_f32_16x16x32_bf16 v[8:11], v[162:165], v[214:217], v[8:11]
	v_mfma_f32_16x16x32_bf16 v[0:3], v[170:173], v[214:217], v[0:3]
	s_barrier
	s_add_i32 s43, s43, 2
	s_add_u32 s18, s18, 0x100
	s_addc_u32 s19, s19, 0
	s_add_u32 s41, s41, 0x100
	s_addc_u32 s42, s42, 0
	s_cmp_gt_u32 s43, 13
	s_cbranch_scc0 .LBB0_978
	s_and_b64 vcc, exec, s[8:9]
	s_cbranch_vccz .LBB0_981
	s_barrier

; #define PG8_STAGE(bufoff, gbase, voff) do { _Pragma("unroll") for (int _i = 0; _i < 2; ++_i) \
;         __builtin_amdgcn_global_load_lds((const unsigned*)((const char*)(gbase) + (voff)[_i]), (LAS unsigned*)(lds + (bufoff) + ldsw + _i * 8192), 16, 0, 0); } while (0)
; #define PG8_LDA(dst, b, h) do { _Pragma("unroll") for (int m = 0; m < 4; ++m) _Pragma("unroll") for (int k = 0; k < 2; ++k) dst[m][k] = *(const LAS bf16x8*)(lds + PG8_SA(b, h) + aoff + m * 2048 + k * 1024); } while (0)
; #define PG8_LDB(dst, b, h) do { _Pragma("unroll") for (int n = 0; n < 2; ++n) _Pragma("unroll") for (int k = 0; k < 2; ++k) dst[n][k] = *(const LAS bf16x8*)(lds + PG8_SB(b, h) + boff + n * 2048 + k * 1024); } while (0)
; #define PG8_MMA(ai, bj, At, Bt) do { __builtin_amdgcn_s_setprio(1); _Pragma("unroll") for (int m = 0; m < 4; ++m) _Pragma("unroll") for (int n = 0; n < 2; ++n) _Pragma("unroll") for (int k = 0; k < 2; ++k) \
;         acc[ai][bj][m][n] = __builtin_amdgcn_mfma_f32_16x16x32_bf16(Bt[n][k], At[m][k], acc[ai][bj][m][n], 0, 0, 0); __builtin_amdgcn_s_setprio(0); } while (0)
; #define PG8_WAIT_V(n) asm volatile("s_waitcnt vmcnt(" #n ")" ::: "memory")
; #define PG8_WAIT_L(n) asm volatile("s_waitcnt lgkmcnt(" #n ")" ::: "memory")
; #define PG8_BAR __builtin_amdgcn_s_barrier()
; #define PG8_SCHED __builtin_amdgcn_sched_barrier(0)
; template <class Epi, class Sched>
; __device__ __forceinline__ void gemm_phase(int wv, LAS unsigned char* lds, const Gemm g, const Sched& S, const Epi& E) {
;     ...
;             const bool last = (t == nt - 2);
;             const char* a1 = cA + (size_t)(t + 1) * kstep;
;             const char* a2 = last ? nA : cA + (size_t)(t + 2) * kstep; const char* b2 = last ? nB : cB + (size_t)(t + 2) * kstep;
;             const char* a3 = a2 + kstep; const char* b3 = b2 + kstep;
;             PG8_LDB(B0, 0, 0); PG8_LDB(B1, 0, 1); PG8_SCHED; PG8_LDA(At, 0, 0); PG8_STAGE(PG8_SA(1, 1), a1 + hstep, voffA);
;             PG8_WAIT_V(8); PG8_WAIT_L(0); PG8_BAR; PG8_MMA(0, 0, At, B0); PG8_MMA(0, 1, At, B1); PG8_BAR; PG8_SCHED;
;             PG8_LDA(At, 0, 1); PG8_STAGE(PG8_SB(0, 0), b2, voffB); PG8_STAGE(PG8_SB(0, 1), b2 + hstepB, voffB); PG8_STAGE(PG8_SA(0, 0), a2, voffA);
;             PG8_WAIT_V(8); PG8_WAIT_L(0); PG8_BAR; PG8_MMA(1, 0, At, B0); PG8_MMA(1, 1, At, B1); PG8_BAR; PG8_SCHED;
.LBB0_1055:
	s_add_u32 s4, s22, 0x100
	s_addc_u32 s5, s23, 0
	s_add_i32 s48, 0, 0x10000
	s_cmp_eq_u32 s47, 40
	s_cselect_b32 s27, s19, s5
	s_cselect_b32 s26, s18, s4
	s_cselect_b32 s25, s21, s46
	s_cselect_b32 s24, s20, s45
	s_add_i32 s49, 0, 0x14000
	v_add_u32_e32 v136, s48, v213
	v_add_u32_e32 v156, s49, v213
	ds_read_b128 v[96:99], v136
	ds_read_b128 v[100:103], v136 offset:1024
	ds_read_b128 v[104:107], v136 offset:2048
	ds_read_b128 v[136:139], v136 offset:3072
	ds_read_b128 v[140:143], v156
	ds_read_b128 v[144:147], v156 offset:1024
	ds_read_b128 v[152:155], v156 offset:2048
	ds_read_b128 v[156:159], v156 offset:3072
	v_lshl_add_u64 v[186:187], s[22:23], 0, v[182:183]
	s_add_i32 m0, s35, 0xc000
	ds_read_b128 v[160:163], v217
	ds_read_b128 v[164:167], v217 offset:1024
	ds_read_b128 v[168:171], v217 offset:2048
	ds_read_b128 v[172:175], v217 offset:3072
	ds_read_b128 v[198:201], v217 offset:4096
	ds_read_b128 v[202:205], v217 offset:5120
	ds_read_b128 v[206:209], v217 offset:6144
	ds_read_b128 v[218:221], v217 offset:7168
	global_load_lds_dwordx4 v[186:187], off
	v_lshl_add_u64 v[186:187], s[22:23], 0, v[184:185]
	s_add_i32 m0, s35, 0xe000
	s_nop 0
	global_load_lds_dwordx4 v[186:187], off
	s_waitcnt vmcnt(8)
	s_waitcnt lgkmcnt(0)
	s_barrier
	s_waitcnt lgkmcnt(0)
	v_mfma_f32_16x16x32_bf16 v[148:151], v[96:99], v[160:163], v[148:151]
	v_mfma_f32_16x16x32_bf16 v[124:127], v[104:107], v[160:163], v[124:127]
	v_mfma_f32_16x16x32_bf16 v[132:135], v[96:99], v[168:171], v[132:135]
	v_mfma_f32_16x16x32_bf16 v[128:131], v[104:107], v[168:171], v[128:131]
	v_mfma_f32_16x16x32_bf16 v[92:95], v[96:99], v[198:201], v[92:95]
	v_mfma_f32_16x16x32_bf16 v[88:91], v[104:107], v[198:201], v[88:91]
	v_mfma_f32_16x16x32_bf16 v[76:79], v[96:99], v[206:209], v[76:79]
	v_mfma_f32_16x16x32_bf16 v[72:75], v[104:107], v[206:209], v[72:75]
	v_mfma_f32_16x16x32_bf16 v[148:151], v[100:103], v[164:167], v[148:151]
	v_mfma_f32_16x16x32_bf16 v[124:127], v[136:139], v[164:167], v[124:127]
	v_mfma_f32_16x16x32_bf16 v[132:135], v[100:103], v[172:175], v[132:135]
	v_mfma_f32_16x16x32_bf16 v[128:131], v[136:139], v[172:175], v[128:131]
	v_mfma_f32_16x16x32_bf16 v[92:95], v[100:103], v[202:205], v[92:95]
	v_mfma_f32_16x16x32_bf16 v[88:91], v[136:139], v[202:205], v[88:91]
	v_mfma_f32_16x16x32_bf16 v[76:79], v[100:103], v[218:221], v[76:79]
	v_mfma_f32_16x16x32_bf16 v[72:75], v[136:139], v[218:221], v[72:75]
	v_mfma_f32_16x16x32_bf16 v[116:119], v[140:143], v[160:163], v[116:119]
	v_mfma_f32_16x16x32_bf16 v[108:111], v[152:155], v[160:163], v[108:111]
	v_mfma_f32_16x16x32_bf16 v[120:123], v[140:143], v[168:171], v[120:123]
	v_mfma_f32_16x16x32_bf16 v[112:115], v[152:155], v[168:171], v[112:115]
	v_mfma_f32_16x16x32_bf16 v[84:87], v[140:143], v[198:201], v[84:87]
	v_mfma_f32_16x16x32_bf16 v[80:83], v[152:155], v[198:201], v[80:83]
	v_mfma_f32_16x16x32_bf16 v[68:71], v[140:143], v[206:209], v[68:71]
	v_mfma_f32_16x16x32_bf16 v[64:67], v[152:155], v[206:209], v[64:67]
	v_mfma_f32_16x16x32_bf16 v[116:119], v[144:147], v[164:167], v[116:119]
	v_mfma_f32_16x16x32_bf16 v[108:111], v[156:159], v[164:167], v[108:111]
	v_mfma_f32_16x16x32_bf16 v[120:123], v[144:147], v[172:175], v[120:123]
	v_mfma_f32_16x16x32_bf16 v[112:115], v[156:159], v[172:175], v[112:115]
	v_mfma_f32_16x16x32_bf16 v[84:87], v[144:147], v[202:205], v[84:87]
	v_mfma_f32_16x16x32_bf16 v[80:83], v[156:159], v[202:205], v[80:83]
	v_mfma_f32_16x16x32_bf16 v[68:71], v[144:147], v[218:221], v[68:71]
	v_mfma_f32_16x16x32_bf16 v[64:67], v[156:159], v[218:221], v[64:67]
	s_barrier
	s_add_i32 s22, s48, s34
	v_lshl_add_u64 v[186:187], s[24:25], 0, v[188:189]
	s_mov_b32 m0, s22
	ds_read_b128 v[160:163], v217 offset:16384
	ds_read_b128 v[164:167], v217 offset:17408
	ds_read_b128 v[168:171], v217 offset:18432
	ds_read_b128 v[172:175], v217 offset:19456
	ds_read_b128 v[198:201], v217 offset:20480
	ds_read_b128 v[202:205], v217 offset:21504
	ds_read_b128 v[206:209], v217 offset:22528
	ds_read_b128 v[218:221], v217 offset:23552
	global_load_lds_dwordx4 v[186:187], off
	s_add_i32 m0, s22, 0x2000
	s_add_u32 s22, s24, 0xb000
	v_lshl_add_u64 v[210:211], s[24:25], 0, v[176:177]
	s_addc_u32 s23, s25, 0
	s_add_i32 s48, s49, s34
	global_load_lds_dwordx4 v[210:211], off
	v_lshl_add_u64 v[222:223], s[22:23], 0, v[188:189]
	s_mov_b32 m0, s48
	v_lshl_add_u64 v[228:229], s[26:27], 0, v[178:179]
	global_load_lds_dwordx4 v[222:223], off
	v_lshl_add_u64 v[222:223], s[22:23], 0, v[176:177]
	s_add_i32 m0, s48, 0x2000
	s_nop 0
	global_load_lds_dwordx4 v[222:223], off
	v_lshl_add_u64 v[222:223], s[26:27], 0, v[180:181]
	s_mov_b32 m0, s35
	s_nop 0
	global_load_lds_dwordx4 v[222:223], off
	s_mov_b32 m0, s36
	s_nop 0
	global_load_lds_dwordx4 v[228:229], off
	s_waitcnt vmcnt(8)
	s_waitcnt lgkmcnt(0)
	s_barrier
; #define PG8_STAGE(bufoff, gbase, voff) do { _Pragma("unroll") for (int _i = 0; _i < 2; ++_i) \
;         __builtin_amdgcn_global_load_lds((const unsigned*)((const char*)(gbase) + (voff)[_i]), (LAS unsigned*)(lds + (bufoff) + ldsw + _i * 8192), 16, 0, 0); } while (0)
; #define PG8_LDA(dst, b, h) do { _Pragma("unroll") for (int m = 0; m < 4; ++m) _Pragma("unroll") for (int k = 0; k < 2; ++k) dst[m][k] = *(const LAS bf16x8*)(lds + PG8_SA(b, h) + aoff + m * 2048 + k * 1024); } while (0)
; #define PG8_LDB(dst, b, h) do { _Pragma("unroll") for (int n = 0; n < 2; ++n) _Pragma("unroll") for (int k = 0; k < 2; ++k) dst[n][k] = *(const LAS bf16x8*)(lds + PG8_SB(b, h) + boff + n * 2048 + k * 1024); } while (0)
; #define PG8_MMA(ai, bj, At, Bt) do { __builtin_amdgcn_s_setprio(1); _Pragma("unroll") for (int m = 0; m < 4; ++m) _Pragma("unroll") for (int n = 0; n < 2; ++n) _Pragma("unroll") for (int k = 0; k < 2; ++k) \
;         acc[ai][bj][m][n] = __builtin_amdgcn_mfma_f32_16x16x32_bf16(Bt[n][k], At[m][k], acc[ai][bj][m][n], 0, 0, 0); __builtin_amdgcn_s_setprio(0); } while (0)
; #define PG8_WAIT_V(n) asm volatile("s_waitcnt vmcnt(" #n ")" ::: "memory")
; #define PG8_WAIT_L(n) asm volatile("s_waitcnt lgkmcnt(" #n ")" ::: "memory")
; #define PG8_BAR __builtin_amdgcn_s_barrier()
; #define PG8_SCHED __builtin_amdgcn_sched_barrier(0)
; template <class Epi, class Sched>
; __device__ __forceinline__ void gemm_phase(int wv, LAS unsigned char* lds, const Gemm g, const Sched& S, const Epi& E) {
;     ...
;             PG8_WAIT_V(8); PG8_WAIT_L(0); PG8_BAR; PG8_MMA(1, 0, At, B0); PG8_MMA(1, 1, At, B1); PG8_BAR; PG8_SCHED;
;             PG8_LDB(B0, 1, 0); PG8_LDB(B1, 1, 1); PG8_SCHED; PG8_LDA(At, 1, 0); PG8_STAGE(PG8_SA(0, 1), a2 + hstep, voffA);
;             PG8_WAIT_V(8); PG8_WAIT_L(0); PG8_BAR; PG8_MMA(0, 0, At, B0); PG8_MMA(0, 1, At, B1); PG8_BAR; PG8_SCHED;
	s_waitcnt lgkmcnt(0)
	v_mfma_f32_16x16x32_bf16 v[60:63], v[96:99], v[160:163], v[60:63]
	v_mfma_f32_16x16x32_bf16 v[56:59], v[104:107], v[160:163], v[56:59]
	v_mfma_f32_16x16x32_bf16 v[44:47], v[96:99], v[168:171], v[44:47]
	v_mfma_f32_16x16x32_bf16 v[40:43], v[104:107], v[168:171], v[40:43]
	v_mfma_f32_16x16x32_bf16 v[28:31], v[96:99], v[198:201], v[28:31]
	v_mfma_f32_16x16x32_bf16 v[24:27], v[104:107], v[198:201], v[24:27]
	v_mfma_f32_16x16x32_bf16 v[12:15], v[96:99], v[206:209], v[12:15]
	v_mfma_f32_16x16x32_bf16 v[8:11], v[104:107], v[206:209], v[8:11]
	v_mfma_f32_16x16x32_bf16 v[60:63], v[100:103], v[164:167], v[60:63]
	v_mfma_f32_16x16x32_bf16 v[56:59], v[136:139], v[164:167], v[56:59]
	v_mfma_f32_16x16x32_bf16 v[44:47], v[100:103], v[172:175], v[44:47]
	v_mfma_f32_16x16x32_bf16 v[40:43], v[136:139], v[172:175], v[40:43]
	v_mfma_f32_16x16x32_bf16 v[28:31], v[100:103], v[202:205], v[28:31]
	v_mfma_f32_16x16x32_bf16 v[24:27], v[136:139], v[202:205], v[24:27]
	v_mfma_f32_16x16x32_bf16 v[12:15], v[100:103], v[218:221], v[12:15]
	v_mfma_f32_16x16x32_bf16 v[8:11], v[136:139], v[218:221], v[8:11]
	v_mfma_f32_16x16x32_bf16 v[52:55], v[140:143], v[160:163], v[52:55]
	v_mfma_f32_16x16x32_bf16 v[48:51], v[152:155], v[160:163], v[48:51]
	v_mfma_f32_16x16x32_bf16 v[36:39], v[140:143], v[168:171], v[36:39]
	v_mfma_f32_16x16x32_bf16 v[32:35], v[152:155], v[168:171], v[32:35]
	v_mfma_f32_16x16x32_bf16 v[20:23], v[140:143], v[198:201], v[20:23]
	v_mfma_f32_16x16x32_bf16 v[16:19], v[152:155], v[198:201], v[16:19]
	v_mfma_f32_16x16x32_bf16 v[4:7], v[140:143], v[206:209], v[4:7]
	v_mfma_f32_16x16x32_bf16 v[0:3], v[152:155], v[206:209], v[0:3]
	v_mfma_f32_16x16x32_bf16 v[52:55], v[144:147], v[164:167], v[52:55]
	v_mfma_f32_16x16x32_bf16 v[48:51], v[156:159], v[164:167], v[48:51]
	v_mfma_f32_16x16x32_bf16 v[36:39], v[144:147], v[172:175], v[36:39]
	v_mfma_f32_16x16x32_bf16 v[32:35], v[156:159], v[172:175], v[32:35]
	v_mfma_f32_16x16x32_bf16 v[20:23], v[144:147], v[202:205], v[20:23]
	v_mfma_f32_16x16x32_bf16 v[16:19], v[156:159], v[202:205], v[16:19]
	v_mfma_f32_16x16x32_bf16 v[4:7], v[144:147], v[218:221], v[4:7]
	v_mfma_f32_16x16x32_bf16 v[0:3], v[156:159], v[218:221], v[0:3]
	s_barrier
	s_add_i32 s48, 0, 0x1c000
	v_add_u32_e32 v136, s95, v213
	v_add_u32_e32 v156, s48, v213
	ds_read_b128 v[96:99], v136
	ds_read_b128 v[100:103], v136 offset:1024
	ds_read_b128 v[104:107], v136 offset:2048
	ds_read_b128 v[136:139], v136 offset:3072
	ds_read_b128 v[140:143], v156
	ds_read_b128 v[144:147], v156 offset:1024
	ds_read_b128 v[152:155], v156 offset:2048
	ds_read_b128 v[156:159], v156 offset:3072
	s_add_u32 s22, s26, 0xb0000
	s_addc_u32 s23, s27, 0
	s_mov_b32 m0, s37
	v_lshl_add_u64 v[230:231], s[22:23], 0, v[180:181]
	ds_read_b128 v[160:163], v217 offset:32768
	ds_read_b128 v[164:167], v217 offset:33792
	ds_read_b128 v[168:171], v217 offset:34816
	ds_read_b128 v[172:175], v217 offset:35840
	ds_read_b128 v[198:201], v217 offset:36864
	ds_read_b128 v[202:205], v217 offset:37888
	ds_read_b128 v[206:209], v217 offset:38912
	ds_read_b128 v[218:221], v217 offset:39936
	global_load_lds_dwordx4 v[230:231], off
	v_lshl_add_u64 v[230:231], s[22:23], 0, v[178:179]
	s_mov_b32 m0, s38
	s_nop 0
	global_load_lds_dwordx4 v[230:231], off
	s_waitcnt vmcnt(8)
	s_waitcnt lgkmcnt(0)
	s_barrier
	s_waitcnt lgkmcnt(0)
	v_mfma_f32_16x16x32_bf16 v[148:151], v[96:99], v[160:163], v[148:151]
	v_mfma_f32_16x16x32_bf16 v[124:127], v[104:107], v[160:163], v[124:127]
	v_mfma_f32_16x16x32_bf16 v[132:135], v[96:99], v[168:171], v[132:135]
	v_mfma_f32_16x16x32_bf16 v[128:131], v[104:107], v[168:171], v[128:131]
	v_mfma_f32_16x16x32_bf16 v[92:95], v[96:99], v[198:201], v[92:95]
	v_mfma_f32_16x16x32_bf16 v[88:91], v[104:107], v[198:201], v[88:91]
	v_mfma_f32_16x16x32_bf16 v[76:79], v[96:99], v[206:209], v[76:79]
	v_mfma_f32_16x16x32_bf16 v[72:75], v[104:107], v[206:209], v[72:75]
	v_mfma_f32_16x16x32_bf16 v[148:151], v[100:103], v[164:167], v[148:151]
	v_mfma_f32_16x16x32_bf16 v[124:127], v[136:139], v[164:167], v[124:127]
	v_mfma_f32_16x16x32_bf16 v[132:135], v[100:103], v[172:175], v[132:135]
	v_mfma_f32_16x16x32_bf16 v[128:131], v[136:139], v[172:175], v[128:131]
	v_mfma_f32_16x16x32_bf16 v[92:95], v[100:103], v[202:205], v[92:95]
	v_mfma_f32_16x16x32_bf16 v[88:91], v[136:139], v[202:205], v[88:91]
	v_mfma_f32_16x16x32_bf16 v[76:79], v[100:103], v[218:221], v[76:79]
	v_mfma_f32_16x16x32_bf16 v[72:75], v[136:139], v[218:221], v[72:75]
	v_mfma_f32_16x16x32_bf16 v[116:119], v[140:143], v[160:163], v[116:119]
	v_mfma_f32_16x16x32_bf16 v[108:111], v[152:155], v[160:163], v[108:111]
	v_mfma_f32_16x16x32_bf16 v[120:123], v[140:143], v[168:171], v[120:123]
	v_mfma_f32_16x16x32_bf16 v[112:115], v[152:155], v[168:171], v[112:115]
	v_mfma_f32_16x16x32_bf16 v[84:87], v[140:143], v[198:201], v[84:87]
	v_mfma_f32_16x16x32_bf16 v[80:83], v[152:155], v[198:201], v[80:83]
	v_mfma_f32_16x16x32_bf16 v[68:71], v[140:143], v[206:209], v[68:71]
	v_mfma_f32_16x16x32_bf16 v[64:67], v[152:155], v[206:209], v[64:67]
	v_mfma_f32_16x16x32_bf16 v[116:119], v[144:147], v[164:167], v[116:119]
	v_mfma_f32_16x16x32_bf16 v[108:111], v[156:159], v[164:167], v[108:111]
	v_mfma_f32_16x16x32_bf16 v[120:123], v[144:147], v[172:175], v[120:123]
	v_mfma_f32_16x16x32_bf16 v[112:115], v[156:159], v[172:175], v[112:115]
	v_mfma_f32_16x16x32_bf16 v[84:87], v[144:147], v[202:205], v[84:87]
	v_mfma_f32_16x16x32_bf16 v[80:83], v[156:159], v[202:205], v[80:83]
	v_mfma_f32_16x16x32_bf16 v[68:71], v[144:147], v[218:221], v[68:71]
	v_mfma_f32_16x16x32_bf16 v[64:67], v[156:159], v[218:221], v[64:67]
	s_barrier
; #define PG8_STAGE(bufoff, gbase, voff) do { _Pragma("unroll") for (int _i = 0; _i < 2; ++_i) \
;         __builtin_amdgcn_global_load_lds((const unsigned*)((const char*)(gbase) + (voff)[_i]), (LAS unsigned*)(lds + (bufoff) + ldsw + _i * 8192), 16, 0, 0); } while (0)
; #define PG8_LDA(dst, b, h) do { _Pragma("unroll") for (int m = 0; m < 4; ++m) _Pragma("unroll") for (int k = 0; k < 2; ++k) dst[m][k] = *(const LAS bf16x8*)(lds + PG8_SA(b, h) + aoff + m * 2048 + k * 1024); } while (0)
; #define PG8_MMA(ai, bj, At, Bt) do { __builtin_amdgcn_s_setprio(1); _Pragma("unroll") for (int m = 0; m < 4; ++m) _Pragma("unroll") for (int n = 0; n < 2; ++n) _Pragma("unroll") for (int k = 0; k < 2; ++k) \
;         acc[ai][bj][m][n] = __builtin_amdgcn_mfma_f32_16x16x32_bf16(Bt[n][k], At[m][k], acc[ai][bj][m][n], 0, 0, 0); __builtin_amdgcn_s_setprio(0); } while (0)
; #define PG8_WAIT_V(n) asm volatile("s_waitcnt vmcnt(" #n ")" ::: "memory")
; #define PG8_WAIT_L(n) asm volatile("s_waitcnt lgkmcnt(" #n ")" ::: "memory")
; #define PG8_BAR __builtin_amdgcn_s_barrier()
; #define PG8_SCHED __builtin_amdgcn_sched_barrier(0)
; template <class Epi, class Sched>
; __device__ __forceinline__ void gemm_phase(int wv, LAS unsigned char* lds, const Gemm g, const Sched& S, const Epi& E) {
;     ...
;             PG8_LDA(At, 1, 1); PG8_STAGE(PG8_SB(1, 0), b3, voffB); PG8_STAGE(PG8_SB(1, 1), b3 + hstepB, voffB); PG8_STAGE(PG8_SA(1, 0), a3, voffA);
;             PG8_WAIT_V(8); PG8_WAIT_L(0); PG8_BAR; PG8_MMA(1, 0, At, B0); PG8_MMA(1, 1, At, B1); PG8_BAR; PG8_SCHED;
;         }
;         if (wr == 0) PG8_BAR;
	s_add_i32 s22, s95, s34
	v_lshl_add_u64 v[186:187], v[186:187], 0, s[74:75]
	s_mov_b32 m0, s22
	ds_read_b128 v[160:163], v217 offset:49152
	ds_read_b128 v[164:167], v217 offset:50176
	ds_read_b128 v[168:171], v217 offset:51200
	ds_read_b128 v[172:175], v217 offset:52224
	ds_read_b128 v[198:201], v217 offset:53248
	ds_read_b128 v[202:205], v217 offset:54272
	ds_read_b128 v[206:209], v217 offset:55296
	ds_read_b128 v[218:221], v217 offset:56320
	global_load_lds_dwordx4 v[186:187], off
	s_add_i32 m0, s22, 0x2000
	s_add_u32 s22, s24, 0xb080
	v_lshl_add_u64 v[186:187], v[210:211], 0, s[74:75]
	s_addc_u32 s23, s25, 0
	s_add_i32 s24, s48, s34
	global_load_lds_dwordx4 v[186:187], off
	v_lshl_add_u64 v[186:187], s[22:23], 0, v[188:189]
	s_mov_b32 m0, s24
	s_nop 0
	global_load_lds_dwordx4 v[186:187], off
	v_lshl_add_u64 v[186:187], s[22:23], 0, v[176:177]
	s_add_i32 m0, s24, 0x2000
	s_nop 0
	global_load_lds_dwordx4 v[186:187], off
	v_lshl_add_u64 v[186:187], v[222:223], 0, s[74:75]
	s_mov_b32 m0, s39
	s_nop 0
	global_load_lds_dwordx4 v[186:187], off
	v_lshl_add_u64 v[186:187], v[228:229], 0, s[74:75]
	s_mov_b32 m0, s40
	s_nop 0
	global_load_lds_dwordx4 v[186:187], off
	s_waitcnt vmcnt(8)
	s_waitcnt lgkmcnt(0)
	s_barrier
	s_waitcnt lgkmcnt(0)
	v_mfma_f32_16x16x32_bf16 v[60:63], v[96:99], v[160:163], v[60:63]
	v_mfma_f32_16x16x32_bf16 v[56:59], v[104:107], v[160:163], v[56:59]
	v_mfma_f32_16x16x32_bf16 v[44:47], v[96:99], v[168:171], v[44:47]
	v_mfma_f32_16x16x32_bf16 v[40:43], v[104:107], v[168:171], v[40:43]
	v_mfma_f32_16x16x32_bf16 v[28:31], v[96:99], v[198:201], v[28:31]
	v_mfma_f32_16x16x32_bf16 v[24:27], v[104:107], v[198:201], v[24:27]
	v_mfma_f32_16x16x32_bf16 v[12:15], v[96:99], v[206:209], v[12:15]
	v_mfma_f32_16x16x32_bf16 v[8:11], v[104:107], v[206:209], v[8:11]
	v_mfma_f32_16x16x32_bf16 v[60:63], v[100:103], v[164:167], v[60:63]
	v_mfma_f32_16x16x32_bf16 v[56:59], v[136:139], v[164:167], v[56:59]
	v_mfma_f32_16x16x32_bf16 v[44:47], v[100:103], v[172:175], v[44:47]
	v_mfma_f32_16x16x32_bf16 v[40:43], v[136:139], v[172:175], v[40:43]
	v_mfma_f32_16x16x32_bf16 v[28:31], v[100:103], v[202:205], v[28:31]
	v_mfma_f32_16x16x32_bf16 v[24:27], v[136:139], v[202:205], v[24:27]
	v_mfma_f32_16x16x32_bf16 v[12:15], v[100:103], v[218:221], v[12:15]
	v_mfma_f32_16x16x32_bf16 v[8:11], v[136:139], v[218:221], v[8:11]
	v_mfma_f32_16x16x32_bf16 v[52:55], v[140:143], v[160:163], v[52:55]
	v_mfma_f32_16x16x32_bf16 v[48:51], v[152:155], v[160:163], v[48:51]
	v_mfma_f32_16x16x32_bf16 v[36:39], v[140:143], v[168:171], v[36:39]
	v_mfma_f32_16x16x32_bf16 v[32:35], v[152:155], v[168:171], v[32:35]
	v_mfma_f32_16x16x32_bf16 v[20:23], v[140:143], v[198:201], v[20:23]
	v_mfma_f32_16x16x32_bf16 v[16:19], v[152:155], v[198:201], v[16:19]
	v_mfma_f32_16x16x32_bf16 v[4:7], v[140:143], v[206:209], v[4:7]
	v_mfma_f32_16x16x32_bf16 v[0:3], v[152:155], v[206:209], v[0:3]
	v_mfma_f32_16x16x32_bf16 v[52:55], v[144:147], v[164:167], v[52:55]
	v_mfma_f32_16x16x32_bf16 v[48:51], v[156:159], v[164:167], v[48:51]
	v_mfma_f32_16x16x32_bf16 v[36:39], v[144:147], v[172:175], v[36:39]
	v_mfma_f32_16x16x32_bf16 v[32:35], v[156:159], v[172:175], v[32:35]
	v_mfma_f32_16x16x32_bf16 v[20:23], v[144:147], v[202:205], v[20:23]
	v_mfma_f32_16x16x32_bf16 v[16:19], v[156:159], v[202:205], v[16:19]
	v_mfma_f32_16x16x32_bf16 v[4:7], v[144:147], v[218:221], v[4:7]
	v_mfma_f32_16x16x32_bf16 v[0:3], v[156:159], v[218:221], v[0:3]
	s_barrier
	s_add_i32 s47, s47, 2
	s_add_u32 s45, s45, 0x100
	s_addc_u32 s46, s46, 0
	s_cmp_gt_u32 s47, 41
	s_mov_b64 s[22:23], s[4:5]
	s_cbranch_scc0 .LBB0_1055
	s_and_b64 vcc, exec, s[16:17]
	s_cbranch_vccz .LBB0_1058
	s_barrier
